# v30 plus the back-to-back s_setprio 0/1 pairs in the middle of each 32-MFMA segment removed (all GEMM K-loops)
# baseline (speedup 1.0000x reference)
; #define PG8_STAGE(bufoff, gbase, voff) do { _Pragma("unroll") for (int _i = 0; _i < 2; ++_i) \
;         __builtin_amdgcn_global_load_lds((const unsigned*)((const char*)(gbase) + (voff)[_i]), (LAS unsigned*)(lds + (bufoff) + ldsw + _i * 8192), 16, 0, 0); } while (0)
; #define PG8_LDA(dst, b, h) do { _Pragma("unroll") for (int m = 0; m < 4; ++m) _Pragma("unroll") for (int k = 0; k < 2; ++k) dst[m][k] = *(const LAS bf16x8*)(lds + PG8_SA(b, h) + aoff + m * 2048 + k * 1024); } while (0)
; #define PG8_WAIT_V(n) asm volatile("s_waitcnt vmcnt(" #n ")" ::: "memory")
; template <class Epi, class Sched, bool ALIGN_EPI = false, bool SP2 = false, bool TWOA = false, bool AGM = false>
; __device__ __forceinline__ void gemm_phase(LAS unsigned char* lds, const Gemm g, const Sched& S, const Epi& E, int wid) {
;     ...
;         const bool has_next = S.next(ui + 1, nxt);
;         const char* nA = has_next ? (const char*)g.A + (size_t)nxt.pm * tstepA : cA; const char* nB = has_next ? (const char*)g.Bt + (size_t)nxt.pn * tstep : cB;
;         for (int t = 0; t < nt; t += 2) {
;             const bool last = (t == nt - 2);
;             const char* cA2 = TWOA ? (const char*)g.A2 + (cA - (const char*)g.A) - (size_t)nh * kstepA : cA;
;             const char* a1_ = (TWOA && t + 1 >= nh ? cA2 : cA) + (size_t)(t + 1) * kstepA;
;             const char* a2_ = last ? nA : (TWOA && t + 2 >= nh ? cA2 : cA) + (size_t)(t + 2) * kstepA; const char* a1 = a1_; const char* a2 = a2_; const char* b2 = last ? nB : cB + (size_t)(t + 2) * kstep;
;             if constexpr (TWOA) { asm volatile("" : "+s"(a1)); asm volatile("" : "+s"(a2)); }
;             const char* a3 = a2 + kstepA; const char* b3 = b2 + kstep;
;             if (last && has_next) S.a_ready(nxt);
;             if constexpr (has_mid<Epi>::value) { if (t == nh) E.mid(acc, cur, wr, wc, fr, fq); }
;             if constexpr (SP2) {
;             PG8_LDB(B0, 0, 0); PG8_LDB(B1, 0, 1); PG8_SCHED; PG8_LDA(At, 0, 0); PG8_STAGE(PG8_SA(1, 1), a1 + hstepA, voffA);
;             PG8_WAIT_V(8); PG8_WAIT_L(0); PG8_BAR; PG8_MMA(0, 0, At, B0); PG8_MMA(0, 1, At, B1); PG8_BAR; PG8_SCHED;
;             PG8_LDA(At, 0, 1); PG8_STAGE(PG8_SB(0, 0), b2, voffB); PG8_STAGE(PG8_SB(0, 1), b2 + hstep, voffB); PG8_STAGE(PG8_SA(0, 0), a2, voffA);
;             PG8_WAIT_V(8); PG8_WAIT_L(0); PG8_BAR; PG8_MMA(1, 0, At, B0); PG8_MMA(1, 1, At, B1); PG8_BAR; PG8_SCHED;
.LBB0_230:
	ds_read_b128 v[146:149], v155
	ds_read_b128 v[160:163], v155 offset:1024
	ds_read_b128 v[164:167], v155 offset:2048
	ds_read_b128 v[168:171], v155 offset:3072
	ds_read_b128 v[172:175], v156
	ds_read_b128 v[176:179], v156 offset:1024
	ds_read_b128 v[180:183], v156 offset:2048
	ds_read_b128 v[184:187], v156 offset:3072
	s_add_u32 s12, s10, 0xfff00080
	s_addc_u32 s13, s11, -1
	s_cmp_eq_u32 s70, 60
	s_cselect_b32 s67, s7, s13
	s_cselect_b32 s66, s9, s12
	s_cselect_b32 s13, s53, s69
	s_cselect_b32 s12, s55, s68
	s_add_i32 m0, s76, 0xc000
	ds_read_b128 v[188:191], v157
	ds_read_b128 v[192:195], v157 offset:1024
	ds_read_b128 v[196:199], v157 offset:2048
	ds_read_b128 v[200:203], v157 offset:3072
	ds_read_b128 v[204:207], v157 offset:4096
	ds_read_b128 v[208:211], v157 offset:5120
	ds_read_b128 v[212:215], v157 offset:6144
	ds_read_b128 v[216:219], v157 offset:7168
	global_load_lds_dwordx4 v138, s[10:11]
	s_add_i32 m0, s76, 0xe000
	s_nop 0
	global_load_lds_dwordx4 v140, s[10:11]
	s_waitcnt vmcnt(8)
	s_waitcnt lgkmcnt(0)
	s_barrier
	s_setprio 1
	s_waitcnt lgkmcnt(0)
	v_mfma_f32_16x16x32_bf16 v[124:127], v[146:149], v[188:191], v[124:127]
	v_mfma_f32_16x16x32_bf16 v[120:123], v[164:167], v[188:191], v[120:123]
	v_mfma_f32_16x16x32_bf16 v[108:111], v[146:149], v[196:199], v[108:111]
	v_mfma_f32_16x16x32_bf16 v[104:107], v[164:167], v[196:199], v[104:107]
	v_mfma_f32_16x16x32_bf16 v[92:95], v[146:149], v[204:207], v[92:95]
	v_mfma_f32_16x16x32_bf16 v[88:91], v[164:167], v[204:207], v[88:91]
	v_mfma_f32_16x16x32_bf16 v[76:79], v[146:149], v[212:215], v[76:79]
	v_mfma_f32_16x16x32_bf16 v[72:75], v[164:167], v[212:215], v[72:75]
	v_mfma_f32_16x16x32_bf16 v[124:127], v[160:163], v[192:195], v[124:127]
	v_mfma_f32_16x16x32_bf16 v[120:123], v[168:171], v[192:195], v[120:123]
	v_mfma_f32_16x16x32_bf16 v[108:111], v[160:163], v[200:203], v[108:111]
	v_mfma_f32_16x16x32_bf16 v[104:107], v[168:171], v[200:203], v[104:107]
	v_mfma_f32_16x16x32_bf16 v[92:95], v[160:163], v[208:211], v[92:95]
	v_mfma_f32_16x16x32_bf16 v[88:91], v[168:171], v[208:211], v[88:91]
	v_mfma_f32_16x16x32_bf16 v[76:79], v[160:163], v[216:219], v[76:79]
	v_mfma_f32_16x16x32_bf16 v[72:75], v[168:171], v[216:219], v[72:75]
	v_mfma_f32_16x16x32_bf16 v[116:119], v[172:175], v[188:191], v[116:119]
	v_mfma_f32_16x16x32_bf16 v[112:115], v[180:183], v[188:191], v[112:115]
	v_mfma_f32_16x16x32_bf16 v[100:103], v[172:175], v[196:199], v[100:103]
	v_mfma_f32_16x16x32_bf16 v[96:99], v[180:183], v[196:199], v[96:99]
	v_mfma_f32_16x16x32_bf16 v[84:87], v[172:175], v[204:207], v[84:87]
	v_mfma_f32_16x16x32_bf16 v[80:83], v[180:183], v[204:207], v[80:83]
	v_mfma_f32_16x16x32_bf16 v[68:71], v[172:175], v[212:215], v[68:71]
	v_mfma_f32_16x16x32_bf16 v[64:67], v[180:183], v[212:215], v[64:67]
	v_mfma_f32_16x16x32_bf16 v[116:119], v[176:179], v[192:195], v[116:119]
	v_mfma_f32_16x16x32_bf16 v[112:115], v[184:187], v[192:195], v[112:115]
	v_mfma_f32_16x16x32_bf16 v[100:103], v[176:179], v[200:203], v[100:103]
	v_mfma_f32_16x16x32_bf16 v[96:99], v[184:187], v[200:203], v[96:99]
	v_mfma_f32_16x16x32_bf16 v[84:87], v[176:179], v[208:211], v[84:87]
	v_mfma_f32_16x16x32_bf16 v[80:83], v[184:187], v[208:211], v[80:83]
	v_mfma_f32_16x16x32_bf16 v[68:71], v[176:179], v[216:219], v[68:71]
	v_mfma_f32_16x16x32_bf16 v[64:67], v[184:187], v[216:219], v[64:67]
	s_setprio 0
	s_barrier
	s_add_i32 s34, s95, s75
	s_mov_b32 m0, s34
	ds_read_b128 v[188:191], v157 offset:16384
	ds_read_b128 v[192:195], v157 offset:17408
	ds_read_b128 v[196:199], v157 offset:18432
	ds_read_b128 v[200:203], v157 offset:19456
	ds_read_b128 v[204:207], v157 offset:20480
	ds_read_b128 v[208:211], v157 offset:21504
	ds_read_b128 v[212:215], v157 offset:22528
	ds_read_b128 v[216:219], v157 offset:23552
	global_load_lds_dwordx4 v130, s[12:13]
	s_add_i32 m0, s34, 0x2000
	s_add_u32 s34, s12, 0x100000
	s_addc_u32 s35, s13, 0
	s_add_i32 s71, s96, s75
	global_load_lds_dwordx4 v134, s[12:13]
	s_mov_b32 m0, s71
	s_nop 0
	global_load_lds_dwordx4 v130, s[34:35]
	s_add_i32 m0, s71, 0x2000
	s_nop 0
	global_load_lds_dwordx4 v134, s[34:35]
	s_mov_b32 m0, s76
	s_nop 0
	global_load_lds_dwordx4 v128, s[66:67]
	s_mov_b32 m0, s77
	s_nop 0
	global_load_lds_dwordx4 v132, s[66:67]
	s_waitcnt vmcnt(8)
	s_waitcnt lgkmcnt(0)
	s_barrier
	s_setprio 1
	s_waitcnt lgkmcnt(0)
	v_mfma_f32_16x16x32_bf16 v[60:63], v[146:149], v[188:191], v[60:63]
	v_mfma_f32_16x16x32_bf16 v[56:59], v[164:167], v[188:191], v[56:59]
	v_mfma_f32_16x16x32_bf16 v[44:47], v[146:149], v[196:199], v[44:47]
	v_mfma_f32_16x16x32_bf16 v[40:43], v[164:167], v[196:199], v[40:43]
	v_mfma_f32_16x16x32_bf16 v[28:31], v[146:149], v[204:207], v[28:31]
	v_mfma_f32_16x16x32_bf16 v[24:27], v[164:167], v[204:207], v[24:27]
	v_mfma_f32_16x16x32_bf16 v[12:15], v[146:149], v[212:215], v[12:15]
	v_mfma_f32_16x16x32_bf16 v[8:11], v[164:167], v[212:215], v[8:11]
	v_mfma_f32_16x16x32_bf16 v[60:63], v[160:163], v[192:195], v[60:63]
	v_mfma_f32_16x16x32_bf16 v[56:59], v[168:171], v[192:195], v[56:59]
	v_mfma_f32_16x16x32_bf16 v[44:47], v[160:163], v[200:203], v[44:47]
	v_mfma_f32_16x16x32_bf16 v[40:43], v[168:171], v[200:203], v[40:43]
	v_mfma_f32_16x16x32_bf16 v[28:31], v[160:163], v[208:211], v[28:31]
	v_mfma_f32_16x16x32_bf16 v[24:27], v[168:171], v[208:211], v[24:27]
	v_mfma_f32_16x16x32_bf16 v[12:15], v[160:163], v[216:219], v[12:15]
	v_mfma_f32_16x16x32_bf16 v[8:11], v[168:171], v[216:219], v[8:11]
	v_mfma_f32_16x16x32_bf16 v[52:55], v[172:175], v[188:191], v[52:55]
	v_mfma_f32_16x16x32_bf16 v[48:51], v[180:183], v[188:191], v[48:51]
	v_mfma_f32_16x16x32_bf16 v[36:39], v[172:175], v[196:199], v[36:39]
	v_mfma_f32_16x16x32_bf16 v[32:35], v[180:183], v[196:199], v[32:35]
	v_mfma_f32_16x16x32_bf16 v[20:23], v[172:175], v[204:207], v[20:23]
	v_mfma_f32_16x16x32_bf16 v[16:19], v[180:183], v[204:207], v[16:19]
	v_mfma_f32_16x16x32_bf16 v[4:7], v[172:175], v[212:215], v[4:7]
	v_mfma_f32_16x16x32_bf16 v[0:3], v[180:183], v[212:215], v[0:3]
	v_mfma_f32_16x16x32_bf16 v[52:55], v[176:179], v[192:195], v[52:55]
	v_mfma_f32_16x16x32_bf16 v[48:51], v[184:187], v[192:195], v[48:51]
	v_mfma_f32_16x16x32_bf16 v[36:39], v[176:179], v[200:203], v[36:39]
	v_mfma_f32_16x16x32_bf16 v[32:35], v[184:187], v[200:203], v[32:35]
	v_mfma_f32_16x16x32_bf16 v[20:23], v[176:179], v[208:211], v[20:23]
	v_mfma_f32_16x16x32_bf16 v[16:19], v[184:187], v[208:211], v[16:19]
	v_mfma_f32_16x16x32_bf16 v[4:7], v[176:179], v[216:219], v[4:7]
	v_mfma_f32_16x16x32_bf16 v[0:3], v[184:187], v[216:219], v[0:3]
	s_setprio 0
	s_barrier
; #define PG8_STAGE(bufoff, gbase, voff) do { _Pragma("unroll") for (int _i = 0; _i < 2; ++_i) \
;         __builtin_amdgcn_global_load_lds((const unsigned*)((const char*)(gbase) + (voff)[_i]), (LAS unsigned*)(lds + (bufoff) + ldsw + _i * 8192), 16, 0, 0); } while (0)
; #define PG8_LDA(dst, b, h) do { _Pragma("unroll") for (int m = 0; m < 4; ++m) _Pragma("unroll") for (int k = 0; k < 2; ++k) dst[m][k] = *(const LAS bf16x8*)(lds + PG8_SA(b, h) + aoff + m * 2048 + k * 1024); } while (0)
; #define PG8_LDB(dst, b, h) do { _Pragma("unroll") for (int n = 0; n < 2; ++n) _Pragma("unroll") for (int k = 0; k < 2; ++k) dst[n][k] = *(const LAS bf16x8*)(lds + PG8_SB(b, h) + boff + n * 2048 + k * 1024); } while (0)
; #define PG8_MMA(ai, bj, At, Bt) do { __builtin_amdgcn_s_setprio(1); _Pragma("unroll") for (int m = 0; m < 4; ++m) _Pragma("unroll") for (int n = 0; n < 2; ++n) _Pragma("unroll") for (int k = 0; k < 2; ++k) \
;         acc[ai][bj][m][n] = __builtin_amdgcn_mfma_f32_16x16x32_bf16(Bt[n][k], At[m][k], acc[ai][bj][m][n], 0, 0, 0); __builtin_amdgcn_s_setprio(0); } while (0)
; #define PG8_WAIT_V(n) asm volatile("s_waitcnt vmcnt(" #n ")" ::: "memory")
; #define PG8_WAIT_L(n) asm volatile("s_waitcnt lgkmcnt(" #n ")" ::: "memory")
; #define PG8_BAR __builtin_amdgcn_s_barrier()
; #define PG8_SCHED __builtin_amdgcn_sched_barrier(0)
; template <class Epi, class Sched, bool ALIGN_EPI = false, bool SP2 = false, bool TWOA = false, bool AGM = false>
; __device__ __forceinline__ void gemm_phase(LAS unsigned char* lds, const Gemm g, const Sched& S, const Epi& E, int wid) {
;     ...
;         for (int t = 0; t < nt; t += 2) {
;             const bool last = (t == nt - 2);
;     ...
;             PG8_LDB(B0, 1, 0); PG8_LDB(B1, 1, 1); PG8_SCHED; PG8_LDA(At, 1, 0); PG8_STAGE(PG8_SA(0, 1), a2 + hstepA, voffA);
;             PG8_WAIT_V(8); PG8_WAIT_L(0); PG8_BAR; PG8_MMA(0, 0, At, B0); PG8_MMA(0, 1, At, B1); PG8_BAR; PG8_SCHED;
;             PG8_LDA(At, 1, 1); PG8_STAGE(PG8_SB(1, 0), b3, voffB); PG8_STAGE(PG8_SB(1, 1), b3 + hstep, voffB); PG8_STAGE(PG8_SA(1, 0), a3, voffA);
;             PG8_WAIT_V(8); PG8_WAIT_L(0); PG8_BAR; PG8_MMA(1, 0, At, B0); PG8_MMA(1, 1, At, B1); PG8_BAR; PG8_SCHED;
	s_add_i32 s71, 0, 0x18000
	v_add_u32_e32 v136, s71, v153
	s_add_i32 s72, 0, 0x1c000
	ds_read_b128 v[146:149], v136
	ds_read_b128 v[160:163], v136 offset:1024
	ds_read_b128 v[164:167], v136 offset:2048
	ds_read_b128 v[168:171], v136 offset:3072
	v_add_u32_e32 v136, s72, v153
	ds_read_b128 v[172:175], v136
	ds_read_b128 v[176:179], v136 offset:1024
	ds_read_b128 v[180:183], v136 offset:2048
	ds_read_b128 v[184:187], v136 offset:3072
	s_add_u32 s34, s66, 0x100000
	s_addc_u32 s35, s67, 0
	s_mov_b32 m0, s81
	ds_read_b128 v[188:191], v157 offset:32768
	ds_read_b128 v[192:195], v157 offset:33792
	ds_read_b128 v[196:199], v157 offset:34816
	ds_read_b128 v[200:203], v157 offset:35840
	ds_read_b128 v[204:207], v157 offset:36864
	ds_read_b128 v[208:211], v157 offset:37888
	ds_read_b128 v[212:215], v157 offset:38912
	ds_read_b128 v[216:219], v157 offset:39936
	global_load_lds_dwordx4 v128, s[34:35]
	s_mov_b32 m0, s82
	s_nop 0
	global_load_lds_dwordx4 v132, s[34:35]
	s_waitcnt vmcnt(8)
	s_waitcnt lgkmcnt(0)
	s_barrier
	s_setprio 1
	s_waitcnt lgkmcnt(0)
	v_mfma_f32_16x16x32_bf16 v[124:127], v[146:149], v[188:191], v[124:127]
	v_mfma_f32_16x16x32_bf16 v[120:123], v[164:167], v[188:191], v[120:123]
	v_mfma_f32_16x16x32_bf16 v[108:111], v[146:149], v[196:199], v[108:111]
	v_mfma_f32_16x16x32_bf16 v[104:107], v[164:167], v[196:199], v[104:107]
	v_mfma_f32_16x16x32_bf16 v[92:95], v[146:149], v[204:207], v[92:95]
	v_mfma_f32_16x16x32_bf16 v[88:91], v[164:167], v[204:207], v[88:91]
	v_mfma_f32_16x16x32_bf16 v[76:79], v[146:149], v[212:215], v[76:79]
	v_mfma_f32_16x16x32_bf16 v[72:75], v[164:167], v[212:215], v[72:75]
	v_mfma_f32_16x16x32_bf16 v[124:127], v[160:163], v[192:195], v[124:127]
	v_mfma_f32_16x16x32_bf16 v[120:123], v[168:171], v[192:195], v[120:123]
	v_mfma_f32_16x16x32_bf16 v[108:111], v[160:163], v[200:203], v[108:111]
	v_mfma_f32_16x16x32_bf16 v[104:107], v[168:171], v[200:203], v[104:107]
	v_mfma_f32_16x16x32_bf16 v[92:95], v[160:163], v[208:211], v[92:95]
	v_mfma_f32_16x16x32_bf16 v[88:91], v[168:171], v[208:211], v[88:91]
	v_mfma_f32_16x16x32_bf16 v[76:79], v[160:163], v[216:219], v[76:79]
	v_mfma_f32_16x16x32_bf16 v[72:75], v[168:171], v[216:219], v[72:75]
	v_mfma_f32_16x16x32_bf16 v[116:119], v[172:175], v[188:191], v[116:119]
	v_mfma_f32_16x16x32_bf16 v[112:115], v[180:183], v[188:191], v[112:115]
	v_mfma_f32_16x16x32_bf16 v[100:103], v[172:175], v[196:199], v[100:103]
	v_mfma_f32_16x16x32_bf16 v[96:99], v[180:183], v[196:199], v[96:99]
	v_mfma_f32_16x16x32_bf16 v[84:87], v[172:175], v[204:207], v[84:87]
	v_mfma_f32_16x16x32_bf16 v[80:83], v[180:183], v[204:207], v[80:83]
	v_mfma_f32_16x16x32_bf16 v[68:71], v[172:175], v[212:215], v[68:71]
	v_mfma_f32_16x16x32_bf16 v[64:67], v[180:183], v[212:215], v[64:67]
	v_mfma_f32_16x16x32_bf16 v[116:119], v[176:179], v[192:195], v[116:119]
	v_mfma_f32_16x16x32_bf16 v[112:115], v[184:187], v[192:195], v[112:115]
	v_mfma_f32_16x16x32_bf16 v[100:103], v[176:179], v[200:203], v[100:103]
	v_mfma_f32_16x16x32_bf16 v[96:99], v[184:187], v[200:203], v[96:99]
	v_mfma_f32_16x16x32_bf16 v[84:87], v[176:179], v[208:211], v[84:87]
	v_mfma_f32_16x16x32_bf16 v[80:83], v[184:187], v[208:211], v[80:83]
	v_mfma_f32_16x16x32_bf16 v[68:71], v[176:179], v[216:219], v[68:71]
	v_mfma_f32_16x16x32_bf16 v[64:67], v[184:187], v[216:219], v[64:67]
	s_setprio 0
	s_barrier
	s_add_i32 s34, s71, s75
	s_add_u32 s98, s12, s46
	s_addc_u32 s99, s13, s47
	s_mov_b32 m0, s34
	ds_read_b128 v[188:191], v157 offset:49152
	ds_read_b128 v[192:195], v157 offset:50176
	ds_read_b128 v[196:199], v157 offset:51200
	ds_read_b128 v[200:203], v157 offset:52224
	ds_read_b128 v[204:207], v157 offset:53248
	ds_read_b128 v[208:211], v157 offset:54272
	ds_read_b128 v[212:215], v157 offset:55296
	ds_read_b128 v[216:219], v157 offset:56320
	global_load_lds_dwordx4 v130, s[98:99]
	s_add_i32 m0, s34, 0x2000
	s_add_u32 s12, s12, 0x100080
	s_addc_u32 s13, s13, 0
	s_add_i32 s34, s72, s75
	global_load_lds_dwordx4 v134, s[98:99]
	s_mov_b32 m0, s34
	s_nop 0
	global_load_lds_dwordx4 v130, s[12:13]
	s_add_i32 m0, s34, 0x2000
	s_nop 0
	global_load_lds_dwordx4 v134, s[12:13]
	s_add_u32 s100, s66, s46
	s_addc_u32 s101, s67, s47
	s_mov_b32 m0, s88
	s_nop 0
	global_load_lds_dwordx4 v128, s[100:101]
	s_mov_b32 m0, s89
	s_nop 0
	global_load_lds_dwordx4 v132, s[100:101]
	s_waitcnt vmcnt(8)
	s_waitcnt lgkmcnt(0)
	s_barrier
	s_setprio 1
	s_waitcnt lgkmcnt(0)
	v_mfma_f32_16x16x32_bf16 v[60:63], v[146:149], v[188:191], v[60:63]
	v_mfma_f32_16x16x32_bf16 v[56:59], v[164:167], v[188:191], v[56:59]
	v_mfma_f32_16x16x32_bf16 v[44:47], v[146:149], v[196:199], v[44:47]
	v_mfma_f32_16x16x32_bf16 v[40:43], v[164:167], v[196:199], v[40:43]
	v_mfma_f32_16x16x32_bf16 v[28:31], v[146:149], v[204:207], v[28:31]
	v_mfma_f32_16x16x32_bf16 v[24:27], v[164:167], v[204:207], v[24:27]
	v_mfma_f32_16x16x32_bf16 v[12:15], v[146:149], v[212:215], v[12:15]
	v_mfma_f32_16x16x32_bf16 v[8:11], v[164:167], v[212:215], v[8:11]
	v_mfma_f32_16x16x32_bf16 v[60:63], v[160:163], v[192:195], v[60:63]
	v_mfma_f32_16x16x32_bf16 v[56:59], v[168:171], v[192:195], v[56:59]
	v_mfma_f32_16x16x32_bf16 v[44:47], v[160:163], v[200:203], v[44:47]
	v_mfma_f32_16x16x32_bf16 v[40:43], v[168:171], v[200:203], v[40:43]
	v_mfma_f32_16x16x32_bf16 v[28:31], v[160:163], v[208:211], v[28:31]
	v_mfma_f32_16x16x32_bf16 v[24:27], v[168:171], v[208:211], v[24:27]
	v_mfma_f32_16x16x32_bf16 v[12:15], v[160:163], v[216:219], v[12:15]
	v_mfma_f32_16x16x32_bf16 v[8:11], v[168:171], v[216:219], v[8:11]
	v_mfma_f32_16x16x32_bf16 v[52:55], v[172:175], v[188:191], v[52:55]
	v_mfma_f32_16x16x32_bf16 v[48:51], v[180:183], v[188:191], v[48:51]
	v_mfma_f32_16x16x32_bf16 v[36:39], v[172:175], v[196:199], v[36:39]
	v_mfma_f32_16x16x32_bf16 v[32:35], v[180:183], v[196:199], v[32:35]
	v_mfma_f32_16x16x32_bf16 v[20:23], v[172:175], v[204:207], v[20:23]
	v_mfma_f32_16x16x32_bf16 v[16:19], v[180:183], v[204:207], v[16:19]
	v_mfma_f32_16x16x32_bf16 v[4:7], v[172:175], v[212:215], v[4:7]
	v_mfma_f32_16x16x32_bf16 v[0:3], v[180:183], v[212:215], v[0:3]
	v_mfma_f32_16x16x32_bf16 v[52:55], v[176:179], v[192:195], v[52:55]
	v_mfma_f32_16x16x32_bf16 v[48:51], v[184:187], v[192:195], v[48:51]
	v_mfma_f32_16x16x32_bf16 v[36:39], v[176:179], v[200:203], v[36:39]
	v_mfma_f32_16x16x32_bf16 v[32:35], v[184:187], v[200:203], v[32:35]
	v_mfma_f32_16x16x32_bf16 v[20:23], v[176:179], v[208:211], v[20:23]
	v_mfma_f32_16x16x32_bf16 v[16:19], v[184:187], v[208:211], v[16:19]
	v_mfma_f32_16x16x32_bf16 v[4:7], v[176:179], v[216:219], v[4:7]
	v_mfma_f32_16x16x32_bf16 v[0:3], v[184:187], v[216:219], v[0:3]
	s_setprio 0
	s_barrier
	s_add_i32 s70, s70, 2
	s_add_u32 s10, s10, 0x100
	s_addc_u32 s11, s11, 0
	s_add_u32 s68, s68, 0x100
	s_addc_u32 s69, s69, 0
	s_cmp_gt_u32 s70, 61
	s_cbranch_scc0 .LBB0_230
	s_and_b64 vcc, exec, s[50:51]
	s_cbranch_vccz .LBB0_233
	s_barrier

; #define PG8_STAGE(bufoff, gbase, voff) do { _Pragma("unroll") for (int _i = 0; _i < 2; ++_i) \
;         __builtin_amdgcn_global_load_lds((const unsigned*)((const char*)(gbase) + (voff)[_i]), (LAS unsigned*)(lds + (bufoff) + ldsw + _i * 8192), 16, 0, 0); } while (0)
; #define PG8_LDA(dst, b, h) do { _Pragma("unroll") for (int m = 0; m < 4; ++m) _Pragma("unroll") for (int k = 0; k < 2; ++k) dst[m][k] = *(const LAS bf16x8*)(lds + PG8_SA(b, h) + aoff + m * 2048 + k * 1024); } while (0)
; #define PG8_LDB(dst, b, h) do { _Pragma("unroll") for (int n = 0; n < 2; ++n) _Pragma("unroll") for (int k = 0; k < 2; ++k) dst[n][k] = *(const LAS bf16x8*)(lds + PG8_SB(b, h) + boff + n * 2048 + k * 1024); } while (0)
; template <class Epi, class Sched, bool ALIGN_EPI = false, bool SP2 = false, bool TWOA = false, bool AGM = false>
; __device__ __forceinline__ void gemm_phase(LAS unsigned char* lds, const Gemm g, const Sched& S, const Epi& E, int wid) {
;     ...
;         const char* nA = has_next ? (const char*)g.A + (size_t)nxt.pm * tstepA : cA; const char* nB = has_next ? (const char*)g.Bt + (size_t)nxt.pn * tstep : cB;
;         for (int t = 0; t < nt; t += 2) {
;             const bool last = (t == nt - 2);
;             const char* cA2 = TWOA ? (const char*)g.A2 + (cA - (const char*)g.A) - (size_t)nh * kstepA : cA;
;             const char* a1_ = (TWOA && t + 1 >= nh ? cA2 : cA) + (size_t)(t + 1) * kstepA;
;             const char* a2_ = last ? nA : (TWOA && t + 2 >= nh ? cA2 : cA) + (size_t)(t + 2) * kstepA; const char* a1 = a1_; const char* a2 = a2_; const char* b2 = last ? nB : cB + (size_t)(t + 2) * kstep;
;             if constexpr (TWOA) { asm volatile("" : "+s"(a1)); asm volatile("" : "+s"(a2)); }
;             const char* a3 = a2 + kstepA; const char* b3 = b2 + kstep;
;             if (last && has_next) S.a_ready(nxt);
;             if constexpr (has_mid<Epi>::value) { if (t == nh) E.mid(acc, cur, wr, wc, fr, fq); }
;             if constexpr (SP2) {
;             PG8_LDB(B0, 0, 0); PG8_LDB(B1, 0, 1); PG8_SCHED; PG8_LDA(At, 0, 0); PG8_STAGE(PG8_SA(1, 1), a1 + hstepA, voffA);
;             PG8_WAIT_V(8); PG8_WAIT_L(0); PG8_BAR; PG8_MMA(0, 0, At, B0); PG8_MMA(0, 1, At, B1); PG8_BAR; PG8_SCHED;
;             PG8_LDA(At, 0, 1); PG8_STAGE(PG8_SB(0, 0), b2, voffB); PG8_STAGE(PG8_SB(0, 1), b2 + hstep, voffB); PG8_STAGE(PG8_SA(0, 0), a2, voffA);
.LBB0_523:
	ds_read_b128 v[0:3], v137
	ds_read_b128 v[4:7], v137 offset:1024
	ds_read_b128 v[8:11], v137 offset:2048
	ds_read_b128 v[12:15], v137 offset:3072
	ds_read_b128 v[16:19], v138
	ds_read_b128 v[20:23], v138 offset:1024
	ds_read_b128 v[24:27], v138 offset:2048
	ds_read_b128 v[28:31], v138 offset:3072
	s_ashr_i32 s27, s26, 31
	s_lshl_b64 s[30:31], s[26:27], 17
	s_add_u32 s30, s3, s30
	s_addc_u32 s31, s50, s31
	s_and_b64 s[34:35], s[36:37], exec
	s_cselect_b32 s47, s31, s41
	s_cselect_b32 s46, s30, s40
	s_ashr_i32 s25, s24, 31
	s_lshl_b64 s[34:35], s[24:25], 17
	s_add_u32 s38, s51, s34
	s_addc_u32 s39, s52, s35
	s_and_b64 s[34:35], s[36:37], exec
	s_cselect_b32 s43, s39, s45
	s_cselect_b32 s42, s38, s44
	s_add_u32 s34, s40, 0x10080
	s_addc_u32 s35, s41, 0
	s_mov_b32 m0, s66
	v_lshl_add_u64 v[64:65], s[34:35], 0, v[134:135]
	ds_read_b128 v[32:35], v139
	ds_read_b128 v[36:39], v139 offset:1024
	ds_read_b128 v[40:43], v139 offset:2048
	ds_read_b128 v[44:47], v139 offset:3072
	ds_read_b128 v[48:51], v139 offset:4096
	ds_read_b128 v[52:55], v139 offset:5120
	ds_read_b128 v[56:59], v139 offset:6144
	ds_read_b128 v[60:63], v139 offset:7168
	global_load_lds_dwordx4 v[64:65], off
	v_lshl_add_u64 v[64:65], s[34:35], 0, v[130:131]
	s_mov_b32 m0, s67
	s_nop 0
	global_load_lds_dwordx4 v[64:65], off
	s_waitcnt vmcnt(8)
	s_waitcnt lgkmcnt(0)
	s_barrier
	s_setprio 1
	s_waitcnt lgkmcnt(0)
	v_mfma_f32_16x16x32_bf16 v[64:67], v[0:3], v[32:35], 0
	v_mfma_f32_16x16x32_bf16 v[68:71], v[8:11], v[32:35], 0
	v_mfma_f32_16x16x32_bf16 v[72:75], v[0:3], v[40:43], 0
	v_mfma_f32_16x16x32_bf16 v[76:79], v[8:11], v[40:43], 0
	v_mfma_f32_16x16x32_bf16 v[80:83], v[0:3], v[48:51], 0
	v_mfma_f32_16x16x32_bf16 v[84:87], v[8:11], v[48:51], 0
	v_mfma_f32_16x16x32_bf16 v[88:91], v[0:3], v[56:59], 0
	v_mfma_f32_16x16x32_bf16 v[92:95], v[8:11], v[56:59], 0
	v_mfma_f32_16x16x32_bf16 v[64:67], v[4:7], v[36:39], v[64:67]
	v_mfma_f32_16x16x32_bf16 v[68:71], v[12:15], v[36:39], v[68:71]
	v_mfma_f32_16x16x32_bf16 v[72:75], v[4:7], v[44:47], v[72:75]
	v_mfma_f32_16x16x32_bf16 v[76:79], v[12:15], v[44:47], v[76:79]
	v_mfma_f32_16x16x32_bf16 v[80:83], v[4:7], v[52:55], v[80:83]
	v_mfma_f32_16x16x32_bf16 v[84:87], v[12:15], v[52:55], v[84:87]
	v_mfma_f32_16x16x32_bf16 v[88:91], v[4:7], v[60:63], v[88:91]
	v_mfma_f32_16x16x32_bf16 v[92:95], v[12:15], v[60:63], v[92:95]
	v_mfma_f32_16x16x32_bf16 v[96:99], v[16:19], v[32:35], 0
	v_mfma_f32_16x16x32_bf16 v[32:35], v[24:27], v[32:35], 0
	v_mfma_f32_16x16x32_bf16 v[96:99], v[20:23], v[36:39], v[96:99]
	v_mfma_f32_16x16x32_bf16 v[32:35], v[28:31], v[36:39], v[32:35]
	v_mfma_f32_16x16x32_bf16 v[36:39], v[16:19], v[40:43], 0
	v_mfma_f32_16x16x32_bf16 v[40:43], v[24:27], v[40:43], 0
	v_mfma_f32_16x16x32_bf16 v[36:39], v[20:23], v[44:47], v[36:39]
	v_mfma_f32_16x16x32_bf16 v[40:43], v[28:31], v[44:47], v[40:43]
	v_mfma_f32_16x16x32_bf16 v[44:47], v[16:19], v[48:51], 0
	v_mfma_f32_16x16x32_bf16 v[48:51], v[24:27], v[48:51], 0
	v_mfma_f32_16x16x32_bf16 v[44:47], v[20:23], v[52:55], v[44:47]
	v_mfma_f32_16x16x32_bf16 v[48:51], v[28:31], v[52:55], v[48:51]
	v_mfma_f32_16x16x32_bf16 v[52:55], v[16:19], v[56:59], 0
	v_mfma_f32_16x16x32_bf16 v[56:59], v[24:27], v[56:59], 0
	v_mfma_f32_16x16x32_bf16 v[52:55], v[20:23], v[60:63], v[52:55]
	v_mfma_f32_16x16x32_bf16 v[56:59], v[28:31], v[60:63], v[56:59]
	s_setprio 0
	s_barrier
	v_lshl_add_u64 v[206:207], s[44:45], 0, v[132:133]
	s_mov_b32 m0, s68
	v_lshl_add_u64 v[142:143], v[206:207], 0, s[20:21]
	v_lshl_add_u64 v[208:209], s[44:45], 0, v[128:129]
	s_add_u32 s34, s44, 0x10100
	ds_read_b128 v[60:63], v139 offset:16384
	ds_read_b128 v[100:103], v139 offset:17408
	ds_read_b128 v[104:107], v139 offset:18432
	ds_read_b128 v[108:111], v139 offset:19456
	ds_read_b128 v[112:115], v139 offset:20480
	ds_read_b128 v[116:119], v139 offset:21504
	ds_read_b128 v[120:123], v139 offset:22528
	ds_read_b128 v[124:127], v139 offset:23552
	global_load_lds_dwordx4 v[142:143], off
	v_lshl_add_u64 v[142:143], v[208:209], 0, s[20:21]
	s_mov_b32 m0, s69
	s_addc_u32 s35, s45, 0
	global_load_lds_dwordx4 v[142:143], off
	v_lshl_add_u64 v[142:143], s[34:35], 0, v[132:133]
	s_mov_b32 m0, s70
	v_lshl_add_u64 v[210:211], s[40:41], 0, v[134:135]
	global_load_lds_dwordx4 v[142:143], off
	v_lshl_add_u64 v[142:143], s[34:35], 0, v[128:129]
	s_mov_b32 m0, s71
	v_lshl_add_u64 v[212:213], s[40:41], 0, v[130:131]
	global_load_lds_dwordx4 v[142:143], off
	v_lshl_add_u64 v[142:143], v[210:211], 0, s[20:21]
	s_mov_b32 m0, s53
	s_nop 0
	global_load_lds_dwordx4 v[142:143], off
	v_lshl_add_u64 v[142:143], v[212:213], 0, s[20:21]
	s_mov_b32 m0, s54
	s_nop 0
	global_load_lds_dwordx4 v[142:143], off
	s_waitcnt vmcnt(8)
	s_waitcnt lgkmcnt(0)
	s_barrier
; #define PG8_STAGE(bufoff, gbase, voff) do { _Pragma("unroll") for (int _i = 0; _i < 2; ++_i) \
;         __builtin_amdgcn_global_load_lds((const unsigned*)((const char*)(gbase) + (voff)[_i]), (LAS unsigned*)(lds + (bufoff) + ldsw + _i * 8192), 16, 0, 0); } while (0)
; #define PG8_LDA(dst, b, h) do { _Pragma("unroll") for (int m = 0; m < 4; ++m) _Pragma("unroll") for (int k = 0; k < 2; ++k) dst[m][k] = *(const LAS bf16x8*)(lds + PG8_SA(b, h) + aoff + m * 2048 + k * 1024); } while (0)
; #define PG8_LDB(dst, b, h) do { _Pragma("unroll") for (int n = 0; n < 2; ++n) _Pragma("unroll") for (int k = 0; k < 2; ++k) dst[n][k] = *(const LAS bf16x8*)(lds + PG8_SB(b, h) + boff + n * 2048 + k * 1024); } while (0)
; #define PG8_MMA(ai, bj, At, Bt) do { __builtin_amdgcn_s_setprio(1); _Pragma("unroll") for (int m = 0; m < 4; ++m) _Pragma("unroll") for (int n = 0; n < 2; ++n) _Pragma("unroll") for (int k = 0; k < 2; ++k) \
;         acc[ai][bj][m][n] = __builtin_amdgcn_mfma_f32_16x16x32_bf16(Bt[n][k], At[m][k], acc[ai][bj][m][n], 0, 0, 0); __builtin_amdgcn_s_setprio(0); } while (0)
; #define PG8_WAIT_V(n) asm volatile("s_waitcnt vmcnt(" #n ")" ::: "memory")
; #define PG8_WAIT_L(n) asm volatile("s_waitcnt lgkmcnt(" #n ")" ::: "memory")
; #define PG8_BAR __builtin_amdgcn_s_barrier()
; #define PG8_SCHED __builtin_amdgcn_sched_barrier(0)
; template <class Epi, class Sched, bool ALIGN_EPI = false, bool SP2 = false, bool TWOA = false, bool AGM = false>
; __device__ __forceinline__ void gemm_phase(LAS unsigned char* lds, const Gemm g, const Sched& S, const Epi& E, int wid) {
;     ...
;             PG8_WAIT_V(8); PG8_WAIT_L(0); PG8_BAR; PG8_MMA(1, 0, At, B0); PG8_MMA(1, 1, At, B1); PG8_BAR; PG8_SCHED;
;             PG8_LDB(B0, 1, 0); PG8_LDB(B1, 1, 1); PG8_SCHED; PG8_LDA(At, 1, 0); PG8_STAGE(PG8_SA(0, 1), a2 + hstepA, voffA);
;             PG8_WAIT_V(8); PG8_WAIT_L(0); PG8_BAR; PG8_MMA(0, 0, At, B0); PG8_MMA(0, 1, At, B1); PG8_BAR; PG8_SCHED;
	s_setprio 1
	s_waitcnt lgkmcnt(0)
	v_mfma_f32_16x16x32_bf16 v[142:145], v[0:3], v[60:63], 0
	v_mfma_f32_16x16x32_bf16 v[150:153], v[0:3], v[104:107], 0
	v_mfma_f32_16x16x32_bf16 v[158:161], v[0:3], v[112:115], 0
	v_mfma_f32_16x16x32_bf16 v[0:3], v[0:3], v[120:123], 0
	v_mfma_f32_16x16x32_bf16 v[142:145], v[4:7], v[100:103], v[142:145]
	v_mfma_f32_16x16x32_bf16 v[150:153], v[4:7], v[108:111], v[150:153]
	v_mfma_f32_16x16x32_bf16 v[158:161], v[4:7], v[116:119], v[158:161]
	v_mfma_f32_16x16x32_bf16 v[0:3], v[4:7], v[124:127], v[0:3]
	v_mfma_f32_16x16x32_bf16 v[4:7], v[8:11], v[120:123], 0
	v_mfma_f32_16x16x32_bf16 v[146:149], v[8:11], v[60:63], 0
	v_mfma_f32_16x16x32_bf16 v[154:157], v[8:11], v[104:107], 0
	v_mfma_f32_16x16x32_bf16 v[162:165], v[8:11], v[112:115], 0
	v_mfma_f32_16x16x32_bf16 v[4:7], v[12:15], v[124:127], v[4:7]
	v_mfma_f32_16x16x32_bf16 v[146:149], v[12:15], v[100:103], v[146:149]
	v_mfma_f32_16x16x32_bf16 v[154:157], v[12:15], v[108:111], v[154:157]
	v_mfma_f32_16x16x32_bf16 v[162:165], v[12:15], v[116:119], v[162:165]
	v_mfma_f32_16x16x32_bf16 v[8:11], v[16:19], v[60:63], 0
	v_mfma_f32_16x16x32_bf16 v[12:15], v[24:27], v[60:63], 0
	v_mfma_f32_16x16x32_bf16 v[8:11], v[20:23], v[100:103], v[8:11]
	v_mfma_f32_16x16x32_bf16 v[12:15], v[28:31], v[100:103], v[12:15]
	v_mfma_f32_16x16x32_bf16 v[60:63], v[16:19], v[104:107], 0
	v_mfma_f32_16x16x32_bf16 v[100:103], v[24:27], v[104:107], 0
	v_mfma_f32_16x16x32_bf16 v[104:107], v[16:19], v[112:115], 0
	v_mfma_f32_16x16x32_bf16 v[16:19], v[16:19], v[120:123], 0
	v_mfma_f32_16x16x32_bf16 v[60:63], v[20:23], v[108:111], v[60:63]
	v_mfma_f32_16x16x32_bf16 v[100:103], v[28:31], v[108:111], v[100:103]
	v_mfma_f32_16x16x32_bf16 v[104:107], v[20:23], v[116:119], v[104:107]
	v_mfma_f32_16x16x32_bf16 v[108:111], v[24:27], v[112:115], 0
	v_mfma_f32_16x16x32_bf16 v[16:19], v[20:23], v[124:127], v[16:19]
	v_mfma_f32_16x16x32_bf16 v[20:23], v[24:27], v[120:123], 0
	v_mfma_f32_16x16x32_bf16 v[108:111], v[28:31], v[116:119], v[108:111]
	v_mfma_f32_16x16x32_bf16 v[20:23], v[28:31], v[124:127], v[20:23]
	s_setprio 0
	s_barrier
	ds_read_b128 v[24:27], v140
	ds_read_b128 v[28:31], v140 offset:1024
	ds_read_b128 v[112:115], v140 offset:2048
	ds_read_b128 v[116:119], v140 offset:3072
	ds_read_b128 v[120:123], v141
	ds_read_b128 v[124:127], v141 offset:1024
	ds_read_b128 v[166:169], v141 offset:2048
	ds_read_b128 v[170:173], v141 offset:3072
	s_add_u32 s34, s40, 0x10100
	s_addc_u32 s35, s41, 0
	s_mov_b32 m0, s55
	v_lshl_add_u64 v[214:215], s[34:35], 0, v[134:135]
	ds_read_b128 v[174:177], v139 offset:32768
	ds_read_b128 v[178:181], v139 offset:33792
	ds_read_b128 v[182:185], v139 offset:34816
	ds_read_b128 v[186:189], v139 offset:35840
	ds_read_b128 v[190:193], v139 offset:36864
	ds_read_b128 v[194:197], v139 offset:37888
	ds_read_b128 v[198:201], v139 offset:38912
	ds_read_b128 v[202:205], v139 offset:39936
	global_load_lds_dwordx4 v[214:215], off
	v_lshl_add_u64 v[214:215], s[34:35], 0, v[130:131]
	s_mov_b32 m0, s56
	s_nop 0
	global_load_lds_dwordx4 v[214:215], off
	s_waitcnt vmcnt(8)
	s_waitcnt lgkmcnt(0)
	s_barrier
	s_setprio 1
	s_waitcnt lgkmcnt(0)
	v_mfma_f32_16x16x32_bf16 v[64:67], v[24:27], v[174:177], v[64:67]
	v_mfma_f32_16x16x32_bf16 v[68:71], v[112:115], v[174:177], v[68:71]
	v_mfma_f32_16x16x32_bf16 v[72:75], v[24:27], v[182:185], v[72:75]
	v_mfma_f32_16x16x32_bf16 v[76:79], v[112:115], v[182:185], v[76:79]
	v_mfma_f32_16x16x32_bf16 v[80:83], v[24:27], v[190:193], v[80:83]
	v_mfma_f32_16x16x32_bf16 v[84:87], v[112:115], v[190:193], v[84:87]
	v_mfma_f32_16x16x32_bf16 v[88:91], v[24:27], v[198:201], v[88:91]
	v_mfma_f32_16x16x32_bf16 v[92:95], v[112:115], v[198:201], v[92:95]
	v_mfma_f32_16x16x32_bf16 v[64:67], v[28:31], v[178:181], v[64:67]
	v_mfma_f32_16x16x32_bf16 v[68:71], v[116:119], v[178:181], v[68:71]
	v_mfma_f32_16x16x32_bf16 v[72:75], v[28:31], v[186:189], v[72:75]
	v_mfma_f32_16x16x32_bf16 v[76:79], v[116:119], v[186:189], v[76:79]
	v_mfma_f32_16x16x32_bf16 v[80:83], v[28:31], v[194:197], v[80:83]
	v_mfma_f32_16x16x32_bf16 v[84:87], v[116:119], v[194:197], v[84:87]
	v_mfma_f32_16x16x32_bf16 v[88:91], v[28:31], v[202:205], v[88:91]
	v_mfma_f32_16x16x32_bf16 v[92:95], v[116:119], v[202:205], v[92:95]
	v_mfma_f32_16x16x32_bf16 v[96:99], v[120:123], v[174:177], v[96:99]
	v_mfma_f32_16x16x32_bf16 v[32:35], v[166:169], v[174:177], v[32:35]
	v_mfma_f32_16x16x32_bf16 v[36:39], v[120:123], v[182:185], v[36:39]
	v_mfma_f32_16x16x32_bf16 v[40:43], v[166:169], v[182:185], v[40:43]
	v_mfma_f32_16x16x32_bf16 v[44:47], v[120:123], v[190:193], v[44:47]
	v_mfma_f32_16x16x32_bf16 v[48:51], v[166:169], v[190:193], v[48:51]
	v_mfma_f32_16x16x32_bf16 v[52:55], v[120:123], v[198:201], v[52:55]
	v_mfma_f32_16x16x32_bf16 v[56:59], v[166:169], v[198:201], v[56:59]
	v_mfma_f32_16x16x32_bf16 v[96:99], v[124:127], v[178:181], v[96:99]
	v_mfma_f32_16x16x32_bf16 v[32:35], v[170:173], v[178:181], v[32:35]
	v_mfma_f32_16x16x32_bf16 v[36:39], v[124:127], v[186:189], v[36:39]
	v_mfma_f32_16x16x32_bf16 v[40:43], v[170:173], v[186:189], v[40:43]
	v_mfma_f32_16x16x32_bf16 v[44:47], v[124:127], v[194:197], v[44:47]
	v_mfma_f32_16x16x32_bf16 v[48:51], v[170:173], v[194:197], v[48:51]
	v_mfma_f32_16x16x32_bf16 v[52:55], v[124:127], v[202:205], v[52:55]
	v_mfma_f32_16x16x32_bf16 v[56:59], v[170:173], v[202:205], v[56:59]
	s_setprio 0
	s_barrier
; #define PG8_STAGE(bufoff, gbase, voff) do { _Pragma("unroll") for (int _i = 0; _i < 2; ++_i) \
;         __builtin_amdgcn_global_load_lds((const unsigned*)((const char*)(gbase) + (voff)[_i]), (LAS unsigned*)(lds + (bufoff) + ldsw + _i * 8192), 16, 0, 0); } while (0)
; #define PG8_LDA(dst, b, h) do { _Pragma("unroll") for (int m = 0; m < 4; ++m) _Pragma("unroll") for (int k = 0; k < 2; ++k) dst[m][k] = *(const LAS bf16x8*)(lds + PG8_SA(b, h) + aoff + m * 2048 + k * 1024); } while (0)
; #define PG8_LDB(dst, b, h) do { _Pragma("unroll") for (int n = 0; n < 2; ++n) _Pragma("unroll") for (int k = 0; k < 2; ++k) dst[n][k] = *(const LAS bf16x8*)(lds + PG8_SB(b, h) + boff + n * 2048 + k * 1024); } while (0)
; #define PG8_MMA(ai, bj, At, Bt) do { __builtin_amdgcn_s_setprio(1); _Pragma("unroll") for (int m = 0; m < 4; ++m) _Pragma("unroll") for (int n = 0; n < 2; ++n) _Pragma("unroll") for (int k = 0; k < 2; ++k) \
;         acc[ai][bj][m][n] = __builtin_amdgcn_mfma_f32_16x16x32_bf16(Bt[n][k], At[m][k], acc[ai][bj][m][n], 0, 0, 0); __builtin_amdgcn_s_setprio(0); } while (0)
; #define PG8_WAIT_V(n) asm volatile("s_waitcnt vmcnt(" #n ")" ::: "memory")
; #define PG8_WAIT_L(n) asm volatile("s_waitcnt lgkmcnt(" #n ")" ::: "memory")
; #define PG8_BAR __builtin_amdgcn_s_barrier()
; #define PG8_SCHED __builtin_amdgcn_sched_barrier(0)
; template <class Epi, class Sched, bool ALIGN_EPI = false, bool SP2 = false, bool TWOA = false, bool AGM = false>
; __device__ __forceinline__ void gemm_phase(LAS unsigned char* lds, const Gemm g, const Sched& S, const Epi& E, int wid) {
;     ...
;             PG8_LDB(B0, 0, 0); PG8_LDB(B1, 0, 1); PG8_SCHED; PG8_LDA(At, 0, 0); PG8_STAGE(PG8_SA(1, 1), a1 + hstepA, voffA);
;             PG8_WAIT_V(8); PG8_WAIT_L(0); PG8_BAR; PG8_MMA(0, 0, At, B0); PG8_MMA(0, 1, At, B1); PG8_BAR; PG8_SCHED;
;     ...
;             PG8_LDA(At, 1, 1); PG8_STAGE(PG8_SB(1, 0), b3, voffB); PG8_STAGE(PG8_SB(1, 1), b3 + hstep, voffB); PG8_STAGE(PG8_SA(1, 0), a3, voffA);
;             PG8_WAIT_V(8); PG8_WAIT_L(0); PG8_BAR; PG8_MMA(1, 0, At, B0); PG8_MMA(1, 1, At, B1); PG8_BAR; PG8_SCHED;
	s_mov_b32 m0, s72
	v_lshl_add_u64 v[206:207], v[206:207], 0, s[22:23]
	s_add_u32 s34, s44, 0x10180
	ds_read_b128 v[174:177], v139 offset:49152
	ds_read_b128 v[178:181], v139 offset:50176
	ds_read_b128 v[182:185], v139 offset:51200
	ds_read_b128 v[186:189], v139 offset:52224
	ds_read_b128 v[190:193], v139 offset:53248
	ds_read_b128 v[194:197], v139 offset:54272
	ds_read_b128 v[198:201], v139 offset:55296
	ds_read_b128 v[202:205], v139 offset:56320
	global_load_lds_dwordx4 v[206:207], off
	v_lshl_add_u64 v[206:207], v[208:209], 0, s[22:23]
	s_mov_b32 m0, s73
	s_addc_u32 s35, s45, 0
	global_load_lds_dwordx4 v[206:207], off
	v_lshl_add_u64 v[206:207], s[34:35], 0, v[132:133]
	s_mov_b32 m0, s74
	s_nop 0
	global_load_lds_dwordx4 v[206:207], off
	v_lshl_add_u64 v[206:207], s[34:35], 0, v[128:129]
	s_mov_b32 m0, s75
	s_nop 0
	global_load_lds_dwordx4 v[206:207], off
	v_lshl_add_u64 v[206:207], v[210:211], 0, s[22:23]
	s_mov_b32 m0, s57
	s_nop 0
	global_load_lds_dwordx4 v[206:207], off
	v_lshl_add_u64 v[206:207], v[212:213], 0, s[22:23]
	s_mov_b32 m0, s64
	s_nop 0
	global_load_lds_dwordx4 v[206:207], off
	s_waitcnt vmcnt(8)
	s_waitcnt lgkmcnt(0)
	s_barrier
	s_setprio 1
	s_waitcnt lgkmcnt(0)
	v_mfma_f32_16x16x32_bf16 v[0:3], v[24:27], v[198:201], v[0:3]
	v_mfma_f32_16x16x32_bf16 v[4:7], v[112:115], v[198:201], v[4:7]
	v_mfma_f32_16x16x32_bf16 v[142:145], v[24:27], v[174:177], v[142:145]
	v_mfma_f32_16x16x32_bf16 v[146:149], v[112:115], v[174:177], v[146:149]
	v_mfma_f32_16x16x32_bf16 v[150:153], v[24:27], v[182:185], v[150:153]
	v_mfma_f32_16x16x32_bf16 v[154:157], v[112:115], v[182:185], v[154:157]
	v_mfma_f32_16x16x32_bf16 v[158:161], v[24:27], v[190:193], v[158:161]
	v_mfma_f32_16x16x32_bf16 v[162:165], v[112:115], v[190:193], v[162:165]
	v_mfma_f32_16x16x32_bf16 v[0:3], v[28:31], v[202:205], v[0:3]
	v_mfma_f32_16x16x32_bf16 v[4:7], v[116:119], v[202:205], v[4:7]
	v_mfma_f32_16x16x32_bf16 v[142:145], v[28:31], v[178:181], v[142:145]
	v_mfma_f32_16x16x32_bf16 v[146:149], v[116:119], v[178:181], v[146:149]
	v_mfma_f32_16x16x32_bf16 v[150:153], v[28:31], v[186:189], v[150:153]
	v_mfma_f32_16x16x32_bf16 v[154:157], v[116:119], v[186:189], v[154:157]
	v_mfma_f32_16x16x32_bf16 v[158:161], v[28:31], v[194:197], v[158:161]
	v_mfma_f32_16x16x32_bf16 v[162:165], v[116:119], v[194:197], v[162:165]
	v_mfma_f32_16x16x32_bf16 v[8:11], v[120:123], v[174:177], v[8:11]
	v_mfma_f32_16x16x32_bf16 v[12:15], v[166:169], v[174:177], v[12:15]
	v_mfma_f32_16x16x32_bf16 v[24:27], v[120:123], v[182:185], v[60:63]
	v_mfma_f32_16x16x32_bf16 v[28:31], v[166:169], v[182:185], v[100:103]
	v_mfma_f32_16x16x32_bf16 v[60:63], v[120:123], v[190:193], v[104:107]
	v_mfma_f32_16x16x32_bf16 v[100:103], v[166:169], v[190:193], v[108:111]
	v_mfma_f32_16x16x32_bf16 v[16:19], v[120:123], v[198:201], v[16:19]
	v_mfma_f32_16x16x32_bf16 v[20:23], v[166:169], v[198:201], v[20:23]
	v_mfma_f32_16x16x32_bf16 v[8:11], v[124:127], v[178:181], v[8:11]
	v_mfma_f32_16x16x32_bf16 v[12:15], v[170:173], v[178:181], v[12:15]
	v_mfma_f32_16x16x32_bf16 v[24:27], v[124:127], v[186:189], v[24:27]
	v_mfma_f32_16x16x32_bf16 v[28:31], v[170:173], v[186:189], v[28:31]
	v_mfma_f32_16x16x32_bf16 v[60:63], v[124:127], v[194:197], v[60:63]
	v_mfma_f32_16x16x32_bf16 v[100:103], v[170:173], v[194:197], v[100:103]
	v_mfma_f32_16x16x32_bf16 v[16:19], v[124:127], v[202:205], v[16:19]
	v_mfma_f32_16x16x32_bf16 v[20:23], v[170:173], v[202:205], v[20:23]
	s_setprio 0
	s_barrier
	ds_read_b128 v[104:107], v137
	ds_read_b128 v[108:111], v137 offset:1024
	ds_read_b128 v[112:115], v137 offset:2048
	ds_read_b128 v[116:119], v137 offset:3072
	ds_read_b128 v[120:123], v138
	ds_read_b128 v[124:127], v138 offset:1024
	ds_read_b128 v[166:169], v138 offset:2048
	ds_read_b128 v[170:173], v138 offset:3072
	s_add_u32 s34, s40, 0x10180
	s_addc_u32 s35, s41, 0
	s_mov_b32 m0, s66
	v_lshl_add_u64 v[206:207], s[34:35], 0, v[134:135]
	ds_read_b128 v[174:177], v139
	ds_read_b128 v[178:181], v139 offset:1024
	ds_read_b128 v[182:185], v139 offset:2048
	ds_read_b128 v[186:189], v139 offset:3072
	ds_read_b128 v[190:193], v139 offset:4096
	ds_read_b128 v[194:197], v139 offset:5120
	ds_read_b128 v[198:201], v139 offset:6144
	ds_read_b128 v[202:205], v139 offset:7168
	global_load_lds_dwordx4 v[206:207], off
	v_lshl_add_u64 v[206:207], s[34:35], 0, v[130:131]
	s_mov_b32 m0, s67
	s_nop 0
	global_load_lds_dwordx4 v[206:207], off
	s_waitcnt vmcnt(8)
	s_waitcnt lgkmcnt(0)
	s_barrier
	s_setprio 1
	s_waitcnt lgkmcnt(0)
	v_mfma_f32_16x16x32_bf16 v[88:91], v[104:107], v[198:201], v[88:91]
	v_mfma_f32_16x16x32_bf16 v[64:67], v[104:107], v[174:177], v[64:67]
	v_mfma_f32_16x16x32_bf16 v[68:71], v[112:115], v[174:177], v[68:71]
	v_mfma_f32_16x16x32_bf16 v[72:75], v[104:107], v[182:185], v[72:75]
	v_mfma_f32_16x16x32_bf16 v[76:79], v[112:115], v[182:185], v[76:79]
	v_mfma_f32_16x16x32_bf16 v[80:83], v[104:107], v[190:193], v[80:83]
	v_mfma_f32_16x16x32_bf16 v[84:87], v[112:115], v[190:193], v[84:87]
	v_mfma_f32_16x16x32_bf16 v[206:209], v[108:111], v[202:205], v[88:91]
	v_mfma_f32_16x16x32_bf16 v[88:91], v[112:115], v[198:201], v[92:95]
	v_mfma_f32_16x16x32_bf16 v[64:67], v[108:111], v[178:181], v[64:67]
	v_mfma_f32_16x16x32_bf16 v[68:71], v[116:119], v[178:181], v[68:71]
	v_mfma_f32_16x16x32_bf16 v[72:75], v[108:111], v[186:189], v[72:75]
	v_mfma_f32_16x16x32_bf16 v[76:79], v[116:119], v[186:189], v[76:79]
	v_mfma_f32_16x16x32_bf16 v[80:83], v[108:111], v[194:197], v[80:83]
	v_mfma_f32_16x16x32_bf16 v[84:87], v[116:119], v[194:197], v[84:87]
	v_mfma_f32_16x16x32_bf16 v[92:95], v[116:119], v[202:205], v[88:91]
	v_mfma_f32_16x16x32_bf16 v[48:51], v[166:169], v[190:193], v[48:51]
	v_mfma_f32_16x16x32_bf16 v[88:91], v[120:123], v[174:177], v[96:99]
	v_mfma_f32_16x16x32_bf16 v[32:35], v[166:169], v[174:177], v[32:35]
	v_mfma_f32_16x16x32_bf16 v[36:39], v[120:123], v[182:185], v[36:39]
	v_mfma_f32_16x16x32_bf16 v[40:43], v[166:169], v[182:185], v[40:43]
	v_mfma_f32_16x16x32_bf16 v[44:47], v[120:123], v[190:193], v[44:47]
	v_mfma_f32_16x16x32_bf16 v[174:177], v[170:173], v[194:197], v[48:51]
	v_mfma_f32_16x16x32_bf16 v[48:51], v[120:123], v[198:201], v[52:55]
	v_mfma_f32_16x16x32_bf16 v[32:35], v[170:173], v[178:181], v[32:35]
	v_mfma_f32_16x16x32_bf16 v[36:39], v[124:127], v[186:189], v[36:39]
	v_mfma_f32_16x16x32_bf16 v[40:43], v[170:173], v[186:189], v[40:43]
	v_mfma_f32_16x16x32_bf16 v[44:47], v[124:127], v[194:197], v[44:47]
	v_mfma_f32_16x16x32_bf16 v[52:55], v[124:127], v[202:205], v[48:51]
	v_mfma_f32_16x16x32_bf16 v[48:51], v[166:169], v[198:201], v[56:59]
	v_mfma_f32_16x16x32_bf16 v[210:213], v[124:127], v[178:181], v[88:91]
	v_mfma_f32_16x16x32_bf16 v[178:181], v[170:173], v[202:205], v[48:51]
	s_setprio 0
	s_barrier
; #define PG8_STAGE(bufoff, gbase, voff) do { _Pragma("unroll") for (int _i = 0; _i < 2; ++_i) \
;         __builtin_amdgcn_global_load_lds((const unsigned*)((const char*)(gbase) + (voff)[_i]), (LAS unsigned*)(lds + (bufoff) + ldsw + _i * 8192), 16, 0, 0); } while (0)
; #define PG8_LDA(dst, b, h) do { _Pragma("unroll") for (int m = 0; m < 4; ++m) _Pragma("unroll") for (int k = 0; k < 2; ++k) dst[m][k] = *(const LAS bf16x8*)(lds + PG8_SA(b, h) + aoff + m * 2048 + k * 1024); } while (0)
; #define PG8_LDB(dst, b, h) do { _Pragma("unroll") for (int n = 0; n < 2; ++n) _Pragma("unroll") for (int k = 0; k < 2; ++k) dst[n][k] = *(const LAS bf16x8*)(lds + PG8_SB(b, h) + boff + n * 2048 + k * 1024); } while (0)
; #define PG8_MMA(ai, bj, At, Bt) do { __builtin_amdgcn_s_setprio(1); _Pragma("unroll") for (int m = 0; m < 4; ++m) _Pragma("unroll") for (int n = 0; n < 2; ++n) _Pragma("unroll") for (int k = 0; k < 2; ++k) \
;         acc[ai][bj][m][n] = __builtin_amdgcn_mfma_f32_16x16x32_bf16(Bt[n][k], At[m][k], acc[ai][bj][m][n], 0, 0, 0); __builtin_amdgcn_s_setprio(0); } while (0)
; #define PG8_WAIT_V(n) asm volatile("s_waitcnt vmcnt(" #n ")" ::: "memory")
; #define PG8_WAIT_L(n) asm volatile("s_waitcnt lgkmcnt(" #n ")" ::: "memory")
; #define PG8_BAR __builtin_amdgcn_s_barrier()
; #define PG8_SCHED __builtin_amdgcn_sched_barrier(0)
; template <class Epi, class Sched, bool ALIGN_EPI = false, bool SP2 = false, bool TWOA = false, bool AGM = false>
; __device__ __forceinline__ void gemm_phase(LAS unsigned char* lds, const Gemm g, const Sched& S, const Epi& E, int wid) {
;     ...
;             PG8_LDA(At, 0, 1); PG8_STAGE(PG8_SB(0, 0), b2, voffB); PG8_STAGE(PG8_SB(0, 1), b2 + hstep, voffB); PG8_STAGE(PG8_SA(0, 0), a2, voffA);
;             PG8_WAIT_V(8); PG8_WAIT_L(0); PG8_BAR; PG8_MMA(1, 0, At, B0); PG8_MMA(1, 1, At, B1); PG8_BAR; PG8_SCHED;
;             PG8_LDB(B0, 1, 0); PG8_LDB(B1, 1, 1); PG8_SCHED; PG8_LDA(At, 1, 0); PG8_STAGE(PG8_SA(0, 1), a2 + hstepA, voffA);
	s_mov_b32 m0, s68
	v_lshl_add_u64 v[246:247], s[42:43], 0, v[132:133]
	s_add_u32 s34, s42, 0x10000
	s_nop 0
	ds_read_b128 v[48:51], v139 offset:16384
	ds_read_b128 v[56:59], v139 offset:17408
	ds_read_b128 v[88:91], v139 offset:18432
	ds_read_b128 v[96:99], v139 offset:19456
	ds_read_b128 v[182:185], v139 offset:20480
	ds_read_b128 v[186:189], v139 offset:21504
	ds_read_b128 v[190:193], v139 offset:22528
	ds_read_b128 v[194:197], v139 offset:23552
	global_load_lds_dwordx4 v[246:247], off
	v_lshl_add_u64 v[248:249], s[42:43], 0, v[128:129]
	s_mov_b32 m0, s69
	s_addc_u32 s35, s43, 0
	global_load_lds_dwordx4 v[248:249], off
	v_lshl_add_u64 v[198:199], s[34:35], 0, v[132:133]
	s_mov_b32 m0, s70
	v_lshl_add_u64 v[250:251], s[46:47], 0, v[134:135]
	global_load_lds_dwordx4 v[198:199], off
	v_lshl_add_u64 v[198:199], s[34:35], 0, v[128:129]
	s_mov_b32 m0, s71
	v_lshl_add_u64 v[252:253], s[46:47], 0, v[130:131]
	global_load_lds_dwordx4 v[198:199], off
	s_mov_b32 m0, s53
	s_nop 0
	global_load_lds_dwordx4 v[250:251], off
	s_mov_b32 m0, s54
	s_nop 0
	global_load_lds_dwordx4 v[252:253], off
	s_waitcnt vmcnt(8)
	s_waitcnt lgkmcnt(0)
	s_barrier
	s_setprio 1
	s_waitcnt lgkmcnt(0)
	v_mfma_f32_16x16x32_bf16 v[0:3], v[104:107], v[190:193], v[0:3]
	v_mfma_f32_16x16x32_bf16 v[4:7], v[112:115], v[190:193], v[4:7]
	v_mfma_f32_16x16x32_bf16 v[142:145], v[104:107], v[48:51], v[142:145]
	v_mfma_f32_16x16x32_bf16 v[146:149], v[112:115], v[48:51], v[146:149]
	v_mfma_f32_16x16x32_bf16 v[150:153], v[104:107], v[88:91], v[150:153]
	v_mfma_f32_16x16x32_bf16 v[154:157], v[112:115], v[88:91], v[154:157]
	v_mfma_f32_16x16x32_bf16 v[158:161], v[104:107], v[182:185], v[158:161]
	v_mfma_f32_16x16x32_bf16 v[162:165], v[112:115], v[182:185], v[162:165]
	v_mfma_f32_16x16x32_bf16 v[0:3], v[108:111], v[194:197], v[0:3]
	v_mfma_f32_16x16x32_bf16 v[4:7], v[116:119], v[194:197], v[4:7]
	v_mfma_f32_16x16x32_bf16 v[142:145], v[108:111], v[56:59], v[142:145]
	v_mfma_f32_16x16x32_bf16 v[146:149], v[116:119], v[56:59], v[146:149]
	v_mfma_f32_16x16x32_bf16 v[150:153], v[108:111], v[96:99], v[150:153]
	v_mfma_f32_16x16x32_bf16 v[154:157], v[116:119], v[96:99], v[154:157]
	v_mfma_f32_16x16x32_bf16 v[158:161], v[108:111], v[186:189], v[158:161]
	v_mfma_f32_16x16x32_bf16 v[162:165], v[116:119], v[186:189], v[162:165]
	v_mfma_f32_16x16x32_bf16 v[8:11], v[120:123], v[48:51], v[8:11]
	v_mfma_f32_16x16x32_bf16 v[198:201], v[124:127], v[56:59], v[8:11]
	v_mfma_f32_16x16x32_bf16 v[8:11], v[166:169], v[48:51], v[12:15]
	v_mfma_f32_16x16x32_bf16 v[12:15], v[170:173], v[56:59], v[8:11]
	v_mfma_f32_16x16x32_bf16 v[8:11], v[120:123], v[88:91], v[24:27]
	v_mfma_f32_16x16x32_bf16 v[202:205], v[124:127], v[96:99], v[8:11]
	v_mfma_f32_16x16x32_bf16 v[8:11], v[166:169], v[88:91], v[28:31]
	v_mfma_f32_16x16x32_bf16 v[28:31], v[170:173], v[96:99], v[8:11]
	v_mfma_f32_16x16x32_bf16 v[8:11], v[120:123], v[182:185], v[60:63]
	v_mfma_f32_16x16x32_bf16 v[214:217], v[124:127], v[186:189], v[8:11]
	v_mfma_f32_16x16x32_bf16 v[8:11], v[166:169], v[182:185], v[100:103]
	v_mfma_f32_16x16x32_bf16 v[182:185], v[170:173], v[186:189], v[8:11]
	v_mfma_f32_16x16x32_bf16 v[8:11], v[120:123], v[190:193], v[16:19]
	v_mfma_f32_16x16x32_bf16 v[186:189], v[124:127], v[194:197], v[8:11]
	v_mfma_f32_16x16x32_bf16 v[8:11], v[166:169], v[190:193], v[20:23]
	v_mfma_f32_16x16x32_bf16 v[166:169], v[170:173], v[194:197], v[8:11]
	s_setprio 0
	s_barrier
	s_nop 4
	ds_read_b128 v[8:11], v140
	ds_read_b128 v[20:23], v140 offset:1024
	ds_read_b128 v[170:173], v140 offset:2048
	ds_read_b128 v[190:193], v140 offset:3072
	ds_read_b128 v[194:197], v141
	ds_read_b128 v[218:221], v141 offset:1024
	ds_read_b128 v[222:225], v141 offset:2048
	ds_read_b128 v[226:229], v141 offset:3072
	s_add_u32 s34, s46, 0x10000
	s_addc_u32 s35, s47, 0
	s_mov_b32 m0, s55
	v_lshl_add_u64 v[48:49], s[34:35], 0, v[134:135]
	ds_read_b128 v[16:19], v139 offset:32768
	ds_read_b128 v[24:27], v139 offset:33792
	ds_read_b128 v[60:63], v139 offset:34816
	ds_read_b128 v[100:103], v139 offset:35840
	ds_read_b128 v[230:233], v139 offset:36864
	ds_read_b128 v[234:237], v139 offset:37888
	ds_read_b128 v[238:241], v139 offset:38912
	ds_read_b128 v[242:245], v139 offset:39936
	global_load_lds_dwordx4 v[48:49], off
	v_lshl_add_u64 v[48:49], s[34:35], 0, v[130:131]
	s_mov_b32 m0, s56
	s_nop 0
	global_load_lds_dwordx4 v[48:49], off
	s_waitcnt vmcnt(8)
	s_waitcnt lgkmcnt(0)
	s_barrier
; #define PG8_STAGE(bufoff, gbase, voff) do { _Pragma("unroll") for (int _i = 0; _i < 2; ++_i) \
;         __builtin_amdgcn_global_load_lds((const unsigned*)((const char*)(gbase) + (voff)[_i]), (LAS unsigned*)(lds + (bufoff) + ldsw + _i * 8192), 16, 0, 0); } while (0)
; #define PG8_LDA(dst, b, h) do { _Pragma("unroll") for (int m = 0; m < 4; ++m) _Pragma("unroll") for (int k = 0; k < 2; ++k) dst[m][k] = *(const LAS bf16x8*)(lds + PG8_SA(b, h) + aoff + m * 2048 + k * 1024); } while (0)
; #define PG8_MMA(ai, bj, At, Bt) do { __builtin_amdgcn_s_setprio(1); _Pragma("unroll") for (int m = 0; m < 4; ++m) _Pragma("unroll") for (int n = 0; n < 2; ++n) _Pragma("unroll") for (int k = 0; k < 2; ++k) \
;         acc[ai][bj][m][n] = __builtin_amdgcn_mfma_f32_16x16x32_bf16(Bt[n][k], At[m][k], acc[ai][bj][m][n], 0, 0, 0); __builtin_amdgcn_s_setprio(0); } while (0)
; #define PG8_WAIT_V(n) asm volatile("s_waitcnt vmcnt(" #n ")" ::: "memory")
; #define PG8_WAIT_L(n) asm volatile("s_waitcnt lgkmcnt(" #n ")" ::: "memory")
; #define PG8_BAR __builtin_amdgcn_s_barrier()
; #define PG8_SCHED __builtin_amdgcn_sched_barrier(0)
; template <class Epi, class Sched, bool ALIGN_EPI = false, bool SP2 = false, bool TWOA = false, bool AGM = false>
; __device__ __forceinline__ void gemm_phase(LAS unsigned char* lds, const Gemm g, const Sched& S, const Epi& E, int wid) {
;     ...
;             PG8_WAIT_V(8); PG8_WAIT_L(0); PG8_BAR; PG8_MMA(0, 0, At, B0); PG8_MMA(0, 1, At, B1); PG8_BAR; PG8_SCHED;
;             PG8_LDA(At, 1, 1); PG8_STAGE(PG8_SB(1, 0), b3, voffB); PG8_STAGE(PG8_SB(1, 1), b3 + hstep, voffB); PG8_STAGE(PG8_SA(1, 0), a3, voffA);
;             PG8_WAIT_V(8); PG8_WAIT_L(0); PG8_BAR; PG8_MMA(1, 0, At, B0); PG8_MMA(1, 1, At, B1); PG8_BAR; PG8_SCHED;
;     ...
;         if constexpr (ALIGN_EPI) { if (wr == 0) PG8_BAR; }
	s_setprio 1
	s_waitcnt lgkmcnt(0)
	v_mfma_f32_16x16x32_bf16 v[48:51], v[8:11], v[16:19], v[64:67]
	v_mfma_f32_16x16x32_bf16 v[120:123], v[20:23], v[24:27], v[48:51]
	v_mfma_f32_16x16x32_bf16 v[48:51], v[170:173], v[16:19], v[68:71]
	v_mfma_f32_16x16x32_bf16 v[112:115], v[190:193], v[24:27], v[48:51]
	v_mfma_f32_16x16x32_bf16 v[48:51], v[8:11], v[60:63], v[72:75]
	v_mfma_f32_16x16x32_bf16 v[104:107], v[20:23], v[100:103], v[48:51]
	v_mfma_f32_16x16x32_bf16 v[48:51], v[170:173], v[60:63], v[76:79]
	v_mfma_f32_16x16x32_bf16 v[96:99], v[190:193], v[100:103], v[48:51]
	v_mfma_f32_16x16x32_bf16 v[48:51], v[8:11], v[230:233], v[80:83]
	v_mfma_f32_16x16x32_bf16 v[88:91], v[20:23], v[234:237], v[48:51]
	v_mfma_f32_16x16x32_bf16 v[48:51], v[170:173], v[230:233], v[84:87]
	v_mfma_f32_16x16x32_bf16 v[80:83], v[190:193], v[234:237], v[48:51]
	v_mfma_f32_16x16x32_bf16 v[48:51], v[8:11], v[238:241], v[206:209]
	v_mfma_f32_16x16x32_bf16 v[56:59], v[20:23], v[242:245], v[48:51]
	v_mfma_f32_16x16x32_bf16 v[48:51], v[170:173], v[238:241], v[92:95]
	v_mfma_f32_16x16x32_bf16 v[48:51], v[190:193], v[242:245], v[48:51]
	v_mfma_f32_16x16x32_bf16 v[64:67], v[194:197], v[16:19], v[210:213]
	v_mfma_f32_16x16x32_bf16 v[16:19], v[222:225], v[16:19], v[32:35]
	v_mfma_f32_16x16x32_bf16 v[116:119], v[226:229], v[24:27], v[16:19]
	v_mfma_f32_16x16x32_bf16 v[16:19], v[194:197], v[60:63], v[36:39]
	v_mfma_f32_16x16x32_bf16 v[108:111], v[218:221], v[100:103], v[16:19]
	v_mfma_f32_16x16x32_bf16 v[16:19], v[222:225], v[60:63], v[40:43]
	v_mfma_f32_16x16x32_bf16 v[100:103], v[226:229], v[100:103], v[16:19]
	v_mfma_f32_16x16x32_bf16 v[16:19], v[194:197], v[230:233], v[44:47]
	v_mfma_f32_16x16x32_bf16 v[92:95], v[218:221], v[234:237], v[16:19]
	v_mfma_f32_16x16x32_bf16 v[16:19], v[222:225], v[230:233], v[174:177]
	v_mfma_f32_16x16x32_bf16 v[84:87], v[226:229], v[234:237], v[16:19]
	v_mfma_f32_16x16x32_bf16 v[16:19], v[194:197], v[238:241], v[52:55]
	v_mfma_f32_16x16x32_bf16 v[60:63], v[218:221], v[242:245], v[16:19]
	v_mfma_f32_16x16x32_bf16 v[16:19], v[222:225], v[238:241], v[178:181]
	v_mfma_f32_16x16x32_bf16 v[124:127], v[218:221], v[24:27], v[64:67]
	v_mfma_f32_16x16x32_bf16 v[52:55], v[226:229], v[242:245], v[16:19]
	s_setprio 0
	s_barrier
	s_mov_b32 m0, s72
	s_nop 2
	v_lshl_add_u64 v[16:17], v[246:247], 0, s[12:13]
	s_add_u32 s34, s42, 0x10080
	ds_read_b128 v[36:39], v139 offset:49152
	ds_read_b128 v[44:47], v139 offset:50176
	ds_read_b128 v[174:177], v139 offset:51200
	ds_read_b128 v[178:181], v139 offset:52224
	ds_read_b128 v[206:209], v139 offset:53248
	ds_read_b128 v[210:213], v139 offset:54272
	ds_read_b128 v[230:233], v139 offset:55296
	ds_read_b128 v[234:237], v139 offset:56320
	global_load_lds_dwordx4 v[16:17], off
	v_lshl_add_u64 v[16:17], v[248:249], 0, s[12:13]
	s_mov_b32 m0, s73
	s_addc_u32 s35, s43, 0
	global_load_lds_dwordx4 v[16:17], off
	v_lshl_add_u64 v[16:17], s[34:35], 0, v[132:133]
	s_mov_b32 m0, s74
	s_nop 0
	global_load_lds_dwordx4 v[16:17], off
	v_lshl_add_u64 v[16:17], s[34:35], 0, v[128:129]
	s_mov_b32 m0, s75
	s_nop 0
	global_load_lds_dwordx4 v[16:17], off
	v_lshl_add_u64 v[16:17], v[250:251], 0, s[12:13]
	s_mov_b32 m0, s57
	s_nop 0
	global_load_lds_dwordx4 v[16:17], off
	v_lshl_add_u64 v[16:17], v[252:253], 0, s[12:13]
	s_mov_b32 m0, s64
	s_nop 0
	global_load_lds_dwordx4 v[16:17], off
	s_waitcnt vmcnt(8)
	s_waitcnt lgkmcnt(0)
	s_barrier
	s_setprio 1
	s_waitcnt lgkmcnt(0)
	v_mfma_f32_16x16x32_bf16 v[16:19], v[8:11], v[36:39], v[142:145]
	v_mfma_f32_16x16x32_bf16 v[72:75], v[20:23], v[44:47], v[16:19]
	v_mfma_f32_16x16x32_bf16 v[16:19], v[170:173], v[36:39], v[146:149]
	v_mfma_f32_16x16x32_bf16 v[64:67], v[190:193], v[44:47], v[16:19]
	v_mfma_f32_16x16x32_bf16 v[16:19], v[8:11], v[174:177], v[150:153]
	v_mfma_f32_16x16x32_bf16 v[40:43], v[20:23], v[178:181], v[16:19]
	v_mfma_f32_16x16x32_bf16 v[16:19], v[170:173], v[174:177], v[154:157]
	v_mfma_f32_16x16x32_bf16 v[32:35], v[190:193], v[178:181], v[16:19]
	v_mfma_f32_16x16x32_bf16 v[16:19], v[8:11], v[206:209], v[158:161]
	v_mfma_f32_16x16x32_bf16 v[0:3], v[8:11], v[230:233], v[0:3]
	v_mfma_f32_16x16x32_bf16 v[24:27], v[20:23], v[210:213], v[16:19]
	v_mfma_f32_16x16x32_bf16 v[16:19], v[170:173], v[206:209], v[162:165]
	v_mfma_f32_16x16x32_bf16 v[8:11], v[20:23], v[234:237], v[0:3]
	v_mfma_f32_16x16x32_bf16 v[0:3], v[170:173], v[230:233], v[4:7]
	v_mfma_f32_16x16x32_bf16 v[16:19], v[190:193], v[210:213], v[16:19]
	v_mfma_f32_16x16x32_bf16 v[0:3], v[190:193], v[234:237], v[0:3]
	v_mfma_f32_16x16x32_bf16 v[4:7], v[194:197], v[36:39], v[198:201]
	v_mfma_f32_16x16x32_bf16 v[76:79], v[218:221], v[44:47], v[4:7]
	v_mfma_f32_16x16x32_bf16 v[4:7], v[222:225], v[36:39], v[12:15]
	v_mfma_f32_16x16x32_bf16 v[68:71], v[226:229], v[44:47], v[4:7]
	v_mfma_f32_16x16x32_bf16 v[4:7], v[194:197], v[174:177], v[202:205]
	v_mfma_f32_16x16x32_bf16 v[44:47], v[218:221], v[178:181], v[4:7]
	v_mfma_f32_16x16x32_bf16 v[4:7], v[222:225], v[174:177], v[28:31]
	v_mfma_f32_16x16x32_bf16 v[36:39], v[226:229], v[178:181], v[4:7]
	v_mfma_f32_16x16x32_bf16 v[4:7], v[194:197], v[206:209], v[214:217]
	v_mfma_f32_16x16x32_bf16 v[28:31], v[218:221], v[210:213], v[4:7]
	v_mfma_f32_16x16x32_bf16 v[4:7], v[222:225], v[206:209], v[182:185]
	v_mfma_f32_16x16x32_bf16 v[20:23], v[226:229], v[210:213], v[4:7]
	v_mfma_f32_16x16x32_bf16 v[4:7], v[194:197], v[230:233], v[186:189]
	v_mfma_f32_16x16x32_bf16 v[12:15], v[218:221], v[234:237], v[4:7]
	v_mfma_f32_16x16x32_bf16 v[4:7], v[222:225], v[230:233], v[166:169]
	v_mfma_f32_16x16x32_bf16 v[4:7], v[226:229], v[234:237], v[4:7]
	s_setprio 0
	s_barrier
	s_and_b64 vcc, exec, s[4:5]
	s_cbranch_vccnz .LBB0_525
	s_barrier

; #define PG8_STAGE(bufoff, gbase, voff) do { _Pragma("unroll") for (int _i = 0; _i < 2; ++_i) \
;         __builtin_amdgcn_global_load_lds((const unsigned*)((const char*)(gbase) + (voff)[_i]), (LAS unsigned*)(lds + (bufoff) + ldsw + _i * 8192), 16, 0, 0); } while (0)
; #define PG8_LDA(dst, b, h) do { _Pragma("unroll") for (int m = 0; m < 4; ++m) _Pragma("unroll") for (int k = 0; k < 2; ++k) dst[m][k] = *(const LAS bf16x8*)(lds + PG8_SA(b, h) + aoff + m * 2048 + k * 1024); } while (0)
; #define PG8_LDB(dst, b, h) do { _Pragma("unroll") for (int n = 0; n < 2; ++n) _Pragma("unroll") for (int k = 0; k < 2; ++k) dst[n][k] = *(const LAS bf16x8*)(lds + PG8_SB(b, h) + boff + n * 2048 + k * 1024); } while (0)
; #define PG8_WAIT_V(n) asm volatile("s_waitcnt vmcnt(" #n ")" ::: "memory")
; #define PG8_BAR __builtin_amdgcn_s_barrier()
; template <class Epi, class Sched, bool ALIGN_EPI = false, bool SP2 = false, bool TWOA = false, bool AGM = false>
; __device__ __forceinline__ void gemm_phase(LAS unsigned char* lds, const Gemm g, const Sched& S, const Epi& E, int wid) {
;     ...
;         const bool has_next = S.next(ui + 1, nxt);
;         const char* nA = has_next ? (const char*)g.A + (size_t)nxt.pm * tstepA : cA; const char* nB = has_next ? (const char*)g.Bt + (size_t)nxt.pn * tstep : cB;
;         for (int t = 0; t < nt; t += 2) {
;             const bool last = (t == nt - 2);
;             const char* cA2 = TWOA ? (const char*)g.A2 + (cA - (const char*)g.A) - (size_t)nh * kstepA : cA;
;             const char* a1_ = (TWOA && t + 1 >= nh ? cA2 : cA) + (size_t)(t + 1) * kstepA;
;             const char* a2_ = last ? nA : (TWOA && t + 2 >= nh ? cA2 : cA) + (size_t)(t + 2) * kstepA; const char* a1 = a1_; const char* a2 = a2_; const char* b2 = last ? nB : cB + (size_t)(t + 2) * kstep;
;             if constexpr (TWOA) { asm volatile("" : "+s"(a1)); asm volatile("" : "+s"(a2)); }
;             const char* a3 = a2 + kstepA; const char* b3 = b2 + kstep;
;             if (last && has_next) S.a_ready(nxt);
;             if constexpr (has_mid<Epi>::value) { if (t == nh) E.mid(acc, cur, wr, wc, fr, fq); }
;             if constexpr (SP2) {
;             PG8_LDB(B0, 0, 0); PG8_LDB(B1, 0, 1); PG8_SCHED; PG8_LDA(At, 0, 0); PG8_STAGE(PG8_SA(1, 1), a1 + hstepA, voffA);
;             PG8_WAIT_V(8); PG8_WAIT_L(0); PG8_BAR; PG8_MMA(0, 0, At, B0); PG8_MMA(0, 1, At, B1); PG8_BAR; PG8_SCHED;
.LBB0_682:
	s_ashr_i32 s37, s36, 31
	s_lshl_b64 s[34:35], s[36:37], 17
	s_add_u32 s38, s8, s34
	s_addc_u32 s39, s9, s35
	s_and_b64 s[34:35], s[42:43], exec
	s_cselect_b32 s37, s39, s55
	s_cselect_b32 s80, s38, s54
	s_ashr_i32 s31, s30, 31
	s_lshl_b64 s[34:35], s[30:31], 18
	s_add_u32 s40, s68, s34
	s_addc_u32 s41, s69, s35
	s_and_b64 s[34:35], s[42:43], exec
	s_cselect_b32 s31, s41, s53
	s_cselect_b32 s82, s40, s52
	s_sub_u32 s34, s54, s8
	s_subb_u32 s35, s55, s9
	s_add_u32 s50, s72, s34
	s_addc_u32 s51, s73, s35
	s_add_u32 s34, s54, 0x80
	s_addc_u32 s35, s55, 0
	s_add_u32 s56, s54, 0x100
	s_addc_u32 s57, s55, 0
	ds_read_b128 v[4:7], v157
	ds_read_b128 v[8:11], v157 offset:1024
	ds_read_b128 v[12:15], v157 offset:2048
	ds_read_b128 v[16:19], v157 offset:3072
	ds_read_b128 v[20:23], v158
	ds_read_b128 v[24:27], v158 offset:1024
	ds_read_b128 v[28:31], v158 offset:2048
	ds_read_b128 v[32:35], v158 offset:3072
	s_add_u32 s34, s34, 0x10000
	s_addc_u32 s35, s35, 0
	s_add_i32 s83, s45, 0xc000
	v_lshl_add_u64 v[64:65], s[34:35], 0, v[134:135]
	s_mov_b32 m0, s83
	s_add_i32 s84, s45, 0xe000
	ds_read_b128 v[0:3], v137
	ds_read_b128 v[36:39], v137 offset:1024
	ds_read_b128 v[40:43], v137 offset:2048
	ds_read_b128 v[44:47], v137 offset:3072
	ds_read_b128 v[48:51], v137 offset:4096
	ds_read_b128 v[52:55], v137 offset:5120
	ds_read_b128 v[56:59], v137 offset:6144
	ds_read_b128 v[60:63], v137 offset:7168
	global_load_lds_dwordx4 v[64:65], off
	v_lshl_add_u64 v[64:65], s[34:35], 0, v[130:131]
	s_mov_b32 m0, s84
	s_nop 0
	global_load_lds_dwordx4 v[64:65], off
	s_waitcnt vmcnt(8)
	s_waitcnt lgkmcnt(0)
	s_barrier
	s_setprio 1
	s_waitcnt lgkmcnt(0)
	v_mfma_f32_16x16x32_bf16 v[64:67], v[4:7], v[0:3], 0
	v_mfma_f32_16x16x32_bf16 v[68:71], v[12:15], v[0:3], 0
	v_mfma_f32_16x16x32_bf16 v[72:75], v[4:7], v[40:43], 0
	v_mfma_f32_16x16x32_bf16 v[76:79], v[12:15], v[40:43], 0
	v_mfma_f32_16x16x32_bf16 v[80:83], v[4:7], v[48:51], 0
	v_mfma_f32_16x16x32_bf16 v[84:87], v[12:15], v[48:51], 0
	v_mfma_f32_16x16x32_bf16 v[88:91], v[4:7], v[56:59], 0
	v_mfma_f32_16x16x32_bf16 v[92:95], v[12:15], v[56:59], 0
	v_mfma_f32_16x16x32_bf16 v[64:67], v[8:11], v[36:39], v[64:67]
	v_mfma_f32_16x16x32_bf16 v[68:71], v[16:19], v[36:39], v[68:71]
	v_mfma_f32_16x16x32_bf16 v[72:75], v[8:11], v[44:47], v[72:75]
	v_mfma_f32_16x16x32_bf16 v[76:79], v[16:19], v[44:47], v[76:79]
	v_mfma_f32_16x16x32_bf16 v[80:83], v[8:11], v[52:55], v[80:83]
	v_mfma_f32_16x16x32_bf16 v[84:87], v[16:19], v[52:55], v[84:87]
	v_mfma_f32_16x16x32_bf16 v[88:91], v[8:11], v[60:63], v[88:91]
	v_mfma_f32_16x16x32_bf16 v[92:95], v[16:19], v[60:63], v[92:95]
	v_mfma_f32_16x16x32_bf16 v[96:99], v[20:23], v[0:3], 0
	v_mfma_f32_16x16x32_bf16 v[0:3], v[28:31], v[0:3], 0
	v_mfma_f32_16x16x32_bf16 v[96:99], v[24:27], v[36:39], v[96:99]
	v_mfma_f32_16x16x32_bf16 v[36:39], v[32:35], v[36:39], v[0:3]
	v_mfma_f32_16x16x32_bf16 v[0:3], v[20:23], v[40:43], 0
	v_mfma_f32_16x16x32_bf16 v[100:103], v[24:27], v[44:47], v[0:3]
	v_mfma_f32_16x16x32_bf16 v[0:3], v[28:31], v[40:43], 0
	v_mfma_f32_16x16x32_bf16 v[40:43], v[32:35], v[44:47], v[0:3]
	v_mfma_f32_16x16x32_bf16 v[0:3], v[20:23], v[48:51], 0
	v_mfma_f32_16x16x32_bf16 v[44:47], v[24:27], v[52:55], v[0:3]
	v_mfma_f32_16x16x32_bf16 v[0:3], v[28:31], v[48:51], 0
	v_mfma_f32_16x16x32_bf16 v[48:51], v[32:35], v[52:55], v[0:3]
	v_mfma_f32_16x16x32_bf16 v[0:3], v[20:23], v[56:59], 0
	v_mfma_f32_16x16x32_bf16 v[52:55], v[24:27], v[60:63], v[0:3]
	v_mfma_f32_16x16x32_bf16 v[0:3], v[28:31], v[56:59], 0
	v_mfma_f32_16x16x32_bf16 v[56:59], v[32:35], v[60:63], v[0:3]
	s_setprio 0
	s_barrier
	s_nop 4
	v_lshl_add_u64 v[0:1], s[52:53], 0, v[132:133]
	s_add_i32 s85, s76, s3
	v_lshl_add_u64 v[2:3], v[0:1], 0, s[22:23]
	s_mov_b32 m0, s85
	s_add_i32 s86, s85, 0x2000
	ds_read_b128 v[60:63], v137 offset:16384
	ds_read_b128 v[104:107], v137 offset:17408
	ds_read_b128 v[108:111], v137 offset:18432
	ds_read_b128 v[112:115], v137 offset:19456
	ds_read_b128 v[116:119], v137 offset:20480
	ds_read_b128 v[120:123], v137 offset:21504
	ds_read_b128 v[124:127], v137 offset:22528
	ds_read_b128 v[160:163], v137 offset:23552
	global_load_lds_dwordx4 v[2:3], off
	v_lshl_add_u64 v[2:3], s[52:53], 0, v[128:129]
	s_add_u32 s34, s52, 0x20100
	v_lshl_add_u64 v[140:141], v[2:3], 0, s[22:23]
	s_mov_b32 m0, s86
	s_addc_u32 s35, s53, 0
	s_add_i32 s87, s77, s3
	global_load_lds_dwordx4 v[140:141], off
	v_lshl_add_u64 v[140:141], s[34:35], 0, v[132:133]
	s_mov_b32 m0, s87
	s_add_i32 s88, s87, 0x2000
	global_load_lds_dwordx4 v[140:141], off
	v_lshl_add_u64 v[140:141], s[34:35], 0, v[128:129]
	s_mov_b32 m0, s88
	v_lshl_add_u64 v[142:143], s[56:57], 0, v[130:131]
	global_load_lds_dwordx4 v[140:141], off
	v_lshl_add_u64 v[140:141], s[56:57], 0, v[134:135]
	s_mov_b32 m0, s45
	s_nop 0
	global_load_lds_dwordx4 v[140:141], off
	s_mov_b32 m0, s47
	s_nop 0
	global_load_lds_dwordx4 v[142:143], off
	s_waitcnt vmcnt(8)
	s_waitcnt lgkmcnt(0)
	s_barrier
; #define PG8_STAGE(bufoff, gbase, voff) do { _Pragma("unroll") for (int _i = 0; _i < 2; ++_i) \
;         __builtin_amdgcn_global_load_lds((const unsigned*)((const char*)(gbase) + (voff)[_i]), (LAS unsigned*)(lds + (bufoff) + ldsw + _i * 8192), 16, 0, 0); } while (0)
; #define PG8_LDA(dst, b, h) do { _Pragma("unroll") for (int m = 0; m < 4; ++m) _Pragma("unroll") for (int k = 0; k < 2; ++k) dst[m][k] = *(const LAS bf16x8*)(lds + PG8_SA(b, h) + aoff + m * 2048 + k * 1024); } while (0)
; #define PG8_LDB(dst, b, h) do { _Pragma("unroll") for (int n = 0; n < 2; ++n) _Pragma("unroll") for (int k = 0; k < 2; ++k) dst[n][k] = *(const LAS bf16x8*)(lds + PG8_SB(b, h) + boff + n * 2048 + k * 1024); } while (0)
; #define PG8_MMA(ai, bj, At, Bt) do { __builtin_amdgcn_s_setprio(1); _Pragma("unroll") for (int m = 0; m < 4; ++m) _Pragma("unroll") for (int n = 0; n < 2; ++n) _Pragma("unroll") for (int k = 0; k < 2; ++k) \
;         acc[ai][bj][m][n] = __builtin_amdgcn_mfma_f32_16x16x32_bf16(Bt[n][k], At[m][k], acc[ai][bj][m][n], 0, 0, 0); __builtin_amdgcn_s_setprio(0); } while (0)
; #define PG8_WAIT_V(n) asm volatile("s_waitcnt vmcnt(" #n ")" ::: "memory")
; #define PG8_WAIT_L(n) asm volatile("s_waitcnt lgkmcnt(" #n ")" ::: "memory")
; #define PG8_BAR __builtin_amdgcn_s_barrier()
; #define PG8_SCHED __builtin_amdgcn_sched_barrier(0)
; template <class Epi, class Sched, bool ALIGN_EPI = false, bool SP2 = false, bool TWOA = false, bool AGM = false>
; __device__ __forceinline__ void gemm_phase(LAS unsigned char* lds, const Gemm g, const Sched& S, const Epi& E, int wid) {
;     ...
;             PG8_WAIT_V(8); PG8_WAIT_L(0); PG8_BAR; PG8_MMA(1, 0, At, B0); PG8_MMA(1, 1, At, B1); PG8_BAR; PG8_SCHED;
;             PG8_LDB(B0, 1, 0); PG8_LDB(B1, 1, 1); PG8_SCHED; PG8_LDA(At, 1, 0); PG8_STAGE(PG8_SA(0, 1), a2 + hstepA, voffA);
;             PG8_WAIT_V(8); PG8_WAIT_L(0); PG8_BAR; PG8_MMA(0, 0, At, B0); PG8_MMA(0, 1, At, B1); PG8_BAR; PG8_SCHED;
	s_setprio 1
	s_waitcnt lgkmcnt(0)
	v_mfma_f32_16x16x32_bf16 v[164:167], v[4:7], v[60:63], 0
	v_mfma_f32_16x16x32_bf16 v[172:175], v[4:7], v[108:111], 0
	v_mfma_f32_16x16x32_bf16 v[180:183], v[4:7], v[116:119], 0
	v_mfma_f32_16x16x32_bf16 v[4:7], v[4:7], v[124:127], 0
	v_mfma_f32_16x16x32_bf16 v[164:167], v[8:11], v[104:107], v[164:167]
	v_mfma_f32_16x16x32_bf16 v[172:175], v[8:11], v[112:115], v[172:175]
	v_mfma_f32_16x16x32_bf16 v[180:183], v[8:11], v[120:123], v[180:183]
	v_mfma_f32_16x16x32_bf16 v[4:7], v[8:11], v[160:163], v[4:7]
	v_mfma_f32_16x16x32_bf16 v[8:11], v[12:15], v[124:127], 0
	v_mfma_f32_16x16x32_bf16 v[168:171], v[12:15], v[60:63], 0
	v_mfma_f32_16x16x32_bf16 v[176:179], v[12:15], v[108:111], 0
	v_mfma_f32_16x16x32_bf16 v[184:187], v[12:15], v[116:119], 0
	v_mfma_f32_16x16x32_bf16 v[8:11], v[16:19], v[160:163], v[8:11]
	v_mfma_f32_16x16x32_bf16 v[168:171], v[16:19], v[104:107], v[168:171]
	v_mfma_f32_16x16x32_bf16 v[176:179], v[16:19], v[112:115], v[176:179]
	v_mfma_f32_16x16x32_bf16 v[184:187], v[16:19], v[120:123], v[184:187]
	v_mfma_f32_16x16x32_bf16 v[12:15], v[20:23], v[60:63], 0
	v_mfma_f32_16x16x32_bf16 v[16:19], v[28:31], v[60:63], 0
	v_mfma_f32_16x16x32_bf16 v[12:15], v[24:27], v[104:107], v[12:15]
	v_mfma_f32_16x16x32_bf16 v[16:19], v[32:35], v[104:107], v[16:19]
	v_mfma_f32_16x16x32_bf16 v[60:63], v[20:23], v[108:111], 0
	v_mfma_f32_16x16x32_bf16 v[104:107], v[28:31], v[108:111], 0
	v_mfma_f32_16x16x32_bf16 v[108:111], v[20:23], v[116:119], 0
	v_mfma_f32_16x16x32_bf16 v[20:23], v[20:23], v[124:127], 0
	v_mfma_f32_16x16x32_bf16 v[60:63], v[24:27], v[112:115], v[60:63]
	v_mfma_f32_16x16x32_bf16 v[104:107], v[32:35], v[112:115], v[104:107]
	v_mfma_f32_16x16x32_bf16 v[108:111], v[24:27], v[120:123], v[108:111]
	v_mfma_f32_16x16x32_bf16 v[112:115], v[28:31], v[116:119], 0
	v_mfma_f32_16x16x32_bf16 v[20:23], v[24:27], v[160:163], v[20:23]
	v_mfma_f32_16x16x32_bf16 v[24:27], v[28:31], v[124:127], 0
	v_mfma_f32_16x16x32_bf16 v[112:115], v[32:35], v[120:123], v[112:115]
	v_mfma_f32_16x16x32_bf16 v[24:27], v[32:35], v[160:163], v[24:27]
	s_setprio 0
	s_barrier
	s_add_i32 s89, 0, 0x18000
	s_add_i32 s90, 0, 0x1c000
	v_add_u32_e32 v159, s89, v136
	v_add_u32_e32 v160, s90, v136
	ds_read_b128 v[28:31], v159
	ds_read_b128 v[32:35], v159 offset:1024
	ds_read_b128 v[116:119], v159 offset:2048
	ds_read_b128 v[120:123], v159 offset:3072
	ds_read_b128 v[124:127], v160
	ds_read_b128 v[188:191], v160 offset:1024
	ds_read_b128 v[192:195], v160 offset:2048
	ds_read_b128 v[196:199], v160 offset:3072
	s_add_u32 s34, s56, 0x10000
	s_addc_u32 s35, s57, 0
	s_mov_b32 m0, s70
	v_lshl_add_u64 v[144:145], s[34:35], 0, v[134:135]
	ds_read_b128 v[200:203], v137 offset:32768
	ds_read_b128 v[204:207], v137 offset:33792
	ds_read_b128 v[208:211], v137 offset:34816
	ds_read_b128 v[212:215], v137 offset:35840
	ds_read_b128 v[216:219], v137 offset:36864
	ds_read_b128 v[220:223], v137 offset:37888
	ds_read_b128 v[224:227], v137 offset:38912
	ds_read_b128 v[228:231], v137 offset:39936
	global_load_lds_dwordx4 v[144:145], off
	v_lshl_add_u64 v[144:145], s[34:35], 0, v[130:131]
	s_mov_b32 m0, s71
	s_nop 0
	global_load_lds_dwordx4 v[144:145], off
	s_waitcnt vmcnt(8)
	s_waitcnt lgkmcnt(0)
	s_barrier
	s_setprio 1
	s_waitcnt lgkmcnt(0)
	v_mfma_f32_16x16x32_bf16 v[64:67], v[28:31], v[200:203], v[64:67]
	v_mfma_f32_16x16x32_bf16 v[68:71], v[116:119], v[200:203], v[68:71]
	v_mfma_f32_16x16x32_bf16 v[72:75], v[28:31], v[208:211], v[72:75]
	v_mfma_f32_16x16x32_bf16 v[76:79], v[116:119], v[208:211], v[76:79]
	v_mfma_f32_16x16x32_bf16 v[80:83], v[28:31], v[216:219], v[80:83]
	v_mfma_f32_16x16x32_bf16 v[84:87], v[116:119], v[216:219], v[84:87]
	v_mfma_f32_16x16x32_bf16 v[88:91], v[28:31], v[224:227], v[88:91]
	v_mfma_f32_16x16x32_bf16 v[92:95], v[116:119], v[224:227], v[92:95]
	v_mfma_f32_16x16x32_bf16 v[64:67], v[32:35], v[204:207], v[64:67]
	v_mfma_f32_16x16x32_bf16 v[68:71], v[120:123], v[204:207], v[68:71]
	v_mfma_f32_16x16x32_bf16 v[72:75], v[32:35], v[212:215], v[72:75]
	v_mfma_f32_16x16x32_bf16 v[76:79], v[120:123], v[212:215], v[76:79]
	v_mfma_f32_16x16x32_bf16 v[80:83], v[32:35], v[220:223], v[80:83]
	v_mfma_f32_16x16x32_bf16 v[84:87], v[120:123], v[220:223], v[84:87]
	v_mfma_f32_16x16x32_bf16 v[88:91], v[32:35], v[228:231], v[88:91]
	v_mfma_f32_16x16x32_bf16 v[92:95], v[120:123], v[228:231], v[92:95]
	v_mfma_f32_16x16x32_bf16 v[96:99], v[124:127], v[200:203], v[96:99]
	v_mfma_f32_16x16x32_bf16 v[36:39], v[192:195], v[200:203], v[36:39]
	v_mfma_f32_16x16x32_bf16 v[100:103], v[124:127], v[208:211], v[100:103]
	v_mfma_f32_16x16x32_bf16 v[40:43], v[192:195], v[208:211], v[40:43]
	v_mfma_f32_16x16x32_bf16 v[44:47], v[124:127], v[216:219], v[44:47]
	v_mfma_f32_16x16x32_bf16 v[48:51], v[192:195], v[216:219], v[48:51]
	v_mfma_f32_16x16x32_bf16 v[52:55], v[124:127], v[224:227], v[52:55]
	v_mfma_f32_16x16x32_bf16 v[56:59], v[192:195], v[224:227], v[56:59]
	v_mfma_f32_16x16x32_bf16 v[96:99], v[188:191], v[204:207], v[96:99]
	v_mfma_f32_16x16x32_bf16 v[36:39], v[196:199], v[204:207], v[36:39]
	v_mfma_f32_16x16x32_bf16 v[100:103], v[188:191], v[212:215], v[100:103]
	v_mfma_f32_16x16x32_bf16 v[40:43], v[196:199], v[212:215], v[40:43]
	v_mfma_f32_16x16x32_bf16 v[44:47], v[188:191], v[220:223], v[44:47]
	v_mfma_f32_16x16x32_bf16 v[48:51], v[196:199], v[220:223], v[48:51]
	v_mfma_f32_16x16x32_bf16 v[52:55], v[188:191], v[228:231], v[52:55]
	v_mfma_f32_16x16x32_bf16 v[56:59], v[196:199], v[228:231], v[56:59]
	s_setprio 0
	s_barrier
; #define PG8_STAGE(bufoff, gbase, voff) do { _Pragma("unroll") for (int _i = 0; _i < 2; ++_i) \
;         __builtin_amdgcn_global_load_lds((const unsigned*)((const char*)(gbase) + (voff)[_i]), (LAS unsigned*)(lds + (bufoff) + ldsw + _i * 8192), 16, 0, 0); } while (0)
; #define PG8_LDA(dst, b, h) do { _Pragma("unroll") for (int m = 0; m < 4; ++m) _Pragma("unroll") for (int k = 0; k < 2; ++k) dst[m][k] = *(const LAS bf16x8*)(lds + PG8_SA(b, h) + aoff + m * 2048 + k * 1024); } while (0)
; #define PG8_LDB(dst, b, h) do { _Pragma("unroll") for (int n = 0; n < 2; ++n) _Pragma("unroll") for (int k = 0; k < 2; ++k) dst[n][k] = *(const LAS bf16x8*)(lds + PG8_SB(b, h) + boff + n * 2048 + k * 1024); } while (0)
; #define PG8_MMA(ai, bj, At, Bt) do { __builtin_amdgcn_s_setprio(1); _Pragma("unroll") for (int m = 0; m < 4; ++m) _Pragma("unroll") for (int n = 0; n < 2; ++n) _Pragma("unroll") for (int k = 0; k < 2; ++k) \
;         acc[ai][bj][m][n] = __builtin_amdgcn_mfma_f32_16x16x32_bf16(Bt[n][k], At[m][k], acc[ai][bj][m][n], 0, 0, 0); __builtin_amdgcn_s_setprio(0); } while (0)
; #define PG8_WAIT_V(n) asm volatile("s_waitcnt vmcnt(" #n ")" ::: "memory")
; #define PG8_WAIT_L(n) asm volatile("s_waitcnt lgkmcnt(" #n ")" ::: "memory")
; #define PG8_BAR __builtin_amdgcn_s_barrier()
; #define PG8_SCHED __builtin_amdgcn_sched_barrier(0)
; template <class Epi, class Sched, bool ALIGN_EPI = false, bool SP2 = false, bool TWOA = false, bool AGM = false>
; __device__ __forceinline__ void gemm_phase(LAS unsigned char* lds, const Gemm g, const Sched& S, const Epi& E, int wid) {
;     ...
;             PG8_LDB(B0, 0, 0); PG8_LDB(B1, 0, 1); PG8_SCHED; PG8_LDA(At, 0, 0); PG8_STAGE(PG8_SA(1, 1), a1 + hstepA, voffA);
;             PG8_WAIT_V(8); PG8_WAIT_L(0); PG8_BAR; PG8_MMA(0, 0, At, B0); PG8_MMA(0, 1, At, B1); PG8_BAR; PG8_SCHED;
;     ...
;             PG8_LDA(At, 1, 1); PG8_STAGE(PG8_SB(1, 0), b3, voffB); PG8_STAGE(PG8_SB(1, 1), b3 + hstep, voffB); PG8_STAGE(PG8_SA(1, 0), a3, voffA);
;             PG8_WAIT_V(8); PG8_WAIT_L(0); PG8_BAR; PG8_MMA(1, 0, At, B0); PG8_MMA(1, 1, At, B1); PG8_BAR; PG8_SCHED;
	s_add_i32 s56, s89, s3
	s_add_i32 s57, s56, 0x2000
	v_lshl_add_u64 v[144:145], v[0:1], 0, s[24:25]
	s_mov_b32 m0, s56
	s_add_u32 s34, s52, 0x20180
	ds_read_b128 v[200:203], v137 offset:49152
	ds_read_b128 v[204:207], v137 offset:50176
	ds_read_b128 v[208:211], v137 offset:51200
	ds_read_b128 v[212:215], v137 offset:52224
	ds_read_b128 v[216:219], v137 offset:53248
	ds_read_b128 v[220:223], v137 offset:54272
	ds_read_b128 v[224:227], v137 offset:55296
	ds_read_b128 v[228:231], v137 offset:56320
	global_load_lds_dwordx4 v[144:145], off
	v_lshl_add_u64 v[144:145], v[2:3], 0, s[24:25]
	s_mov_b32 m0, s57
	s_addc_u32 s35, s53, 0
	s_add_i32 s89, s90, s3
	global_load_lds_dwordx4 v[144:145], off
	v_lshl_add_u64 v[144:145], s[34:35], 0, v[132:133]
	s_mov_b32 m0, s89
	s_add_i32 s90, s89, 0x2000
	global_load_lds_dwordx4 v[144:145], off
	v_lshl_add_u64 v[144:145], s[34:35], 0, v[128:129]
	s_mov_b32 m0, s90
	v_lshl_add_u64 v[140:141], v[140:141], 0, s[12:13]
	global_load_lds_dwordx4 v[144:145], off
	s_mov_b32 m0, s74
	s_nop 0
	global_load_lds_dwordx4 v[140:141], off
	v_lshl_add_u64 v[140:141], v[142:143], 0, s[12:13]
	s_mov_b32 m0, s75
	s_nop 0
	global_load_lds_dwordx4 v[140:141], off
	s_waitcnt vmcnt(8)
	s_waitcnt lgkmcnt(0)
	s_barrier
	s_setprio 1
	s_waitcnt lgkmcnt(0)
	v_mfma_f32_16x16x32_bf16 v[4:7], v[28:31], v[224:227], v[4:7]
	v_mfma_f32_16x16x32_bf16 v[8:11], v[116:119], v[224:227], v[8:11]
	v_mfma_f32_16x16x32_bf16 v[162:165], v[28:31], v[200:203], v[164:167]
	v_mfma_f32_16x16x32_bf16 v[166:169], v[116:119], v[200:203], v[168:171]
	v_mfma_f32_16x16x32_bf16 v[170:173], v[28:31], v[208:211], v[172:175]
	v_mfma_f32_16x16x32_bf16 v[174:177], v[116:119], v[208:211], v[176:179]
	v_mfma_f32_16x16x32_bf16 v[178:181], v[28:31], v[216:219], v[180:183]
	v_mfma_f32_16x16x32_bf16 v[182:185], v[116:119], v[216:219], v[184:187]
	v_mfma_f32_16x16x32_bf16 v[4:7], v[32:35], v[228:231], v[4:7]
	v_mfma_f32_16x16x32_bf16 v[8:11], v[120:123], v[228:231], v[8:11]
	v_mfma_f32_16x16x32_bf16 v[162:165], v[32:35], v[204:207], v[162:165]
	v_mfma_f32_16x16x32_bf16 v[166:169], v[120:123], v[204:207], v[166:169]
	v_mfma_f32_16x16x32_bf16 v[170:173], v[32:35], v[212:215], v[170:173]
	v_mfma_f32_16x16x32_bf16 v[174:177], v[120:123], v[212:215], v[174:177]
	v_mfma_f32_16x16x32_bf16 v[178:181], v[32:35], v[220:223], v[178:181]
	v_mfma_f32_16x16x32_bf16 v[182:185], v[120:123], v[220:223], v[182:185]
	v_mfma_f32_16x16x32_bf16 v[12:15], v[124:127], v[200:203], v[12:15]
	v_mfma_f32_16x16x32_bf16 v[16:19], v[192:195], v[200:203], v[16:19]
	v_mfma_f32_16x16x32_bf16 v[28:31], v[124:127], v[208:211], v[60:63]
	v_mfma_f32_16x16x32_bf16 v[32:35], v[192:195], v[208:211], v[104:107]
	v_mfma_f32_16x16x32_bf16 v[60:63], v[124:127], v[216:219], v[108:111]
	v_mfma_f32_16x16x32_bf16 v[104:107], v[192:195], v[216:219], v[112:115]
	v_mfma_f32_16x16x32_bf16 v[20:23], v[124:127], v[224:227], v[20:23]
	v_mfma_f32_16x16x32_bf16 v[24:27], v[192:195], v[224:227], v[24:27]
	v_mfma_f32_16x16x32_bf16 v[12:15], v[188:191], v[204:207], v[12:15]
	v_mfma_f32_16x16x32_bf16 v[16:19], v[196:199], v[204:207], v[16:19]
	v_mfma_f32_16x16x32_bf16 v[28:31], v[188:191], v[212:215], v[28:31]
	v_mfma_f32_16x16x32_bf16 v[32:35], v[196:199], v[212:215], v[32:35]
	v_mfma_f32_16x16x32_bf16 v[60:63], v[188:191], v[220:223], v[60:63]
	v_mfma_f32_16x16x32_bf16 v[104:107], v[196:199], v[220:223], v[104:107]
	v_mfma_f32_16x16x32_bf16 v[20:23], v[188:191], v[228:231], v[20:23]
	v_mfma_f32_16x16x32_bf16 v[24:27], v[196:199], v[228:231], v[24:27]
	s_setprio 0
	s_barrier
	s_add_u32 s34, s54, 0x180
	s_addc_u32 s35, s55, 0
	s_mov_b64 s[54:55], s[50:51]
	ds_read_b128 v[108:111], v157
	ds_read_b128 v[112:115], v157 offset:1024
	ds_read_b128 v[116:119], v157 offset:2048
	ds_read_b128 v[120:123], v157 offset:3072
	ds_read_b128 v[124:127], v158
	ds_read_b128 v[186:189], v158 offset:1024
	ds_read_b128 v[190:193], v158 offset:2048
	ds_read_b128 v[194:197], v158 offset:3072
	s_add_u32 s34, s34, 0x10000
	s_addc_u32 s35, s35, 0
	s_mov_b32 m0, s83
	v_lshl_add_u64 v[140:141], s[34:35], 0, v[134:135]
	ds_read_b128 v[198:201], v137
	ds_read_b128 v[202:205], v137 offset:1024
	ds_read_b128 v[206:209], v137 offset:2048
	ds_read_b128 v[210:213], v137 offset:3072
	ds_read_b128 v[214:217], v137 offset:4096
	ds_read_b128 v[218:221], v137 offset:5120
	ds_read_b128 v[222:225], v137 offset:6144
	ds_read_b128 v[226:229], v137 offset:7168
	global_load_lds_dwordx4 v[140:141], off
	v_lshl_add_u64 v[140:141], s[34:35], 0, v[130:131]
	s_mov_b32 m0, s84
	s_nop 0
	global_load_lds_dwordx4 v[140:141], off
	s_waitcnt vmcnt(8)
	s_waitcnt lgkmcnt(0)
	s_barrier
; #define PG8_STAGE(bufoff, gbase, voff) do { _Pragma("unroll") for (int _i = 0; _i < 2; ++_i) \
;         __builtin_amdgcn_global_load_lds((const unsigned*)((const char*)(gbase) + (voff)[_i]), (LAS unsigned*)(lds + (bufoff) + ldsw + _i * 8192), 16, 0, 0); } while (0)
; #define PG8_LDA(dst, b, h) do { _Pragma("unroll") for (int m = 0; m < 4; ++m) _Pragma("unroll") for (int k = 0; k < 2; ++k) dst[m][k] = *(const LAS bf16x8*)(lds + PG8_SA(b, h) + aoff + m * 2048 + k * 1024); } while (0)
; #define PG8_MMA(ai, bj, At, Bt) do { __builtin_amdgcn_s_setprio(1); _Pragma("unroll") for (int m = 0; m < 4; ++m) _Pragma("unroll") for (int n = 0; n < 2; ++n) _Pragma("unroll") for (int k = 0; k < 2; ++k) \
;         acc[ai][bj][m][n] = __builtin_amdgcn_mfma_f32_16x16x32_bf16(Bt[n][k], At[m][k], acc[ai][bj][m][n], 0, 0, 0); __builtin_amdgcn_s_setprio(0); } while (0)
; #define PG8_WAIT_V(n) asm volatile("s_waitcnt vmcnt(" #n ")" ::: "memory")
; #define PG8_WAIT_L(n) asm volatile("s_waitcnt lgkmcnt(" #n ")" ::: "memory")
; #define PG8_BAR __builtin_amdgcn_s_barrier()
; #define PG8_SCHED __builtin_amdgcn_sched_barrier(0)
; template <class Epi, class Sched, bool ALIGN_EPI = false, bool SP2 = false, bool TWOA = false, bool AGM = false>
; __device__ __forceinline__ void gemm_phase(LAS unsigned char* lds, const Gemm g, const Sched& S, const Epi& E, int wid) {
;     ...
;             PG8_WAIT_V(8); PG8_WAIT_L(0); PG8_BAR; PG8_MMA(0, 0, At, B0); PG8_MMA(0, 1, At, B1); PG8_BAR; PG8_SCHED;
;             PG8_LDA(At, 0, 1); PG8_STAGE(PG8_SB(0, 0), b2, voffB); PG8_STAGE(PG8_SB(0, 1), b2 + hstep, voffB); PG8_STAGE(PG8_SA(0, 0), a2, voffA);
;             PG8_WAIT_V(8); PG8_WAIT_L(0); PG8_BAR; PG8_MMA(1, 0, At, B0); PG8_MMA(1, 1, At, B1); PG8_BAR; PG8_SCHED;
	s_setprio 1
	s_waitcnt lgkmcnt(0)
	v_mfma_f32_16x16x32_bf16 v[64:67], v[108:111], v[198:201], v[64:67]
	v_mfma_f32_16x16x32_bf16 v[68:71], v[116:119], v[198:201], v[68:71]
	v_mfma_f32_16x16x32_bf16 v[72:75], v[108:111], v[206:209], v[72:75]
	v_mfma_f32_16x16x32_bf16 v[76:79], v[116:119], v[206:209], v[76:79]
	v_mfma_f32_16x16x32_bf16 v[80:83], v[108:111], v[214:217], v[80:83]
	v_mfma_f32_16x16x32_bf16 v[84:87], v[116:119], v[214:217], v[84:87]
	v_mfma_f32_16x16x32_bf16 v[88:91], v[108:111], v[222:225], v[88:91]
	v_mfma_f32_16x16x32_bf16 v[64:67], v[112:115], v[202:205], v[64:67]
	v_mfma_f32_16x16x32_bf16 v[68:71], v[120:123], v[202:205], v[68:71]
	v_mfma_f32_16x16x32_bf16 v[72:75], v[112:115], v[210:213], v[72:75]
	v_mfma_f32_16x16x32_bf16 v[76:79], v[120:123], v[210:213], v[76:79]
	v_mfma_f32_16x16x32_bf16 v[80:83], v[112:115], v[218:221], v[80:83]
	v_mfma_f32_16x16x32_bf16 v[84:87], v[120:123], v[218:221], v[84:87]
	v_mfma_f32_16x16x32_bf16 v[230:233], v[112:115], v[226:229], v[88:91]
	v_mfma_f32_16x16x32_bf16 v[88:91], v[116:119], v[222:225], v[92:95]
	v_mfma_f32_16x16x32_bf16 v[234:237], v[120:123], v[226:229], v[88:91]
	v_mfma_f32_16x16x32_bf16 v[88:91], v[124:127], v[198:201], v[96:99]
	v_mfma_f32_16x16x32_bf16 v[96:99], v[186:189], v[202:205], v[88:91]
	v_mfma_f32_16x16x32_bf16 v[36:39], v[190:193], v[198:201], v[36:39]
	v_mfma_f32_16x16x32_bf16 v[88:91], v[124:127], v[206:209], v[100:103]
	v_mfma_f32_16x16x32_bf16 v[40:43], v[190:193], v[206:209], v[40:43]
	v_mfma_f32_16x16x32_bf16 v[44:47], v[124:127], v[214:217], v[44:47]
	v_mfma_f32_16x16x32_bf16 v[48:51], v[190:193], v[214:217], v[48:51]
	v_mfma_f32_16x16x32_bf16 v[52:55], v[124:127], v[222:225], v[52:55]
	v_mfma_f32_16x16x32_bf16 v[56:59], v[190:193], v[222:225], v[56:59]
	v_mfma_f32_16x16x32_bf16 v[36:39], v[194:197], v[202:205], v[36:39]
	v_mfma_f32_16x16x32_bf16 v[100:103], v[186:189], v[210:213], v[88:91]
	v_mfma_f32_16x16x32_bf16 v[40:43], v[194:197], v[210:213], v[40:43]
	v_mfma_f32_16x16x32_bf16 v[44:47], v[186:189], v[218:221], v[44:47]
	v_mfma_f32_16x16x32_bf16 v[48:51], v[194:197], v[218:221], v[48:51]
	v_mfma_f32_16x16x32_bf16 v[52:55], v[186:189], v[226:229], v[52:55]
	v_mfma_f32_16x16x32_bf16 v[56:59], v[194:197], v[226:229], v[56:59]
	s_setprio 0
	s_barrier
	s_mov_b32 m0, s85
	v_lshl_add_u64 v[140:141], v[0:1], 0, s[26:27]
	s_add_u32 s34, s52, 0x20200
	ds_read_b128 v[88:91], v137 offset:16384
	ds_read_b128 v[92:95], v137 offset:17408
	ds_read_b128 v[198:201], v137 offset:18432
	ds_read_b128 v[202:205], v137 offset:19456
	ds_read_b128 v[206:209], v137 offset:20480
	ds_read_b128 v[210:213], v137 offset:21504
	ds_read_b128 v[214:217], v137 offset:22528
	ds_read_b128 v[218:221], v137 offset:23552
	global_load_lds_dwordx4 v[140:141], off
	v_lshl_add_u64 v[140:141], v[2:3], 0, s[26:27]
	s_mov_b32 m0, s86
	s_addc_u32 s35, s53, 0
	global_load_lds_dwordx4 v[140:141], off
	v_lshl_add_u64 v[140:141], s[34:35], 0, v[132:133]
	s_mov_b32 m0, s87
	v_lshl_add_u64 v[148:149], s[54:55], 0, v[134:135]
	global_load_lds_dwordx4 v[140:141], off
	v_lshl_add_u64 v[140:141], s[34:35], 0, v[128:129]
	s_mov_b32 m0, s88
	v_lshl_add_u64 v[150:151], s[54:55], 0, v[130:131]
	global_load_lds_dwordx4 v[140:141], off
	s_mov_b32 m0, s45
	s_nop 0
	global_load_lds_dwordx4 v[148:149], off
	s_mov_b32 m0, s47
	s_nop 0
	global_load_lds_dwordx4 v[150:151], off
	s_waitcnt vmcnt(8)
	s_waitcnt lgkmcnt(0)
	s_barrier
	s_setprio 1
	s_waitcnt lgkmcnt(0)
	v_mfma_f32_16x16x32_bf16 v[4:7], v[108:111], v[214:217], v[4:7]
	v_mfma_f32_16x16x32_bf16 v[8:11], v[116:119], v[214:217], v[8:11]
	v_mfma_f32_16x16x32_bf16 v[162:165], v[108:111], v[88:91], v[162:165]
	v_mfma_f32_16x16x32_bf16 v[166:169], v[116:119], v[88:91], v[166:169]
	v_mfma_f32_16x16x32_bf16 v[170:173], v[108:111], v[198:201], v[170:173]
	v_mfma_f32_16x16x32_bf16 v[174:177], v[116:119], v[198:201], v[174:177]
	v_mfma_f32_16x16x32_bf16 v[178:181], v[108:111], v[206:209], v[178:181]
	v_mfma_f32_16x16x32_bf16 v[182:185], v[116:119], v[206:209], v[182:185]
	v_mfma_f32_16x16x32_bf16 v[4:7], v[112:115], v[218:221], v[4:7]
	v_mfma_f32_16x16x32_bf16 v[8:11], v[120:123], v[218:221], v[8:11]
	v_mfma_f32_16x16x32_bf16 v[162:165], v[112:115], v[92:95], v[162:165]
	v_mfma_f32_16x16x32_bf16 v[166:169], v[120:123], v[92:95], v[166:169]
	v_mfma_f32_16x16x32_bf16 v[170:173], v[112:115], v[202:205], v[170:173]
	v_mfma_f32_16x16x32_bf16 v[174:177], v[120:123], v[202:205], v[174:177]
	v_mfma_f32_16x16x32_bf16 v[178:181], v[112:115], v[210:213], v[178:181]
	v_mfma_f32_16x16x32_bf16 v[182:185], v[120:123], v[210:213], v[182:185]
	v_mfma_f32_16x16x32_bf16 v[12:15], v[124:127], v[88:91], v[12:15]
	v_mfma_f32_16x16x32_bf16 v[222:225], v[186:189], v[92:95], v[12:15]
	v_mfma_f32_16x16x32_bf16 v[12:15], v[190:193], v[88:91], v[16:19]
	v_mfma_f32_16x16x32_bf16 v[16:19], v[194:197], v[92:95], v[12:15]
	v_mfma_f32_16x16x32_bf16 v[12:15], v[124:127], v[198:201], v[28:31]
	v_mfma_f32_16x16x32_bf16 v[226:229], v[186:189], v[202:205], v[12:15]
	v_mfma_f32_16x16x32_bf16 v[12:15], v[190:193], v[198:201], v[32:35]
	v_mfma_f32_16x16x32_bf16 v[32:35], v[194:197], v[202:205], v[12:15]
	v_mfma_f32_16x16x32_bf16 v[12:15], v[124:127], v[206:209], v[60:63]
	v_mfma_f32_16x16x32_bf16 v[198:201], v[186:189], v[210:213], v[12:15]
	v_mfma_f32_16x16x32_bf16 v[12:15], v[190:193], v[206:209], v[104:107]
	v_mfma_f32_16x16x32_bf16 v[202:205], v[194:197], v[210:213], v[12:15]
	v_mfma_f32_16x16x32_bf16 v[12:15], v[124:127], v[214:217], v[20:23]
	v_mfma_f32_16x16x32_bf16 v[186:189], v[186:189], v[218:221], v[12:15]
	v_mfma_f32_16x16x32_bf16 v[12:15], v[190:193], v[214:217], v[24:27]
	v_mfma_f32_16x16x32_bf16 v[190:193], v[194:197], v[218:221], v[12:15]
	s_setprio 0
	s_barrier
; #define PG8_STAGE(bufoff, gbase, voff) do { _Pragma("unroll") for (int _i = 0; _i < 2; ++_i) \
;         __builtin_amdgcn_global_load_lds((const unsigned*)((const char*)(gbase) + (voff)[_i]), (LAS unsigned*)(lds + (bufoff) + ldsw + _i * 8192), 16, 0, 0); } while (0)
; #define PG8_LDA(dst, b, h) do { _Pragma("unroll") for (int m = 0; m < 4; ++m) _Pragma("unroll") for (int k = 0; k < 2; ++k) dst[m][k] = *(const LAS bf16x8*)(lds + PG8_SA(b, h) + aoff + m * 2048 + k * 1024); } while (0)
; #define PG8_LDB(dst, b, h) do { _Pragma("unroll") for (int n = 0; n < 2; ++n) _Pragma("unroll") for (int k = 0; k < 2; ++k) dst[n][k] = *(const LAS bf16x8*)(lds + PG8_SB(b, h) + boff + n * 2048 + k * 1024); } while (0)
; #define PG8_MMA(ai, bj, At, Bt) do { __builtin_amdgcn_s_setprio(1); _Pragma("unroll") for (int m = 0; m < 4; ++m) _Pragma("unroll") for (int n = 0; n < 2; ++n) _Pragma("unroll") for (int k = 0; k < 2; ++k) \
;         acc[ai][bj][m][n] = __builtin_amdgcn_mfma_f32_16x16x32_bf16(Bt[n][k], At[m][k], acc[ai][bj][m][n], 0, 0, 0); __builtin_amdgcn_s_setprio(0); } while (0)
; #define PG8_WAIT_V(n) asm volatile("s_waitcnt vmcnt(" #n ")" ::: "memory")
; #define PG8_WAIT_L(n) asm volatile("s_waitcnt lgkmcnt(" #n ")" ::: "memory")
; #define PG8_BAR __builtin_amdgcn_s_barrier()
; #define PG8_SCHED __builtin_amdgcn_sched_barrier(0)
; template <class Epi, class Sched, bool ALIGN_EPI = false, bool SP2 = false, bool TWOA = false, bool AGM = false>
; __device__ __forceinline__ void gemm_phase(LAS unsigned char* lds, const Gemm g, const Sched& S, const Epi& E, int wid) {
;     ...
;             PG8_LDB(B0, 1, 0); PG8_LDB(B1, 1, 1); PG8_SCHED; PG8_LDA(At, 1, 0); PG8_STAGE(PG8_SA(0, 1), a2 + hstepA, voffA);
;             PG8_WAIT_V(8); PG8_WAIT_L(0); PG8_BAR; PG8_MMA(0, 0, At, B0); PG8_MMA(0, 1, At, B1); PG8_BAR; PG8_SCHED;
;             PG8_LDA(At, 1, 1); PG8_STAGE(PG8_SB(1, 0), b3, voffB); PG8_STAGE(PG8_SB(1, 1), b3 + hstep, voffB); PG8_STAGE(PG8_SA(1, 0), a3, voffA);
;             PG8_WAIT_V(8); PG8_WAIT_L(0); PG8_BAR; PG8_MMA(1, 0, At, B0); PG8_MMA(1, 1, At, B1); PG8_BAR; PG8_SCHED;
	s_nop 4
	ds_read_b128 v[12:15], v159
	ds_read_b128 v[20:23], v159 offset:1024
	ds_read_b128 v[194:197], v159 offset:2048
	ds_read_b128 v[206:209], v159 offset:3072
	ds_read_b128 v[210:213], v160
	ds_read_b128 v[214:217], v160 offset:1024
	ds_read_b128 v[218:221], v160 offset:2048
	ds_read_b128 v[238:241], v160 offset:3072
	s_add_u32 s34, s54, 0x10000
	s_addc_u32 s35, s55, 0
	s_mov_b32 m0, s70
	v_lshl_add_u64 v[88:89], s[34:35], 0, v[134:135]
	ds_read_b128 v[24:27], v137 offset:32768
	ds_read_b128 v[28:31], v137 offset:33792
	ds_read_b128 v[60:63], v137 offset:34816
	ds_read_b128 v[242:245], v137 offset:35840
	ds_read_b128 v[246:249], v137 offset:36864
	ds_read_b128 v[250:253], v137 offset:37888
	ds_read_b128 v[140:143], v137 offset:38912
	ds_read_b128 v[144:147], v137 offset:39936
	global_load_lds_dwordx4 v[88:89], off
	v_lshl_add_u64 v[88:89], s[34:35], 0, v[130:131]
	s_mov_b32 m0, s71
	s_nop 0
	global_load_lds_dwordx4 v[88:89], off
	s_waitcnt vmcnt(8)
	s_waitcnt lgkmcnt(0)
	s_barrier
	s_setprio 1
	s_waitcnt lgkmcnt(0)
	v_mfma_f32_16x16x32_bf16 v[64:67], v[12:15], v[24:27], v[64:67]
	v_mfma_f32_16x16x32_bf16 v[124:127], v[20:23], v[28:31], v[64:67]
	v_mfma_f32_16x16x32_bf16 v[64:67], v[194:197], v[24:27], v[68:71]
	v_mfma_f32_16x16x32_bf16 v[120:123], v[206:209], v[28:31], v[64:67]
	v_mfma_f32_16x16x32_bf16 v[64:67], v[12:15], v[60:63], v[72:75]
	v_mfma_f32_16x16x32_bf16 v[108:111], v[20:23], v[242:245], v[64:67]
	v_mfma_f32_16x16x32_bf16 v[64:67], v[194:197], v[60:63], v[76:79]
	v_mfma_f32_16x16x32_bf16 v[104:107], v[206:209], v[242:245], v[64:67]
	v_mfma_f32_16x16x32_bf16 v[64:67], v[12:15], v[246:249], v[80:83]
	v_mfma_f32_16x16x32_bf16 v[92:95], v[20:23], v[250:253], v[64:67]
	v_mfma_f32_16x16x32_bf16 v[64:67], v[194:197], v[246:249], v[84:87]
	v_mfma_f32_16x16x32_bf16 v[88:91], v[206:209], v[250:253], v[64:67]
	v_mfma_f32_16x16x32_bf16 v[64:67], v[12:15], v[140:143], v[230:233]
	v_mfma_f32_16x16x32_bf16 v[76:79], v[20:23], v[144:147], v[64:67]
	v_mfma_f32_16x16x32_bf16 v[64:67], v[194:197], v[140:143], v[234:237]
	v_mfma_f32_16x16x32_bf16 v[72:75], v[206:209], v[144:147], v[64:67]
	v_mfma_f32_16x16x32_bf16 v[64:67], v[210:213], v[24:27], v[96:99]
	v_mfma_f32_16x16x32_bf16 v[24:27], v[218:221], v[24:27], v[36:39]
	v_mfma_f32_16x16x32_bf16 v[112:115], v[238:241], v[28:31], v[24:27]
	v_mfma_f32_16x16x32_bf16 v[24:27], v[210:213], v[60:63], v[100:103]
	v_mfma_f32_16x16x32_bf16 v[100:103], v[214:217], v[242:245], v[24:27]
	v_mfma_f32_16x16x32_bf16 v[24:27], v[218:221], v[60:63], v[40:43]
	v_mfma_f32_16x16x32_bf16 v[96:99], v[238:241], v[242:245], v[24:27]
	v_mfma_f32_16x16x32_bf16 v[24:27], v[210:213], v[246:249], v[44:47]
	v_mfma_f32_16x16x32_bf16 v[84:87], v[214:217], v[250:253], v[24:27]
	v_mfma_f32_16x16x32_bf16 v[24:27], v[218:221], v[246:249], v[48:51]
	v_mfma_f32_16x16x32_bf16 v[80:83], v[238:241], v[250:253], v[24:27]
	v_mfma_f32_16x16x32_bf16 v[24:27], v[210:213], v[140:143], v[52:55]
	v_mfma_f32_16x16x32_bf16 v[68:71], v[214:217], v[144:147], v[24:27]
	v_mfma_f32_16x16x32_bf16 v[24:27], v[218:221], v[140:143], v[56:59]
	v_mfma_f32_16x16x32_bf16 v[116:119], v[214:217], v[28:31], v[64:67]
	v_mfma_f32_16x16x32_bf16 v[64:67], v[238:241], v[144:147], v[24:27]
	s_setprio 0
	s_barrier
	s_mov_b32 m0, s56
	v_lshl_add_u64 v[0:1], v[0:1], 0, s[28:29]
	s_add_u32 s34, s52, 0x20280
	ds_read_b128 v[36:39], v137 offset:49152
	ds_read_b128 v[48:51], v137 offset:50176
	ds_read_b128 v[140:143], v137 offset:51200
	ds_read_b128 v[144:147], v137 offset:52224
	ds_read_b128 v[230:233], v137 offset:53248
	ds_read_b128 v[234:237], v137 offset:54272
	ds_read_b128 v[242:245], v137 offset:55296
	ds_read_b128 v[246:249], v137 offset:56320
	global_load_lds_dwordx4 v[0:1], off
	v_lshl_add_u64 v[0:1], v[2:3], 0, s[28:29]
	s_mov_b32 m0, s57
	s_addc_u32 s35, s53, 0
	global_load_lds_dwordx4 v[0:1], off
	v_lshl_add_u64 v[0:1], s[34:35], 0, v[132:133]
	s_mov_b32 m0, s89
	s_nop 0
	global_load_lds_dwordx4 v[0:1], off
	v_lshl_add_u64 v[0:1], s[34:35], 0, v[128:129]
	s_mov_b32 m0, s90
	s_nop 0
	global_load_lds_dwordx4 v[0:1], off
	v_lshl_add_u64 v[0:1], v[148:149], 0, s[12:13]
	s_mov_b32 m0, s74
	s_nop 0
	global_load_lds_dwordx4 v[0:1], off
	v_lshl_add_u64 v[0:1], v[150:151], 0, s[12:13]
	s_mov_b32 m0, s75
	s_nop 0
	global_load_lds_dwordx4 v[0:1], off
	s_waitcnt vmcnt(8)
	s_waitcnt lgkmcnt(0)
	s_barrier
	s_setprio 1
	s_waitcnt lgkmcnt(0)
	v_mfma_f32_16x16x32_bf16 v[0:3], v[12:15], v[36:39], v[162:165]
	v_mfma_f32_16x16x32_bf16 v[60:63], v[20:23], v[48:51], v[0:3]
	v_mfma_f32_16x16x32_bf16 v[0:3], v[194:197], v[36:39], v[166:169]
	v_mfma_f32_16x16x32_bf16 v[56:59], v[206:209], v[48:51], v[0:3]
	v_mfma_f32_16x16x32_bf16 v[0:3], v[12:15], v[140:143], v[170:173]
	v_mfma_f32_16x16x32_bf16 v[44:47], v[20:23], v[144:147], v[0:3]
	v_mfma_f32_16x16x32_bf16 v[0:3], v[194:197], v[140:143], v[174:177]
	v_mfma_f32_16x16x32_bf16 v[40:43], v[206:209], v[144:147], v[0:3]
	v_mfma_f32_16x16x32_bf16 v[0:3], v[12:15], v[230:233], v[178:181]
	v_mfma_f32_16x16x32_bf16 v[28:31], v[20:23], v[234:237], v[0:3]
	v_mfma_f32_16x16x32_bf16 v[0:3], v[194:197], v[230:233], v[182:185]
	v_mfma_f32_16x16x32_bf16 v[24:27], v[206:209], v[234:237], v[0:3]
	v_mfma_f32_16x16x32_bf16 v[0:3], v[12:15], v[242:245], v[4:7]
	v_mfma_f32_16x16x32_bf16 v[12:15], v[20:23], v[246:249], v[0:3]
	v_mfma_f32_16x16x32_bf16 v[0:3], v[194:197], v[242:245], v[8:11]
	v_mfma_f32_16x16x32_bf16 v[8:11], v[206:209], v[246:249], v[0:3]
	v_mfma_f32_16x16x32_bf16 v[0:3], v[210:213], v[36:39], v[222:225]
	v_mfma_f32_16x16x32_bf16 v[52:55], v[214:217], v[48:51], v[0:3]
	v_mfma_f32_16x16x32_bf16 v[0:3], v[218:221], v[36:39], v[16:19]
	v_mfma_f32_16x16x32_bf16 v[48:51], v[238:241], v[48:51], v[0:3]
	v_mfma_f32_16x16x32_bf16 v[0:3], v[210:213], v[140:143], v[226:229]
	v_mfma_f32_16x16x32_bf16 v[36:39], v[214:217], v[144:147], v[0:3]
	v_mfma_f32_16x16x32_bf16 v[0:3], v[218:221], v[140:143], v[32:35]
	v_mfma_f32_16x16x32_bf16 v[32:35], v[238:241], v[144:147], v[0:3]
	v_mfma_f32_16x16x32_bf16 v[0:3], v[210:213], v[230:233], v[198:201]
	v_mfma_f32_16x16x32_bf16 v[20:23], v[214:217], v[234:237], v[0:3]
	v_mfma_f32_16x16x32_bf16 v[0:3], v[218:221], v[230:233], v[202:205]
	v_mfma_f32_16x16x32_bf16 v[16:19], v[238:241], v[234:237], v[0:3]
	v_mfma_f32_16x16x32_bf16 v[0:3], v[210:213], v[242:245], v[186:189]
	v_mfma_f32_16x16x32_bf16 v[4:7], v[214:217], v[246:249], v[0:3]
	v_mfma_f32_16x16x32_bf16 v[0:3], v[218:221], v[242:245], v[190:193]
	v_mfma_f32_16x16x32_bf16 v[0:3], v[238:241], v[246:249], v[0:3]
	s_setprio 0
	s_barrier
	s_add_u32 s91, s52, 0x300
	s_addc_u32 s92, s53, 0
	s_mov_b32 s93, 2
; #define PG8_STAGE(bufoff, gbase, voff) do { _Pragma("unroll") for (int _i = 0; _i < 2; ++_i) \
;         __builtin_amdgcn_global_load_lds((const unsigned*)((const char*)(gbase) + (voff)[_i]), (LAS unsigned*)(lds + (bufoff) + ldsw + _i * 8192), 16, 0, 0); } while (0)
; #define PG8_LDA(dst, b, h) do { _Pragma("unroll") for (int m = 0; m < 4; ++m) _Pragma("unroll") for (int k = 0; k < 2; ++k) dst[m][k] = *(const LAS bf16x8*)(lds + PG8_SA(b, h) + aoff + m * 2048 + k * 1024); } while (0)
; #define PG8_LDB(dst, b, h) do { _Pragma("unroll") for (int n = 0; n < 2; ++n) _Pragma("unroll") for (int k = 0; k < 2; ++k) dst[n][k] = *(const LAS bf16x8*)(lds + PG8_SB(b, h) + boff + n * 2048 + k * 1024); } while (0)
; #define PG8_MMA(ai, bj, At, Bt) do { __builtin_amdgcn_s_setprio(1); _Pragma("unroll") for (int m = 0; m < 4; ++m) _Pragma("unroll") for (int n = 0; n < 2; ++n) _Pragma("unroll") for (int k = 0; k < 2; ++k) \
;         acc[ai][bj][m][n] = __builtin_amdgcn_mfma_f32_16x16x32_bf16(Bt[n][k], At[m][k], acc[ai][bj][m][n], 0, 0, 0); __builtin_amdgcn_s_setprio(0); } while (0)
; template <class Epi, class Sched, bool ALIGN_EPI = false, bool SP2 = false, bool TWOA = false, bool AGM = false>
; __device__ __forceinline__ void gemm_phase(LAS unsigned char* lds, const Gemm g, const Sched& S, const Epi& E, int wid) {
;     ...
;             const char* a1_ = (TWOA && t + 1 >= nh ? cA2 : cA) + (size_t)(t + 1) * kstepA;
;             const char* a2_ = last ? nA : (TWOA && t + 2 >= nh ? cA2 : cA) + (size_t)(t + 2) * kstepA; const char* a1 = a1_; const char* a2 = a2_; const char* b2 = last ? nB : cB + (size_t)(t + 2) * kstep;
;             if constexpr (TWOA) { asm volatile("" : "+s"(a1)); asm volatile("" : "+s"(a2)); }
;             const char* a3 = a2 + kstepA; const char* b3 = b2 + kstep;
;             if (last && has_next) S.a_ready(nxt);
;             if constexpr (has_mid<Epi>::value) { if (t == nh) E.mid(acc, cur, wr, wc, fr, fq); }
;             if constexpr (SP2) {
;             PG8_LDB(B0, 0, 0); PG8_LDB(B1, 0, 1); PG8_SCHED; PG8_LDA(At, 0, 0); PG8_STAGE(PG8_SA(1, 1), a1 + hstepA, voffA);
;             PG8_WAIT_V(8); PG8_WAIT_L(0); PG8_BAR; PG8_MMA(0, 0, At, B0); PG8_MMA(0, 1, At, B1); PG8_BAR; PG8_SCHED;
;             PG8_LDA(At, 0, 1); PG8_STAGE(PG8_SB(0, 0), b2, voffB); PG8_STAGE(PG8_SB(0, 1), b2 + hstep, voffB); PG8_STAGE(PG8_SA(0, 0), a2, voffA);
.LBB0_683:
	s_add_u32 s34, s50, 0x80
	s_addc_u32 s35, s51, 0
	s_add_u32 s50, s50, 0x100
	s_addc_u32 s51, s51, 0
	s_cmp_eq_u32 s93, 4
	s_cselect_b32 s55, s37, s51
	s_cselect_b32 s54, s80, s50
	ds_read_b128 v[140:143], v157
	ds_read_b128 v[144:147], v157 offset:1024
	ds_read_b128 v[162:165], v157 offset:2048
	ds_read_b128 v[166:169], v157 offset:3072
	ds_read_b128 v[170:173], v158
	ds_read_b128 v[174:177], v158 offset:1024
	ds_read_b128 v[178:181], v158 offset:2048
	ds_read_b128 v[182:185], v158 offset:3072
	s_cselect_b32 s53, s31, s92
	s_cselect_b32 s52, s82, s91
	s_add_u32 s34, s34, 0x10000
	s_addc_u32 s35, s35, 0
	s_mov_b32 m0, s83
	v_lshl_add_u64 v[148:149], s[34:35], 0, v[134:135]
	ds_read_b128 v[186:189], v137
	ds_read_b128 v[190:193], v137 offset:1024
	ds_read_b128 v[194:197], v137 offset:2048
	ds_read_b128 v[198:201], v137 offset:3072
	ds_read_b128 v[202:205], v137 offset:4096
	ds_read_b128 v[206:209], v137 offset:5120
	ds_read_b128 v[210:213], v137 offset:6144
	ds_read_b128 v[214:217], v137 offset:7168
	global_load_lds_dwordx4 v[148:149], off
	v_lshl_add_u64 v[148:149], s[34:35], 0, v[130:131]
	s_mov_b32 m0, s84
	s_nop 0
	global_load_lds_dwordx4 v[148:149], off
	s_waitcnt vmcnt(8)
	s_waitcnt lgkmcnt(0)
	s_barrier
	s_setprio 1
	s_waitcnt lgkmcnt(0)
	v_mfma_f32_16x16x32_bf16 v[124:127], v[140:143], v[186:189], v[124:127]
	v_mfma_f32_16x16x32_bf16 v[120:123], v[162:165], v[186:189], v[120:123]
	v_mfma_f32_16x16x32_bf16 v[108:111], v[140:143], v[194:197], v[108:111]
	v_mfma_f32_16x16x32_bf16 v[104:107], v[162:165], v[194:197], v[104:107]
	v_mfma_f32_16x16x32_bf16 v[92:95], v[140:143], v[202:205], v[92:95]
	v_mfma_f32_16x16x32_bf16 v[88:91], v[162:165], v[202:205], v[88:91]
	v_mfma_f32_16x16x32_bf16 v[76:79], v[140:143], v[210:213], v[76:79]
	v_mfma_f32_16x16x32_bf16 v[72:75], v[162:165], v[210:213], v[72:75]
	v_mfma_f32_16x16x32_bf16 v[124:127], v[144:147], v[190:193], v[124:127]
	v_mfma_f32_16x16x32_bf16 v[120:123], v[166:169], v[190:193], v[120:123]
	v_mfma_f32_16x16x32_bf16 v[108:111], v[144:147], v[198:201], v[108:111]
	v_mfma_f32_16x16x32_bf16 v[104:107], v[166:169], v[198:201], v[104:107]
	v_mfma_f32_16x16x32_bf16 v[92:95], v[144:147], v[206:209], v[92:95]
	v_mfma_f32_16x16x32_bf16 v[88:91], v[166:169], v[206:209], v[88:91]
	v_mfma_f32_16x16x32_bf16 v[76:79], v[144:147], v[214:217], v[76:79]
	v_mfma_f32_16x16x32_bf16 v[72:75], v[166:169], v[214:217], v[72:75]
	v_mfma_f32_16x16x32_bf16 v[116:119], v[170:173], v[186:189], v[116:119]
	v_mfma_f32_16x16x32_bf16 v[112:115], v[178:181], v[186:189], v[112:115]
	v_mfma_f32_16x16x32_bf16 v[100:103], v[170:173], v[194:197], v[100:103]
	v_mfma_f32_16x16x32_bf16 v[96:99], v[178:181], v[194:197], v[96:99]
	v_mfma_f32_16x16x32_bf16 v[84:87], v[170:173], v[202:205], v[84:87]
	v_mfma_f32_16x16x32_bf16 v[80:83], v[178:181], v[202:205], v[80:83]
	v_mfma_f32_16x16x32_bf16 v[68:71], v[170:173], v[210:213], v[68:71]
	v_mfma_f32_16x16x32_bf16 v[64:67], v[178:181], v[210:213], v[64:67]
	v_mfma_f32_16x16x32_bf16 v[116:119], v[174:177], v[190:193], v[116:119]
	v_mfma_f32_16x16x32_bf16 v[112:115], v[182:185], v[190:193], v[112:115]
	v_mfma_f32_16x16x32_bf16 v[100:103], v[174:177], v[198:201], v[100:103]
	v_mfma_f32_16x16x32_bf16 v[96:99], v[182:185], v[198:201], v[96:99]
	v_mfma_f32_16x16x32_bf16 v[84:87], v[174:177], v[206:209], v[84:87]
	v_mfma_f32_16x16x32_bf16 v[80:83], v[182:185], v[206:209], v[80:83]
	v_mfma_f32_16x16x32_bf16 v[68:71], v[174:177], v[214:217], v[68:71]
	v_mfma_f32_16x16x32_bf16 v[64:67], v[182:185], v[214:217], v[64:67]
	s_setprio 0
	s_barrier
	s_mov_b32 m0, s85
	v_lshl_add_u64 v[148:149], s[52:53], 0, v[132:133]
	s_add_u32 s34, s52, 0x20000
	ds_read_b128 v[186:189], v137 offset:16384
	ds_read_b128 v[190:193], v137 offset:17408
	ds_read_b128 v[194:197], v137 offset:18432
	ds_read_b128 v[198:201], v137 offset:19456
	ds_read_b128 v[202:205], v137 offset:20480
	ds_read_b128 v[206:209], v137 offset:21504
	ds_read_b128 v[210:213], v137 offset:22528
	ds_read_b128 v[214:217], v137 offset:23552
	global_load_lds_dwordx4 v[148:149], off
	v_lshl_add_u64 v[150:151], s[52:53], 0, v[128:129]
	s_mov_b32 m0, s86
	s_addc_u32 s35, s53, 0
	global_load_lds_dwordx4 v[150:151], off
	v_lshl_add_u64 v[218:219], s[34:35], 0, v[132:133]
	s_mov_b32 m0, s87
	v_lshl_add_u64 v[220:221], s[54:55], 0, v[130:131]
	global_load_lds_dwordx4 v[218:219], off
	v_lshl_add_u64 v[218:219], s[34:35], 0, v[128:129]
	s_mov_b32 m0, s88
	s_nop 0
	global_load_lds_dwordx4 v[218:219], off
	v_lshl_add_u64 v[218:219], s[54:55], 0, v[134:135]
	s_mov_b32 m0, s45
	s_nop 0
	global_load_lds_dwordx4 v[218:219], off
	s_mov_b32 m0, s47
	s_nop 0
	global_load_lds_dwordx4 v[220:221], off
	s_waitcnt vmcnt(8)
	s_waitcnt lgkmcnt(0)
	s_barrier
; #define PG8_STAGE(bufoff, gbase, voff) do { _Pragma("unroll") for (int _i = 0; _i < 2; ++_i) \
;         __builtin_amdgcn_global_load_lds((const unsigned*)((const char*)(gbase) + (voff)[_i]), (LAS unsigned*)(lds + (bufoff) + ldsw + _i * 8192), 16, 0, 0); } while (0)
; #define PG8_LDA(dst, b, h) do { _Pragma("unroll") for (int m = 0; m < 4; ++m) _Pragma("unroll") for (int k = 0; k < 2; ++k) dst[m][k] = *(const LAS bf16x8*)(lds + PG8_SA(b, h) + aoff + m * 2048 + k * 1024); } while (0)
; #define PG8_LDB(dst, b, h) do { _Pragma("unroll") for (int n = 0; n < 2; ++n) _Pragma("unroll") for (int k = 0; k < 2; ++k) dst[n][k] = *(const LAS bf16x8*)(lds + PG8_SB(b, h) + boff + n * 2048 + k * 1024); } while (0)
; #define PG8_MMA(ai, bj, At, Bt) do { __builtin_amdgcn_s_setprio(1); _Pragma("unroll") for (int m = 0; m < 4; ++m) _Pragma("unroll") for (int n = 0; n < 2; ++n) _Pragma("unroll") for (int k = 0; k < 2; ++k) \
;         acc[ai][bj][m][n] = __builtin_amdgcn_mfma_f32_16x16x32_bf16(Bt[n][k], At[m][k], acc[ai][bj][m][n], 0, 0, 0); __builtin_amdgcn_s_setprio(0); } while (0)
; #define PG8_WAIT_V(n) asm volatile("s_waitcnt vmcnt(" #n ")" ::: "memory")
; #define PG8_WAIT_L(n) asm volatile("s_waitcnt lgkmcnt(" #n ")" ::: "memory")
; #define PG8_BAR __builtin_amdgcn_s_barrier()
; #define PG8_SCHED __builtin_amdgcn_sched_barrier(0)
; template <class Epi, class Sched, bool ALIGN_EPI = false, bool SP2 = false, bool TWOA = false, bool AGM = false>
; __device__ __forceinline__ void gemm_phase(LAS unsigned char* lds, const Gemm g, const Sched& S, const Epi& E, int wid) {
;     ...
;             PG8_WAIT_V(8); PG8_WAIT_L(0); PG8_BAR; PG8_MMA(1, 0, At, B0); PG8_MMA(1, 1, At, B1); PG8_BAR; PG8_SCHED;
;             PG8_LDB(B0, 1, 0); PG8_LDB(B1, 1, 1); PG8_SCHED; PG8_LDA(At, 1, 0); PG8_STAGE(PG8_SA(0, 1), a2 + hstepA, voffA);
;             PG8_WAIT_V(8); PG8_WAIT_L(0); PG8_BAR; PG8_MMA(0, 0, At, B0); PG8_MMA(0, 1, At, B1); PG8_BAR; PG8_SCHED;
	s_setprio 1
	s_waitcnt lgkmcnt(0)
	v_mfma_f32_16x16x32_bf16 v[60:63], v[140:143], v[186:189], v[60:63]
	v_mfma_f32_16x16x32_bf16 v[56:59], v[162:165], v[186:189], v[56:59]
	v_mfma_f32_16x16x32_bf16 v[44:47], v[140:143], v[194:197], v[44:47]
	v_mfma_f32_16x16x32_bf16 v[40:43], v[162:165], v[194:197], v[40:43]
	v_mfma_f32_16x16x32_bf16 v[28:31], v[140:143], v[202:205], v[28:31]
	v_mfma_f32_16x16x32_bf16 v[24:27], v[162:165], v[202:205], v[24:27]
	v_mfma_f32_16x16x32_bf16 v[12:15], v[140:143], v[210:213], v[12:15]
	v_mfma_f32_16x16x32_bf16 v[8:11], v[162:165], v[210:213], v[8:11]
	v_mfma_f32_16x16x32_bf16 v[60:63], v[144:147], v[190:193], v[60:63]
	v_mfma_f32_16x16x32_bf16 v[56:59], v[166:169], v[190:193], v[56:59]
	v_mfma_f32_16x16x32_bf16 v[44:47], v[144:147], v[198:201], v[44:47]
	v_mfma_f32_16x16x32_bf16 v[40:43], v[166:169], v[198:201], v[40:43]
	v_mfma_f32_16x16x32_bf16 v[28:31], v[144:147], v[206:209], v[28:31]
	v_mfma_f32_16x16x32_bf16 v[24:27], v[166:169], v[206:209], v[24:27]
	v_mfma_f32_16x16x32_bf16 v[12:15], v[144:147], v[214:217], v[12:15]
	v_mfma_f32_16x16x32_bf16 v[8:11], v[166:169], v[214:217], v[8:11]
	v_mfma_f32_16x16x32_bf16 v[52:55], v[170:173], v[186:189], v[52:55]
	v_mfma_f32_16x16x32_bf16 v[48:51], v[178:181], v[186:189], v[48:51]
	v_mfma_f32_16x16x32_bf16 v[36:39], v[170:173], v[194:197], v[36:39]
	v_mfma_f32_16x16x32_bf16 v[32:35], v[178:181], v[194:197], v[32:35]
	v_mfma_f32_16x16x32_bf16 v[20:23], v[170:173], v[202:205], v[20:23]
	v_mfma_f32_16x16x32_bf16 v[16:19], v[178:181], v[202:205], v[16:19]
	v_mfma_f32_16x16x32_bf16 v[4:7], v[170:173], v[210:213], v[4:7]
	v_mfma_f32_16x16x32_bf16 v[0:3], v[178:181], v[210:213], v[0:3]
	v_mfma_f32_16x16x32_bf16 v[52:55], v[174:177], v[190:193], v[52:55]
	v_mfma_f32_16x16x32_bf16 v[48:51], v[182:185], v[190:193], v[48:51]
	v_mfma_f32_16x16x32_bf16 v[36:39], v[174:177], v[198:201], v[36:39]
	v_mfma_f32_16x16x32_bf16 v[32:35], v[182:185], v[198:201], v[32:35]
	v_mfma_f32_16x16x32_bf16 v[20:23], v[174:177], v[206:209], v[20:23]
	v_mfma_f32_16x16x32_bf16 v[16:19], v[182:185], v[206:209], v[16:19]
	v_mfma_f32_16x16x32_bf16 v[4:7], v[174:177], v[214:217], v[4:7]
	v_mfma_f32_16x16x32_bf16 v[0:3], v[182:185], v[214:217], v[0:3]
	s_setprio 0
	s_barrier
	ds_read_b128 v[140:143], v159
	ds_read_b128 v[144:147], v159 offset:1024
	ds_read_b128 v[162:165], v159 offset:2048
	ds_read_b128 v[166:169], v159 offset:3072
	ds_read_b128 v[170:173], v160
	ds_read_b128 v[174:177], v160 offset:1024
	ds_read_b128 v[178:181], v160 offset:2048
	ds_read_b128 v[182:185], v160 offset:3072
	s_add_u32 s34, s54, 0x10000
	s_addc_u32 s35, s55, 0
	s_mov_b32 m0, s70
	v_lshl_add_u64 v[222:223], s[34:35], 0, v[134:135]
	ds_read_b128 v[186:189], v137 offset:32768
	ds_read_b128 v[190:193], v137 offset:33792
	ds_read_b128 v[194:197], v137 offset:34816
	ds_read_b128 v[198:201], v137 offset:35840
	ds_read_b128 v[202:205], v137 offset:36864
	ds_read_b128 v[206:209], v137 offset:37888
	ds_read_b128 v[210:213], v137 offset:38912
	ds_read_b128 v[214:217], v137 offset:39936
	global_load_lds_dwordx4 v[222:223], off
	v_lshl_add_u64 v[222:223], s[34:35], 0, v[130:131]
	s_mov_b32 m0, s71
	s_nop 0
	global_load_lds_dwordx4 v[222:223], off
	s_waitcnt vmcnt(8)
	s_waitcnt lgkmcnt(0)
	s_barrier
	s_setprio 1
	s_waitcnt lgkmcnt(0)
	v_mfma_f32_16x16x32_bf16 v[124:127], v[140:143], v[186:189], v[124:127]
	v_mfma_f32_16x16x32_bf16 v[120:123], v[162:165], v[186:189], v[120:123]
	v_mfma_f32_16x16x32_bf16 v[108:111], v[140:143], v[194:197], v[108:111]
	v_mfma_f32_16x16x32_bf16 v[104:107], v[162:165], v[194:197], v[104:107]
	v_mfma_f32_16x16x32_bf16 v[92:95], v[140:143], v[202:205], v[92:95]
	v_mfma_f32_16x16x32_bf16 v[88:91], v[162:165], v[202:205], v[88:91]
	v_mfma_f32_16x16x32_bf16 v[76:79], v[140:143], v[210:213], v[76:79]
	v_mfma_f32_16x16x32_bf16 v[72:75], v[162:165], v[210:213], v[72:75]
	v_mfma_f32_16x16x32_bf16 v[124:127], v[144:147], v[190:193], v[124:127]
	v_mfma_f32_16x16x32_bf16 v[120:123], v[166:169], v[190:193], v[120:123]
	v_mfma_f32_16x16x32_bf16 v[108:111], v[144:147], v[198:201], v[108:111]
	v_mfma_f32_16x16x32_bf16 v[104:107], v[166:169], v[198:201], v[104:107]
	v_mfma_f32_16x16x32_bf16 v[92:95], v[144:147], v[206:209], v[92:95]
	v_mfma_f32_16x16x32_bf16 v[88:91], v[166:169], v[206:209], v[88:91]
	v_mfma_f32_16x16x32_bf16 v[76:79], v[144:147], v[214:217], v[76:79]
	v_mfma_f32_16x16x32_bf16 v[72:75], v[166:169], v[214:217], v[72:75]
	v_mfma_f32_16x16x32_bf16 v[116:119], v[170:173], v[186:189], v[116:119]
	v_mfma_f32_16x16x32_bf16 v[112:115], v[178:181], v[186:189], v[112:115]
	v_mfma_f32_16x16x32_bf16 v[100:103], v[170:173], v[194:197], v[100:103]
	v_mfma_f32_16x16x32_bf16 v[96:99], v[178:181], v[194:197], v[96:99]
	v_mfma_f32_16x16x32_bf16 v[84:87], v[170:173], v[202:205], v[84:87]
	v_mfma_f32_16x16x32_bf16 v[80:83], v[178:181], v[202:205], v[80:83]
	v_mfma_f32_16x16x32_bf16 v[68:71], v[170:173], v[210:213], v[68:71]
	v_mfma_f32_16x16x32_bf16 v[64:67], v[178:181], v[210:213], v[64:67]
	v_mfma_f32_16x16x32_bf16 v[116:119], v[174:177], v[190:193], v[116:119]
	v_mfma_f32_16x16x32_bf16 v[112:115], v[182:185], v[190:193], v[112:115]
	v_mfma_f32_16x16x32_bf16 v[100:103], v[174:177], v[198:201], v[100:103]
	v_mfma_f32_16x16x32_bf16 v[96:99], v[182:185], v[198:201], v[96:99]
	v_mfma_f32_16x16x32_bf16 v[84:87], v[174:177], v[206:209], v[84:87]
	v_mfma_f32_16x16x32_bf16 v[80:83], v[182:185], v[206:209], v[80:83]
	v_mfma_f32_16x16x32_bf16 v[68:71], v[174:177], v[214:217], v[68:71]
	v_mfma_f32_16x16x32_bf16 v[64:67], v[182:185], v[214:217], v[64:67]
	s_setprio 0
	s_barrier
; #define PG8_STAGE(bufoff, gbase, voff) do { _Pragma("unroll") for (int _i = 0; _i < 2; ++_i) \
;         __builtin_amdgcn_global_load_lds((const unsigned*)((const char*)(gbase) + (voff)[_i]), (LAS unsigned*)(lds + (bufoff) + ldsw + _i * 8192), 16, 0, 0); } while (0)
; #define PG8_LDA(dst, b, h) do { _Pragma("unroll") for (int m = 0; m < 4; ++m) _Pragma("unroll") for (int k = 0; k < 2; ++k) dst[m][k] = *(const LAS bf16x8*)(lds + PG8_SA(b, h) + aoff + m * 2048 + k * 1024); } while (0)
; #define PG8_MMA(ai, bj, At, Bt) do { __builtin_amdgcn_s_setprio(1); _Pragma("unroll") for (int m = 0; m < 4; ++m) _Pragma("unroll") for (int n = 0; n < 2; ++n) _Pragma("unroll") for (int k = 0; k < 2; ++k) \
;         acc[ai][bj][m][n] = __builtin_amdgcn_mfma_f32_16x16x32_bf16(Bt[n][k], At[m][k], acc[ai][bj][m][n], 0, 0, 0); __builtin_amdgcn_s_setprio(0); } while (0)
; #define PG8_WAIT_V(n) asm volatile("s_waitcnt vmcnt(" #n ")" ::: "memory")
; #define PG8_WAIT_L(n) asm volatile("s_waitcnt lgkmcnt(" #n ")" ::: "memory")
; #define PG8_BAR __builtin_amdgcn_s_barrier()
; #define PG8_SCHED __builtin_amdgcn_sched_barrier(0)
; template <class Epi, class Sched, bool ALIGN_EPI = false, bool SP2 = false, bool TWOA = false, bool AGM = false>
; __device__ __forceinline__ void gemm_phase(LAS unsigned char* lds, const Gemm g, const Sched& S, const Epi& E, int wid) {
;     ...
;         for (int t = 0; t < nt; t += 2) {
;     ...
;             PG8_LDA(At, 1, 1); PG8_STAGE(PG8_SB(1, 0), b3, voffB); PG8_STAGE(PG8_SB(1, 1), b3 + hstep, voffB); PG8_STAGE(PG8_SA(1, 0), a3, voffA);
;             PG8_WAIT_V(8); PG8_WAIT_L(0); PG8_BAR; PG8_MMA(1, 0, At, B0); PG8_MMA(1, 1, At, B1); PG8_BAR; PG8_SCHED;
;     ...
;         if constexpr (ALIGN_EPI) { if (wr == 0) PG8_BAR; }
	s_mov_b32 m0, s56
	v_lshl_add_u64 v[148:149], v[148:149], 0, s[12:13]
	s_add_u32 s34, s52, 0x20080
	ds_read_b128 v[186:189], v137 offset:49152
	ds_read_b128 v[190:193], v137 offset:50176
	ds_read_b128 v[194:197], v137 offset:51200
	ds_read_b128 v[198:201], v137 offset:52224
	ds_read_b128 v[202:205], v137 offset:53248
	ds_read_b128 v[206:209], v137 offset:54272
	ds_read_b128 v[210:213], v137 offset:55296
	ds_read_b128 v[214:217], v137 offset:56320
	global_load_lds_dwordx4 v[148:149], off
	v_lshl_add_u64 v[148:149], v[150:151], 0, s[12:13]
	s_mov_b32 m0, s57
	s_addc_u32 s35, s53, 0
	global_load_lds_dwordx4 v[148:149], off
	v_lshl_add_u64 v[148:149], s[34:35], 0, v[132:133]
	s_mov_b32 m0, s89
	s_nop 0
	global_load_lds_dwordx4 v[148:149], off
	v_lshl_add_u64 v[148:149], s[34:35], 0, v[128:129]
	s_mov_b32 m0, s90
	s_nop 0
	global_load_lds_dwordx4 v[148:149], off
	v_lshl_add_u64 v[148:149], v[218:219], 0, s[12:13]
	s_mov_b32 m0, s74
	s_nop 0
	global_load_lds_dwordx4 v[148:149], off
	v_lshl_add_u64 v[148:149], v[220:221], 0, s[12:13]
	s_mov_b32 m0, s75
	s_nop 0
	global_load_lds_dwordx4 v[148:149], off
	s_waitcnt vmcnt(8)
	s_waitcnt lgkmcnt(0)
	s_barrier
	s_setprio 1
	s_waitcnt lgkmcnt(0)
	v_mfma_f32_16x16x32_bf16 v[60:63], v[140:143], v[186:189], v[60:63]
	v_mfma_f32_16x16x32_bf16 v[56:59], v[162:165], v[186:189], v[56:59]
	v_mfma_f32_16x16x32_bf16 v[44:47], v[140:143], v[194:197], v[44:47]
	v_mfma_f32_16x16x32_bf16 v[40:43], v[162:165], v[194:197], v[40:43]
	v_mfma_f32_16x16x32_bf16 v[28:31], v[140:143], v[202:205], v[28:31]
	v_mfma_f32_16x16x32_bf16 v[24:27], v[162:165], v[202:205], v[24:27]
	v_mfma_f32_16x16x32_bf16 v[12:15], v[140:143], v[210:213], v[12:15]
	v_mfma_f32_16x16x32_bf16 v[8:11], v[162:165], v[210:213], v[8:11]
	v_mfma_f32_16x16x32_bf16 v[60:63], v[144:147], v[190:193], v[60:63]
	v_mfma_f32_16x16x32_bf16 v[56:59], v[166:169], v[190:193], v[56:59]
	v_mfma_f32_16x16x32_bf16 v[44:47], v[144:147], v[198:201], v[44:47]
	v_mfma_f32_16x16x32_bf16 v[40:43], v[166:169], v[198:201], v[40:43]
	v_mfma_f32_16x16x32_bf16 v[28:31], v[144:147], v[206:209], v[28:31]
	v_mfma_f32_16x16x32_bf16 v[24:27], v[166:169], v[206:209], v[24:27]
	v_mfma_f32_16x16x32_bf16 v[12:15], v[144:147], v[214:217], v[12:15]
	v_mfma_f32_16x16x32_bf16 v[8:11], v[166:169], v[214:217], v[8:11]
	v_mfma_f32_16x16x32_bf16 v[52:55], v[170:173], v[186:189], v[52:55]
	v_mfma_f32_16x16x32_bf16 v[48:51], v[178:181], v[186:189], v[48:51]
	v_mfma_f32_16x16x32_bf16 v[36:39], v[170:173], v[194:197], v[36:39]
	v_mfma_f32_16x16x32_bf16 v[32:35], v[178:181], v[194:197], v[32:35]
	v_mfma_f32_16x16x32_bf16 v[20:23], v[170:173], v[202:205], v[20:23]
	v_mfma_f32_16x16x32_bf16 v[16:19], v[178:181], v[202:205], v[16:19]
	v_mfma_f32_16x16x32_bf16 v[4:7], v[170:173], v[210:213], v[4:7]
	v_mfma_f32_16x16x32_bf16 v[0:3], v[178:181], v[210:213], v[0:3]
	v_mfma_f32_16x16x32_bf16 v[52:55], v[174:177], v[190:193], v[52:55]
	v_mfma_f32_16x16x32_bf16 v[48:51], v[182:185], v[190:193], v[48:51]
	v_mfma_f32_16x16x32_bf16 v[36:39], v[174:177], v[198:201], v[36:39]
	v_mfma_f32_16x16x32_bf16 v[32:35], v[182:185], v[198:201], v[32:35]
	v_mfma_f32_16x16x32_bf16 v[20:23], v[174:177], v[206:209], v[20:23]
	v_mfma_f32_16x16x32_bf16 v[16:19], v[182:185], v[206:209], v[16:19]
	v_mfma_f32_16x16x32_bf16 v[4:7], v[174:177], v[214:217], v[4:7]
	v_mfma_f32_16x16x32_bf16 v[0:3], v[182:185], v[214:217], v[0:3]
	s_setprio 0
	s_barrier
	s_add_i32 s93, s93, 2
	s_add_u32 s91, s91, 0x100
	s_addc_u32 s92, s92, 0
	s_cmp_gt_u32 s93, 5
	s_cbranch_scc0 .LBB0_683
	s_and_b64 vcc, exec, s[20:21]
	s_cbranch_vccz .LBB0_686
	s_barrier

; #define PG8_STAGE(bufoff, gbase, voff) do { _Pragma("unroll") for (int _i = 0; _i < 2; ++_i) \
;         __builtin_amdgcn_global_load_lds((const unsigned*)((const char*)(gbase) + (voff)[_i]), (LAS unsigned*)(lds + (bufoff) + ldsw + _i * 8192), 16, 0, 0); } while (0)
; #define PG8_LDA(dst, b, h) do { _Pragma("unroll") for (int m = 0; m < 4; ++m) _Pragma("unroll") for (int k = 0; k < 2; ++k) dst[m][k] = *(const LAS bf16x8*)(lds + PG8_SA(b, h) + aoff + m * 2048 + k * 1024); } while (0)
; #define PG8_LDB(dst, b, h) do { _Pragma("unroll") for (int n = 0; n < 2; ++n) _Pragma("unroll") for (int k = 0; k < 2; ++k) dst[n][k] = *(const LAS bf16x8*)(lds + PG8_SB(b, h) + boff + n * 2048 + k * 1024); } while (0)
; #define PG8_WAIT_V(n) asm volatile("s_waitcnt vmcnt(" #n ")" ::: "memory")
; template <class Epi, class Sched, bool ALIGN_EPI = false, bool SP2 = false, bool TWOA = false, bool AGM = false>
; __device__ __forceinline__ void gemm_phase(LAS unsigned char* lds, const Gemm g, const Sched& S, const Epi& E, int wid) {
;     ...
;         for (int t = 0; t < nt; t += 2) {
;             const bool last = (t == nt - 2);
;             const char* cA2 = TWOA ? (const char*)g.A2 + (cA - (const char*)g.A) - (size_t)nh * kstepA : cA;
;             const char* a1_ = (TWOA && t + 1 >= nh ? cA2 : cA) + (size_t)(t + 1) * kstepA;
;             const char* a2_ = last ? nA : (TWOA && t + 2 >= nh ? cA2 : cA) + (size_t)(t + 2) * kstepA; const char* a1 = a1_; const char* a2 = a2_; const char* b2 = last ? nB : cB + (size_t)(t + 2) * kstep;
;             if constexpr (TWOA) { asm volatile("" : "+s"(a1)); asm volatile("" : "+s"(a2)); }
;             const char* a3 = a2 + kstepA; const char* b3 = b2 + kstep;
;             if (last && has_next) S.a_ready(nxt);
;             if constexpr (has_mid<Epi>::value) { if (t == nh) E.mid(acc, cur, wr, wc, fr, fq); }
;             if constexpr (SP2) {
;             PG8_LDB(B0, 0, 0); PG8_LDB(B1, 0, 1); PG8_SCHED; PG8_LDA(At, 0, 0); PG8_STAGE(PG8_SA(1, 1), a1 + hstepA, voffA);
;             PG8_WAIT_V(8); PG8_WAIT_L(0); PG8_BAR; PG8_MMA(0, 0, At, B0); PG8_MMA(0, 1, At, B1); PG8_BAR; PG8_SCHED;
;             PG8_LDA(At, 0, 1); PG8_STAGE(PG8_SB(0, 0), b2, voffB); PG8_STAGE(PG8_SB(0, 1), b2 + hstep, voffB); PG8_STAGE(PG8_SA(0, 0), a2, voffA);
;             PG8_WAIT_V(8); PG8_WAIT_L(0); PG8_BAR; PG8_MMA(1, 0, At, B0); PG8_MMA(1, 1, At, B1); PG8_BAR; PG8_SCHED;
.LBB0_753:
	ds_read_b128 v[146:149], v152
	ds_read_b128 v[156:159], v152 offset:1024
	ds_read_b128 v[160:163], v152 offset:2048
	ds_read_b128 v[164:167], v152 offset:3072
	ds_read_b128 v[168:171], v153
	ds_read_b128 v[172:175], v153 offset:1024
	ds_read_b128 v[176:179], v153 offset:2048
	ds_read_b128 v[180:183], v153 offset:3072
	s_add_u32 s38, s36, 0x600000
	s_addc_u32 s39, s37, 0
	s_cmp_eq_u32 s75, 28
	s_cselect_b32 s44, s71, s38
	s_cselect_b32 s45, s25, s39
	s_cselect_b32 s42, s72, s73
	s_cselect_b32 s43, s23, s74
	s_add_u32 s40, s44, 0x300000
	s_addc_u32 s41, s45, 0
	v_lshl_add_u64 v[216:217], s[36:37], 0, v[136:137]
	s_add_i32 m0, s50, 0xc000
	ds_read_b128 v[184:187], v154
	ds_read_b128 v[188:191], v154 offset:1024
	ds_read_b128 v[192:195], v154 offset:2048
	ds_read_b128 v[196:199], v154 offset:3072
	ds_read_b128 v[200:203], v154 offset:4096
	ds_read_b128 v[204:207], v154 offset:5120
	ds_read_b128 v[208:211], v154 offset:6144
	ds_read_b128 v[212:215], v154 offset:7168
	global_load_lds_dwordx4 v[216:217], off
	v_lshl_add_u64 v[216:217], s[36:37], 0, v[138:139]
	s_add_i32 m0, s50, 0xe000
	s_nop 0
	global_load_lds_dwordx4 v[216:217], off
	s_waitcnt vmcnt(8)
	s_waitcnt lgkmcnt(0)
	s_barrier
	s_setprio 1
	s_waitcnt lgkmcnt(0)
	v_mfma_f32_16x16x32_bf16 v[116:119], v[146:149], v[184:187], v[116:119]
	v_mfma_f32_16x16x32_bf16 v[112:115], v[160:163], v[184:187], v[112:115]
	v_mfma_f32_16x16x32_bf16 v[100:103], v[146:149], v[192:195], v[100:103]
	v_mfma_f32_16x16x32_bf16 v[96:99], v[160:163], v[192:195], v[96:99]
	v_mfma_f32_16x16x32_bf16 v[84:87], v[146:149], v[200:203], v[84:87]
	v_mfma_f32_16x16x32_bf16 v[80:83], v[160:163], v[200:203], v[80:83]
	v_mfma_f32_16x16x32_bf16 v[68:71], v[146:149], v[208:211], v[68:71]
	v_mfma_f32_16x16x32_bf16 v[64:67], v[160:163], v[208:211], v[64:67]
	v_mfma_f32_16x16x32_bf16 v[116:119], v[156:159], v[188:191], v[116:119]
	v_mfma_f32_16x16x32_bf16 v[112:115], v[164:167], v[188:191], v[112:115]
	v_mfma_f32_16x16x32_bf16 v[100:103], v[156:159], v[196:199], v[100:103]
	v_mfma_f32_16x16x32_bf16 v[96:99], v[164:167], v[196:199], v[96:99]
	v_mfma_f32_16x16x32_bf16 v[84:87], v[156:159], v[204:207], v[84:87]
	v_mfma_f32_16x16x32_bf16 v[80:83], v[164:167], v[204:207], v[80:83]
	v_mfma_f32_16x16x32_bf16 v[68:71], v[156:159], v[212:215], v[68:71]
	v_mfma_f32_16x16x32_bf16 v[64:67], v[164:167], v[212:215], v[64:67]
	v_mfma_f32_16x16x32_bf16 v[124:127], v[168:171], v[184:187], v[124:127]
	v_mfma_f32_16x16x32_bf16 v[120:123], v[176:179], v[184:187], v[120:123]
	v_mfma_f32_16x16x32_bf16 v[108:111], v[168:171], v[192:195], v[108:111]
	v_mfma_f32_16x16x32_bf16 v[104:107], v[176:179], v[192:195], v[104:107]
	v_mfma_f32_16x16x32_bf16 v[92:95], v[168:171], v[200:203], v[92:95]
	v_mfma_f32_16x16x32_bf16 v[88:91], v[176:179], v[200:203], v[88:91]
	v_mfma_f32_16x16x32_bf16 v[76:79], v[168:171], v[208:211], v[76:79]
	v_mfma_f32_16x16x32_bf16 v[72:75], v[176:179], v[208:211], v[72:75]
	v_mfma_f32_16x16x32_bf16 v[124:127], v[172:175], v[188:191], v[124:127]
	v_mfma_f32_16x16x32_bf16 v[120:123], v[180:183], v[188:191], v[120:123]
	v_mfma_f32_16x16x32_bf16 v[108:111], v[172:175], v[196:199], v[108:111]
	v_mfma_f32_16x16x32_bf16 v[104:107], v[180:183], v[196:199], v[104:107]
	v_mfma_f32_16x16x32_bf16 v[92:95], v[172:175], v[204:207], v[92:95]
	v_mfma_f32_16x16x32_bf16 v[88:91], v[180:183], v[204:207], v[88:91]
	v_mfma_f32_16x16x32_bf16 v[76:79], v[172:175], v[212:215], v[76:79]
	v_mfma_f32_16x16x32_bf16 v[72:75], v[180:183], v[212:215], v[72:75]
	s_setprio 0
	s_barrier
	s_add_i32 s34, s65, s3
	v_lshl_add_u64 v[216:217], s[42:43], 0, v[132:133]
	s_mov_b32 m0, s34
	ds_read_b128 v[184:187], v154 offset:16384
	ds_read_b128 v[188:191], v154 offset:17408
	ds_read_b128 v[192:195], v154 offset:18432
	ds_read_b128 v[196:199], v154 offset:19456
	ds_read_b128 v[200:203], v154 offset:20480
	ds_read_b128 v[204:207], v154 offset:21504
	ds_read_b128 v[208:211], v154 offset:22528
	ds_read_b128 v[212:215], v154 offset:23552
	global_load_lds_dwordx4 v[216:217], off
	s_add_i32 m0, s34, 0x2000
	s_add_u32 s34, s42, 0x80000
	v_lshl_add_u64 v[218:219], s[42:43], 0, v[128:129]
	s_addc_u32 s35, s43, 0
	s_add_i32 s36, s66, s3
	global_load_lds_dwordx4 v[218:219], off
	v_lshl_add_u64 v[220:221], s[34:35], 0, v[132:133]
	s_mov_b32 m0, s36
	s_nop 0
	global_load_lds_dwordx4 v[220:221], off
	v_lshl_add_u64 v[220:221], s[34:35], 0, v[128:129]
	s_add_i32 m0, s36, 0x2000
	s_nop 0
	global_load_lds_dwordx4 v[220:221], off
	v_lshl_add_u64 v[220:221], s[44:45], 0, v[134:135]
	s_mov_b32 m0, s50
	s_nop 0
	global_load_lds_dwordx4 v[220:221], off
	v_lshl_add_u64 v[220:221], s[44:45], 0, v[130:131]
	s_mov_b32 m0, s51
	s_nop 0
	global_load_lds_dwordx4 v[220:221], off
	s_waitcnt vmcnt(8)
	s_waitcnt lgkmcnt(0)
	s_barrier
; #define PG8_STAGE(bufoff, gbase, voff) do { _Pragma("unroll") for (int _i = 0; _i < 2; ++_i) \
;         __builtin_amdgcn_global_load_lds((const unsigned*)((const char*)(gbase) + (voff)[_i]), (LAS unsigned*)(lds + (bufoff) + ldsw + _i * 8192), 16, 0, 0); } while (0)
; #define PG8_LDA(dst, b, h) do { _Pragma("unroll") for (int m = 0; m < 4; ++m) _Pragma("unroll") for (int k = 0; k < 2; ++k) dst[m][k] = *(const LAS bf16x8*)(lds + PG8_SA(b, h) + aoff + m * 2048 + k * 1024); } while (0)
; #define PG8_LDB(dst, b, h) do { _Pragma("unroll") for (int n = 0; n < 2; ++n) _Pragma("unroll") for (int k = 0; k < 2; ++k) dst[n][k] = *(const LAS bf16x8*)(lds + PG8_SB(b, h) + boff + n * 2048 + k * 1024); } while (0)
; #define PG8_MMA(ai, bj, At, Bt) do { __builtin_amdgcn_s_setprio(1); _Pragma("unroll") for (int m = 0; m < 4; ++m) _Pragma("unroll") for (int n = 0; n < 2; ++n) _Pragma("unroll") for (int k = 0; k < 2; ++k) \
;         acc[ai][bj][m][n] = __builtin_amdgcn_mfma_f32_16x16x32_bf16(Bt[n][k], At[m][k], acc[ai][bj][m][n], 0, 0, 0); __builtin_amdgcn_s_setprio(0); } while (0)
; #define PG8_WAIT_V(n) asm volatile("s_waitcnt vmcnt(" #n ")" ::: "memory")
; #define PG8_WAIT_L(n) asm volatile("s_waitcnt lgkmcnt(" #n ")" ::: "memory")
; #define PG8_BAR __builtin_amdgcn_s_barrier()
; #define PG8_SCHED __builtin_amdgcn_sched_barrier(0)
; template <class Epi, class Sched, bool ALIGN_EPI = false, bool SP2 = false, bool TWOA = false, bool AGM = false>
; __device__ __forceinline__ void gemm_phase(LAS unsigned char* lds, const Gemm g, const Sched& S, const Epi& E, int wid) {
;     ...
;             PG8_WAIT_V(8); PG8_WAIT_L(0); PG8_BAR; PG8_MMA(0, 0, At, B0); PG8_MMA(0, 1, At, B1); PG8_BAR; PG8_SCHED;
;             PG8_LDA(At, 0, 1); PG8_STAGE(PG8_SB(0, 0), b2, voffB); PG8_STAGE(PG8_SB(0, 1), b2 + hstep, voffB); PG8_STAGE(PG8_SA(0, 0), a2, voffA);
;             PG8_WAIT_V(8); PG8_WAIT_L(0); PG8_BAR; PG8_MMA(1, 0, At, B0); PG8_MMA(1, 1, At, B1); PG8_BAR; PG8_SCHED;
;             PG8_LDB(B0, 1, 0); PG8_LDB(B1, 1, 1); PG8_SCHED; PG8_LDA(At, 1, 0); PG8_STAGE(PG8_SA(0, 1), a2 + hstepA, voffA);
;             PG8_WAIT_V(8); PG8_WAIT_L(0); PG8_BAR; PG8_MMA(0, 0, At, B0); PG8_MMA(0, 1, At, B1); PG8_BAR; PG8_SCHED;
	s_setprio 1
	s_waitcnt lgkmcnt(0)
	v_mfma_f32_16x16x32_bf16 v[52:55], v[146:149], v[184:187], v[52:55]
	v_mfma_f32_16x16x32_bf16 v[48:51], v[160:163], v[184:187], v[48:51]
	v_mfma_f32_16x16x32_bf16 v[36:39], v[146:149], v[192:195], v[36:39]
	v_mfma_f32_16x16x32_bf16 v[32:35], v[160:163], v[192:195], v[32:35]
	v_mfma_f32_16x16x32_bf16 v[20:23], v[146:149], v[200:203], v[20:23]
	v_mfma_f32_16x16x32_bf16 v[16:19], v[160:163], v[200:203], v[16:19]
	v_mfma_f32_16x16x32_bf16 v[4:7], v[146:149], v[208:211], v[4:7]
	v_mfma_f32_16x16x32_bf16 v[0:3], v[160:163], v[208:211], v[0:3]
	v_mfma_f32_16x16x32_bf16 v[52:55], v[156:159], v[188:191], v[52:55]
	v_mfma_f32_16x16x32_bf16 v[48:51], v[164:167], v[188:191], v[48:51]
	v_mfma_f32_16x16x32_bf16 v[36:39], v[156:159], v[196:199], v[36:39]
	v_mfma_f32_16x16x32_bf16 v[32:35], v[164:167], v[196:199], v[32:35]
	v_mfma_f32_16x16x32_bf16 v[20:23], v[156:159], v[204:207], v[20:23]
	v_mfma_f32_16x16x32_bf16 v[16:19], v[164:167], v[204:207], v[16:19]
	v_mfma_f32_16x16x32_bf16 v[4:7], v[156:159], v[212:215], v[4:7]
	v_mfma_f32_16x16x32_bf16 v[0:3], v[164:167], v[212:215], v[0:3]
	v_mfma_f32_16x16x32_bf16 v[60:63], v[168:171], v[184:187], v[60:63]
	v_mfma_f32_16x16x32_bf16 v[56:59], v[176:179], v[184:187], v[56:59]
	v_mfma_f32_16x16x32_bf16 v[44:47], v[168:171], v[192:195], v[44:47]
	v_mfma_f32_16x16x32_bf16 v[40:43], v[176:179], v[192:195], v[40:43]
	v_mfma_f32_16x16x32_bf16 v[28:31], v[168:171], v[200:203], v[28:31]
	v_mfma_f32_16x16x32_bf16 v[24:27], v[176:179], v[200:203], v[24:27]
	v_mfma_f32_16x16x32_bf16 v[12:15], v[168:171], v[208:211], v[12:15]
	v_mfma_f32_16x16x32_bf16 v[8:11], v[176:179], v[208:211], v[8:11]
	v_mfma_f32_16x16x32_bf16 v[60:63], v[172:175], v[188:191], v[60:63]
	v_mfma_f32_16x16x32_bf16 v[56:59], v[180:183], v[188:191], v[56:59]
	v_mfma_f32_16x16x32_bf16 v[44:47], v[172:175], v[196:199], v[44:47]
	v_mfma_f32_16x16x32_bf16 v[40:43], v[180:183], v[196:199], v[40:43]
	v_mfma_f32_16x16x32_bf16 v[28:31], v[172:175], v[204:207], v[28:31]
	v_mfma_f32_16x16x32_bf16 v[24:27], v[180:183], v[204:207], v[24:27]
	v_mfma_f32_16x16x32_bf16 v[12:15], v[172:175], v[212:215], v[12:15]
	v_mfma_f32_16x16x32_bf16 v[8:11], v[180:183], v[212:215], v[8:11]
	s_setprio 0
	s_barrier
	s_add_i32 s36, 0, 0x18000
	v_add_u32_e32 v155, s36, v151
	s_add_i32 s37, 0, 0x1c000
	ds_read_b128 v[146:149], v155
	ds_read_b128 v[156:159], v155 offset:1024
	ds_read_b128 v[160:163], v155 offset:2048
	ds_read_b128 v[164:167], v155 offset:3072
	v_add_u32_e32 v155, s37, v151
	ds_read_b128 v[168:171], v155
	ds_read_b128 v[172:175], v155 offset:1024
	ds_read_b128 v[176:179], v155 offset:2048
	ds_read_b128 v[180:183], v155 offset:3072
	s_add_u32 s34, s44, 0x1000
	s_addc_u32 s35, s45, 0
	s_mov_b32 m0, s52
	v_lshl_add_u64 v[220:221], s[34:35], 0, v[134:135]
	ds_read_b128 v[184:187], v154 offset:32768
	ds_read_b128 v[188:191], v154 offset:33792
	ds_read_b128 v[192:195], v154 offset:34816
	ds_read_b128 v[196:199], v154 offset:35840
	ds_read_b128 v[200:203], v154 offset:36864
	ds_read_b128 v[204:207], v154 offset:37888
	ds_read_b128 v[208:211], v154 offset:38912
	ds_read_b128 v[212:215], v154 offset:39936
	global_load_lds_dwordx4 v[220:221], off
	v_lshl_add_u64 v[220:221], s[34:35], 0, v[130:131]
	s_mov_b32 m0, s53
	s_nop 0
	global_load_lds_dwordx4 v[220:221], off
	s_waitcnt vmcnt(8)
	s_waitcnt lgkmcnt(0)
	s_barrier
	s_setprio 1
	s_waitcnt lgkmcnt(0)
	v_mfma_f32_16x16x32_bf16 v[116:119], v[146:149], v[184:187], v[116:119]
	v_mfma_f32_16x16x32_bf16 v[112:115], v[160:163], v[184:187], v[112:115]
	v_mfma_f32_16x16x32_bf16 v[100:103], v[146:149], v[192:195], v[100:103]
	v_mfma_f32_16x16x32_bf16 v[96:99], v[160:163], v[192:195], v[96:99]
	v_mfma_f32_16x16x32_bf16 v[84:87], v[146:149], v[200:203], v[84:87]
	v_mfma_f32_16x16x32_bf16 v[80:83], v[160:163], v[200:203], v[80:83]
	v_mfma_f32_16x16x32_bf16 v[68:71], v[146:149], v[208:211], v[68:71]
	v_mfma_f32_16x16x32_bf16 v[64:67], v[160:163], v[208:211], v[64:67]
	v_mfma_f32_16x16x32_bf16 v[116:119], v[156:159], v[188:191], v[116:119]
	v_mfma_f32_16x16x32_bf16 v[112:115], v[164:167], v[188:191], v[112:115]
	v_mfma_f32_16x16x32_bf16 v[100:103], v[156:159], v[196:199], v[100:103]
	v_mfma_f32_16x16x32_bf16 v[96:99], v[164:167], v[196:199], v[96:99]
	v_mfma_f32_16x16x32_bf16 v[84:87], v[156:159], v[204:207], v[84:87]
	v_mfma_f32_16x16x32_bf16 v[80:83], v[164:167], v[204:207], v[80:83]
	v_mfma_f32_16x16x32_bf16 v[68:71], v[156:159], v[212:215], v[68:71]
	v_mfma_f32_16x16x32_bf16 v[64:67], v[164:167], v[212:215], v[64:67]
	v_mfma_f32_16x16x32_bf16 v[124:127], v[168:171], v[184:187], v[124:127]
	v_mfma_f32_16x16x32_bf16 v[120:123], v[176:179], v[184:187], v[120:123]
	v_mfma_f32_16x16x32_bf16 v[108:111], v[168:171], v[192:195], v[108:111]
	v_mfma_f32_16x16x32_bf16 v[104:107], v[176:179], v[192:195], v[104:107]
	v_mfma_f32_16x16x32_bf16 v[92:95], v[168:171], v[200:203], v[92:95]
	v_mfma_f32_16x16x32_bf16 v[88:91], v[176:179], v[200:203], v[88:91]
	v_mfma_f32_16x16x32_bf16 v[76:79], v[168:171], v[208:211], v[76:79]
	v_mfma_f32_16x16x32_bf16 v[72:75], v[176:179], v[208:211], v[72:75]
	v_mfma_f32_16x16x32_bf16 v[124:127], v[172:175], v[188:191], v[124:127]
	v_mfma_f32_16x16x32_bf16 v[120:123], v[180:183], v[188:191], v[120:123]
	v_mfma_f32_16x16x32_bf16 v[108:111], v[172:175], v[196:199], v[108:111]
	v_mfma_f32_16x16x32_bf16 v[104:107], v[180:183], v[196:199], v[104:107]
	v_mfma_f32_16x16x32_bf16 v[92:95], v[172:175], v[204:207], v[92:95]
	v_mfma_f32_16x16x32_bf16 v[88:91], v[180:183], v[204:207], v[88:91]
	v_mfma_f32_16x16x32_bf16 v[76:79], v[172:175], v[212:215], v[76:79]
	v_mfma_f32_16x16x32_bf16 v[72:75], v[180:183], v[212:215], v[72:75]
	s_setprio 0
	s_barrier
; #define PG8_STAGE(bufoff, gbase, voff) do { _Pragma("unroll") for (int _i = 0; _i < 2; ++_i) \
;         __builtin_amdgcn_global_load_lds((const unsigned*)((const char*)(gbase) + (voff)[_i]), (LAS unsigned*)(lds + (bufoff) + ldsw + _i * 8192), 16, 0, 0); } while (0)
; #define PG8_LDA(dst, b, h) do { _Pragma("unroll") for (int m = 0; m < 4; ++m) _Pragma("unroll") for (int k = 0; k < 2; ++k) dst[m][k] = *(const LAS bf16x8*)(lds + PG8_SA(b, h) + aoff + m * 2048 + k * 1024); } while (0)
; #define PG8_MMA(ai, bj, At, Bt) do { __builtin_amdgcn_s_setprio(1); _Pragma("unroll") for (int m = 0; m < 4; ++m) _Pragma("unroll") for (int n = 0; n < 2; ++n) _Pragma("unroll") for (int k = 0; k < 2; ++k) \
;         acc[ai][bj][m][n] = __builtin_amdgcn_mfma_f32_16x16x32_bf16(Bt[n][k], At[m][k], acc[ai][bj][m][n], 0, 0, 0); __builtin_amdgcn_s_setprio(0); } while (0)
; #define PG8_WAIT_V(n) asm volatile("s_waitcnt vmcnt(" #n ")" ::: "memory")
; #define PG8_WAIT_L(n) asm volatile("s_waitcnt lgkmcnt(" #n ")" ::: "memory")
; #define PG8_BAR __builtin_amdgcn_s_barrier()
; #define PG8_SCHED __builtin_amdgcn_sched_barrier(0)
; template <class Epi, class Sched, bool ALIGN_EPI = false, bool SP2 = false, bool TWOA = false, bool AGM = false>
; __device__ __forceinline__ void gemm_phase(LAS unsigned char* lds, const Gemm g, const Sched& S, const Epi& E, int wid) {
;     ...
;             PG8_LDA(At, 1, 1); PG8_STAGE(PG8_SB(1, 0), b3, voffB); PG8_STAGE(PG8_SB(1, 1), b3 + hstep, voffB); PG8_STAGE(PG8_SA(1, 0), a3, voffA);
;             PG8_WAIT_V(8); PG8_WAIT_L(0); PG8_BAR; PG8_MMA(1, 0, At, B0); PG8_MMA(1, 1, At, B1); PG8_BAR; PG8_SCHED;
;     ...
;         if constexpr (ALIGN_EPI) { if (wr == 0) PG8_BAR; }
	s_add_i32 s34, s36, s3
	v_lshl_add_u64 v[216:217], v[216:217], 0, s[12:13]
	s_mov_b32 m0, s34
	ds_read_b128 v[184:187], v154 offset:49152
	ds_read_b128 v[188:191], v154 offset:50176
	ds_read_b128 v[192:195], v154 offset:51200
	ds_read_b128 v[196:199], v154 offset:52224
	ds_read_b128 v[200:203], v154 offset:53248
	ds_read_b128 v[204:207], v154 offset:54272
	ds_read_b128 v[208:211], v154 offset:55296
	ds_read_b128 v[212:215], v154 offset:56320
	global_load_lds_dwordx4 v[216:217], off
	s_add_i32 m0, s34, 0x2000
	s_add_u32 s34, s42, 0x80080
	v_lshl_add_u64 v[216:217], v[218:219], 0, s[12:13]
	s_addc_u32 s35, s43, 0
	s_add_i32 s36, s37, s3
	global_load_lds_dwordx4 v[216:217], off
	v_lshl_add_u64 v[216:217], s[34:35], 0, v[132:133]
	s_mov_b32 m0, s36
	s_nop 0
	global_load_lds_dwordx4 v[216:217], off
	v_lshl_add_u64 v[216:217], s[34:35], 0, v[128:129]
	s_add_i32 m0, s36, 0x2000
	s_nop 0
	global_load_lds_dwordx4 v[216:217], off
	v_lshl_add_u64 v[216:217], s[40:41], 0, v[134:135]
	s_mov_b32 m0, s55
	s_nop 0
	global_load_lds_dwordx4 v[216:217], off
	v_lshl_add_u64 v[216:217], s[40:41], 0, v[130:131]
	s_mov_b32 m0, s56
	s_nop 0
	global_load_lds_dwordx4 v[216:217], off
	s_waitcnt vmcnt(8)
	s_waitcnt lgkmcnt(0)
	s_barrier
	s_setprio 1
	s_waitcnt lgkmcnt(0)
	v_mfma_f32_16x16x32_bf16 v[52:55], v[146:149], v[184:187], v[52:55]
	v_mfma_f32_16x16x32_bf16 v[48:51], v[160:163], v[184:187], v[48:51]
	v_mfma_f32_16x16x32_bf16 v[36:39], v[146:149], v[192:195], v[36:39]
	v_mfma_f32_16x16x32_bf16 v[32:35], v[160:163], v[192:195], v[32:35]
	v_mfma_f32_16x16x32_bf16 v[20:23], v[146:149], v[200:203], v[20:23]
	v_mfma_f32_16x16x32_bf16 v[16:19], v[160:163], v[200:203], v[16:19]
	v_mfma_f32_16x16x32_bf16 v[4:7], v[146:149], v[208:211], v[4:7]
	v_mfma_f32_16x16x32_bf16 v[0:3], v[160:163], v[208:211], v[0:3]
	v_mfma_f32_16x16x32_bf16 v[52:55], v[156:159], v[188:191], v[52:55]
	v_mfma_f32_16x16x32_bf16 v[48:51], v[164:167], v[188:191], v[48:51]
	v_mfma_f32_16x16x32_bf16 v[36:39], v[156:159], v[196:199], v[36:39]
	v_mfma_f32_16x16x32_bf16 v[32:35], v[164:167], v[196:199], v[32:35]
	v_mfma_f32_16x16x32_bf16 v[20:23], v[156:159], v[204:207], v[20:23]
	v_mfma_f32_16x16x32_bf16 v[16:19], v[164:167], v[204:207], v[16:19]
	v_mfma_f32_16x16x32_bf16 v[4:7], v[156:159], v[212:215], v[4:7]
	v_mfma_f32_16x16x32_bf16 v[0:3], v[164:167], v[212:215], v[0:3]
	v_mfma_f32_16x16x32_bf16 v[60:63], v[168:171], v[184:187], v[60:63]
	v_mfma_f32_16x16x32_bf16 v[56:59], v[176:179], v[184:187], v[56:59]
	v_mfma_f32_16x16x32_bf16 v[44:47], v[168:171], v[192:195], v[44:47]
	v_mfma_f32_16x16x32_bf16 v[40:43], v[176:179], v[192:195], v[40:43]
	v_mfma_f32_16x16x32_bf16 v[28:31], v[168:171], v[200:203], v[28:31]
	v_mfma_f32_16x16x32_bf16 v[24:27], v[176:179], v[200:203], v[24:27]
	v_mfma_f32_16x16x32_bf16 v[12:15], v[168:171], v[208:211], v[12:15]
	v_mfma_f32_16x16x32_bf16 v[8:11], v[176:179], v[208:211], v[8:11]
	v_mfma_f32_16x16x32_bf16 v[60:63], v[172:175], v[188:191], v[60:63]
	v_mfma_f32_16x16x32_bf16 v[56:59], v[180:183], v[188:191], v[56:59]
	v_mfma_f32_16x16x32_bf16 v[44:47], v[172:175], v[196:199], v[44:47]
	v_mfma_f32_16x16x32_bf16 v[40:43], v[180:183], v[196:199], v[40:43]
	v_mfma_f32_16x16x32_bf16 v[28:31], v[172:175], v[204:207], v[28:31]
	v_mfma_f32_16x16x32_bf16 v[24:27], v[180:183], v[204:207], v[24:27]
	v_mfma_f32_16x16x32_bf16 v[12:15], v[172:175], v[212:215], v[12:15]
	v_mfma_f32_16x16x32_bf16 v[8:11], v[180:183], v[212:215], v[8:11]
	s_setprio 0
	s_barrier
	s_add_i32 s75, s75, 2
	s_add_u32 s73, s73, 0x100
	s_addc_u32 s74, s74, 0
	s_cmp_gt_u32 s75, 29
	s_mov_b64 s[36:37], s[38:39]
	s_cbranch_scc0 .LBB0_753
	s_and_b64 vcc, exec, s[20:21]
	s_cbranch_vccz .LBB0_756
	s_barrier

; #define PG8_STAGE(bufoff, gbase, voff) do { _Pragma("unroll") for (int _i = 0; _i < 2; ++_i) \
;         __builtin_amdgcn_global_load_lds((const unsigned*)((const char*)(gbase) + (voff)[_i]), (LAS unsigned*)(lds + (bufoff) + ldsw + _i * 8192), 16, 0, 0); } while (0)
; #define PG8_LDA(dst, b, h) do { _Pragma("unroll") for (int m = 0; m < 4; ++m) _Pragma("unroll") for (int k = 0; k < 2; ++k) dst[m][k] = *(const LAS bf16x8*)(lds + PG8_SA(b, h) + aoff + m * 2048 + k * 1024); } while (0)
; #define PG8_WAIT_V(n) asm volatile("s_waitcnt vmcnt(" #n ")" ::: "memory")
; #define PG8_WAIT_L(n) asm volatile("s_waitcnt lgkmcnt(" #n ")" ::: "memory")
; template <class Epi, class Sched, bool ALIGN_EPI = false, bool SP2 = false, bool TWOA = false, bool AGM = false>
; __device__ __forceinline__ void gemm_phase(LAS unsigned char* lds, const Gemm g, const Sched& S, const Epi& E, int wid) {
;     ...
;         for (int t = 0; t < nt; t += 2) {
;             const bool last = (t == nt - 2);
;             const char* cA2 = TWOA ? (const char*)g.A2 + (cA - (const char*)g.A) - (size_t)nh * kstepA : cA;
;             const char* a1_ = (TWOA && t + 1 >= nh ? cA2 : cA) + (size_t)(t + 1) * kstepA;
;             const char* a2_ = last ? nA : (TWOA && t + 2 >= nh ? cA2 : cA) + (size_t)(t + 2) * kstepA; const char* a1 = a1_; const char* a2 = a2_; const char* b2 = last ? nB : cB + (size_t)(t + 2) * kstep;
;             if constexpr (TWOA) { asm volatile("" : "+s"(a1)); asm volatile("" : "+s"(a2)); }
;             const char* a3 = a2 + kstepA; const char* b3 = b2 + kstep;
;             if (last && has_next) S.a_ready(nxt);
;             if constexpr (has_mid<Epi>::value) { if (t == nh) E.mid(acc, cur, wr, wc, fr, fq); }
;             if constexpr (SP2) {
;             PG8_LDB(B0, 0, 0); PG8_LDB(B1, 0, 1); PG8_SCHED; PG8_LDA(At, 0, 0); PG8_STAGE(PG8_SA(1, 1), a1 + hstepA, voffA);
;             PG8_WAIT_V(8); PG8_WAIT_L(0); PG8_BAR; PG8_MMA(0, 0, At, B0); PG8_MMA(0, 1, At, B1); PG8_BAR; PG8_SCHED;
;             PG8_LDA(At, 0, 1); PG8_STAGE(PG8_SB(0, 0), b2, voffB); PG8_STAGE(PG8_SB(0, 1), b2 + hstep, voffB); PG8_STAGE(PG8_SA(0, 0), a2, voffA);
;             PG8_WAIT_V(8); PG8_WAIT_L(0); PG8_BAR; PG8_MMA(1, 0, At, B0); PG8_MMA(1, 1, At, B1); PG8_BAR; PG8_SCHED;
;             PG8_LDB(B0, 1, 0); PG8_LDB(B1, 1, 1); PG8_SCHED; PG8_LDA(At, 1, 0); PG8_STAGE(PG8_SA(0, 1), a2 + hstepA, voffA);
.LBB0_826:
	v_add_u32_e32 v1, s65, v153
	ds_read_b128 v[132:135], v1
	ds_read_b128 v[136:139], v1 offset:1024
	ds_read_b128 v[158:161], v1 offset:2048
	ds_read_b128 v[162:165], v1 offset:3072
	v_add_u32_e32 v1, s66, v153
	ds_read_b128 v[166:169], v1
	ds_read_b128 v[170:173], v1 offset:1024
	ds_read_b128 v[174:177], v1 offset:2048
	ds_read_b128 v[178:181], v1 offset:3072
	s_add_u32 s74, s71, s36
	s_addc_u32 s75, s72, s37
	s_and_b64 s[34:35], s[42:43], exec
	s_cselect_b32 s43, s23, s75
	s_cselect_b32 s42, s68, s74
	s_add_u32 s34, s40, 0x80000
	s_addc_u32 s35, s41, 0
	v_lshl_add_u64 v[2:3], s[34:35], 0, v[146:147]
	s_add_i32 m0, s50, 0xc000
	ds_read_b128 v[182:185], v156
	ds_read_b128 v[186:189], v156 offset:1024
	ds_read_b128 v[190:193], v156 offset:2048
	ds_read_b128 v[194:197], v156 offset:3072
	ds_read_b128 v[198:201], v156 offset:4096
	ds_read_b128 v[202:205], v156 offset:5120
	ds_read_b128 v[206:209], v156 offset:6144
	ds_read_b128 v[210:213], v156 offset:7168
	global_load_lds_dwordx4 v[2:3], off
	v_lshl_add_u64 v[2:3], s[34:35], 0, v[142:143]
	s_add_i32 m0, s50, 0xe000
	s_nop 0
	global_load_lds_dwordx4 v[2:3], off
	s_waitcnt vmcnt(8)
	s_waitcnt lgkmcnt(0)
	s_barrier
	s_setprio 1
	s_waitcnt lgkmcnt(0)
	v_mfma_f32_16x16x32_bf16 v[128:131], v[132:135], v[182:185], v[128:131]
	v_mfma_f32_16x16x32_bf16 v[124:127], v[158:161], v[182:185], v[124:127]
	v_mfma_f32_16x16x32_bf16 v[112:115], v[132:135], v[190:193], v[112:115]
	v_mfma_f32_16x16x32_bf16 v[108:111], v[158:161], v[190:193], v[108:111]
	v_mfma_f32_16x16x32_bf16 v[96:99], v[132:135], v[198:201], v[96:99]
	v_mfma_f32_16x16x32_bf16 v[92:95], v[158:161], v[198:201], v[92:95]
	v_mfma_f32_16x16x32_bf16 v[80:83], v[132:135], v[206:209], v[80:83]
	v_mfma_f32_16x16x32_bf16 v[76:79], v[158:161], v[206:209], v[76:79]
	v_mfma_f32_16x16x32_bf16 v[128:131], v[136:139], v[186:189], v[128:131]
	v_mfma_f32_16x16x32_bf16 v[124:127], v[162:165], v[186:189], v[124:127]
	v_mfma_f32_16x16x32_bf16 v[112:115], v[136:139], v[194:197], v[112:115]
	v_mfma_f32_16x16x32_bf16 v[108:111], v[162:165], v[194:197], v[108:111]
	v_mfma_f32_16x16x32_bf16 v[96:99], v[136:139], v[202:205], v[96:99]
	v_mfma_f32_16x16x32_bf16 v[92:95], v[162:165], v[202:205], v[92:95]
	v_mfma_f32_16x16x32_bf16 v[80:83], v[136:139], v[210:213], v[80:83]
	v_mfma_f32_16x16x32_bf16 v[76:79], v[162:165], v[210:213], v[76:79]
	v_mfma_f32_16x16x32_bf16 v[120:123], v[166:169], v[182:185], v[120:123]
	v_mfma_f32_16x16x32_bf16 v[116:119], v[174:177], v[182:185], v[116:119]
	v_mfma_f32_16x16x32_bf16 v[104:107], v[166:169], v[190:193], v[104:107]
	v_mfma_f32_16x16x32_bf16 v[100:103], v[174:177], v[190:193], v[100:103]
	v_mfma_f32_16x16x32_bf16 v[88:91], v[166:169], v[198:201], v[88:91]
	v_mfma_f32_16x16x32_bf16 v[84:87], v[174:177], v[198:201], v[84:87]
	v_mfma_f32_16x16x32_bf16 v[72:75], v[166:169], v[206:209], v[72:75]
	v_mfma_f32_16x16x32_bf16 v[68:71], v[174:177], v[206:209], v[68:71]
	v_mfma_f32_16x16x32_bf16 v[120:123], v[170:173], v[186:189], v[120:123]
	v_mfma_f32_16x16x32_bf16 v[116:119], v[178:181], v[186:189], v[116:119]
	v_mfma_f32_16x16x32_bf16 v[104:107], v[170:173], v[194:197], v[104:107]
	v_mfma_f32_16x16x32_bf16 v[100:103], v[178:181], v[194:197], v[100:103]
	v_mfma_f32_16x16x32_bf16 v[88:91], v[170:173], v[202:205], v[88:91]
	v_mfma_f32_16x16x32_bf16 v[84:87], v[178:181], v[202:205], v[84:87]
	v_mfma_f32_16x16x32_bf16 v[72:75], v[170:173], v[210:213], v[72:75]
	v_mfma_f32_16x16x32_bf16 v[68:71], v[178:181], v[210:213], v[68:71]
	s_setprio 0
	s_barrier
	s_add_i32 s34, s65, s47
	v_lshl_add_u64 v[214:215], s[42:43], 0, v[144:145]
	s_mov_b32 m0, s34
	ds_read_b128 v[182:185], v156 offset:16384
	ds_read_b128 v[186:189], v156 offset:17408
	ds_read_b128 v[190:193], v156 offset:18432
	ds_read_b128 v[194:197], v156 offset:19456
	ds_read_b128 v[198:201], v156 offset:20480
	ds_read_b128 v[202:205], v156 offset:21504
	ds_read_b128 v[206:209], v156 offset:22528
	ds_read_b128 v[210:213], v156 offset:23552
	global_load_lds_dwordx4 v[214:215], off
	s_add_i32 m0, s34, 0x2000
	s_add_u32 s34, s42, 0x100000
	v_lshl_add_u64 v[216:217], s[42:43], 0, v[140:141]
	s_addc_u32 s35, s43, 0
	s_add_i32 s40, s66, s47
	global_load_lds_dwordx4 v[216:217], off
	v_lshl_add_u64 v[2:3], s[34:35], 0, v[144:145]
	s_mov_b32 m0, s40
	v_lshl_add_u64 v[218:219], s[38:39], 0, v[146:147]
	global_load_lds_dwordx4 v[2:3], off
	v_lshl_add_u64 v[2:3], s[34:35], 0, v[140:141]
	s_add_i32 m0, s40, 0x2000
	v_lshl_add_u64 v[220:221], s[38:39], 0, v[142:143]
	global_load_lds_dwordx4 v[2:3], off
	s_mov_b32 m0, s50
	s_nop 0
	global_load_lds_dwordx4 v[218:219], off
	s_mov_b32 m0, s51
	s_nop 0
	global_load_lds_dwordx4 v[220:221], off
	s_waitcnt vmcnt(8)
	s_waitcnt lgkmcnt(0)
	s_barrier
; #define PG8_STAGE(bufoff, gbase, voff) do { _Pragma("unroll") for (int _i = 0; _i < 2; ++_i) \
;         __builtin_amdgcn_global_load_lds((const unsigned*)((const char*)(gbase) + (voff)[_i]), (LAS unsigned*)(lds + (bufoff) + ldsw + _i * 8192), 16, 0, 0); } while (0)
; #define PG8_LDA(dst, b, h) do { _Pragma("unroll") for (int m = 0; m < 4; ++m) _Pragma("unroll") for (int k = 0; k < 2; ++k) dst[m][k] = *(const LAS bf16x8*)(lds + PG8_SA(b, h) + aoff + m * 2048 + k * 1024); } while (0)
; #define PG8_LDB(dst, b, h) do { _Pragma("unroll") for (int n = 0; n < 2; ++n) _Pragma("unroll") for (int k = 0; k < 2; ++k) dst[n][k] = *(const LAS bf16x8*)(lds + PG8_SB(b, h) + boff + n * 2048 + k * 1024); } while (0)
; #define PG8_MMA(ai, bj, At, Bt) do { __builtin_amdgcn_s_setprio(1); _Pragma("unroll") for (int m = 0; m < 4; ++m) _Pragma("unroll") for (int n = 0; n < 2; ++n) _Pragma("unroll") for (int k = 0; k < 2; ++k) \
;         acc[ai][bj][m][n] = __builtin_amdgcn_mfma_f32_16x16x32_bf16(Bt[n][k], At[m][k], acc[ai][bj][m][n], 0, 0, 0); __builtin_amdgcn_s_setprio(0); } while (0)
; #define PG8_WAIT_V(n) asm volatile("s_waitcnt vmcnt(" #n ")" ::: "memory")
; #define PG8_WAIT_L(n) asm volatile("s_waitcnt lgkmcnt(" #n ")" ::: "memory")
; #define PG8_BAR __builtin_amdgcn_s_barrier()
; #define PG8_SCHED __builtin_amdgcn_sched_barrier(0)
; template <class Epi, class Sched, bool ALIGN_EPI = false, bool SP2 = false, bool TWOA = false, bool AGM = false>
; __device__ __forceinline__ void gemm_phase(LAS unsigned char* lds, const Gemm g, const Sched& S, const Epi& E, int wid) {
;     ...
;             PG8_WAIT_V(8); PG8_WAIT_L(0); PG8_BAR; PG8_MMA(0, 0, At, B0); PG8_MMA(0, 1, At, B1); PG8_BAR; PG8_SCHED;
;             PG8_LDA(At, 0, 1); PG8_STAGE(PG8_SB(0, 0), b2, voffB); PG8_STAGE(PG8_SB(0, 1), b2 + hstep, voffB); PG8_STAGE(PG8_SA(0, 0), a2, voffA);
;             PG8_WAIT_V(8); PG8_WAIT_L(0); PG8_BAR; PG8_MMA(1, 0, At, B0); PG8_MMA(1, 1, At, B1); PG8_BAR; PG8_SCHED;
;             PG8_LDB(B0, 1, 0); PG8_LDB(B1, 1, 1); PG8_SCHED; PG8_LDA(At, 1, 0); PG8_STAGE(PG8_SA(0, 1), a2 + hstepA, voffA);
;             PG8_WAIT_V(8); PG8_WAIT_L(0); PG8_BAR; PG8_MMA(0, 0, At, B0); PG8_MMA(0, 1, At, B1); PG8_BAR; PG8_SCHED;
	s_setprio 1
	s_waitcnt lgkmcnt(0)
	v_mfma_f32_16x16x32_bf16 v[64:67], v[132:135], v[182:185], v[64:67]
	v_mfma_f32_16x16x32_bf16 v[60:63], v[158:161], v[182:185], v[60:63]
	v_mfma_f32_16x16x32_bf16 v[48:51], v[132:135], v[190:193], v[48:51]
	v_mfma_f32_16x16x32_bf16 v[44:47], v[158:161], v[190:193], v[44:47]
	v_mfma_f32_16x16x32_bf16 v[32:35], v[132:135], v[198:201], v[32:35]
	v_mfma_f32_16x16x32_bf16 v[28:31], v[158:161], v[198:201], v[28:31]
	v_mfma_f32_16x16x32_bf16 v[16:19], v[132:135], v[206:209], v[16:19]
	v_mfma_f32_16x16x32_bf16 v[12:15], v[158:161], v[206:209], v[12:15]
	v_mfma_f32_16x16x32_bf16 v[64:67], v[136:139], v[186:189], v[64:67]
	v_mfma_f32_16x16x32_bf16 v[60:63], v[162:165], v[186:189], v[60:63]
	v_mfma_f32_16x16x32_bf16 v[48:51], v[136:139], v[194:197], v[48:51]
	v_mfma_f32_16x16x32_bf16 v[44:47], v[162:165], v[194:197], v[44:47]
	v_mfma_f32_16x16x32_bf16 v[32:35], v[136:139], v[202:205], v[32:35]
	v_mfma_f32_16x16x32_bf16 v[28:31], v[162:165], v[202:205], v[28:31]
	v_mfma_f32_16x16x32_bf16 v[16:19], v[136:139], v[210:213], v[16:19]
	v_mfma_f32_16x16x32_bf16 v[12:15], v[162:165], v[210:213], v[12:15]
	v_mfma_f32_16x16x32_bf16 v[56:59], v[166:169], v[182:185], v[56:59]
	v_mfma_f32_16x16x32_bf16 v[52:55], v[174:177], v[182:185], v[52:55]
	v_mfma_f32_16x16x32_bf16 v[40:43], v[166:169], v[190:193], v[40:43]
	v_mfma_f32_16x16x32_bf16 v[36:39], v[174:177], v[190:193], v[36:39]
	v_mfma_f32_16x16x32_bf16 v[24:27], v[166:169], v[198:201], v[24:27]
	v_mfma_f32_16x16x32_bf16 v[20:23], v[174:177], v[198:201], v[20:23]
	v_mfma_f32_16x16x32_bf16 v[8:11], v[166:169], v[206:209], v[8:11]
	v_mfma_f32_16x16x32_bf16 v[2:5], v[174:177], v[206:209], v[4:7]
	v_mfma_f32_16x16x32_bf16 v[56:59], v[170:173], v[186:189], v[56:59]
	v_mfma_f32_16x16x32_bf16 v[52:55], v[178:181], v[186:189], v[52:55]
	v_mfma_f32_16x16x32_bf16 v[40:43], v[170:173], v[194:197], v[40:43]
	v_mfma_f32_16x16x32_bf16 v[36:39], v[178:181], v[194:197], v[36:39]
	v_mfma_f32_16x16x32_bf16 v[24:27], v[170:173], v[202:205], v[24:27]
	v_mfma_f32_16x16x32_bf16 v[20:23], v[178:181], v[202:205], v[20:23]
	v_mfma_f32_16x16x32_bf16 v[8:11], v[170:173], v[210:213], v[8:11]
	v_mfma_f32_16x16x32_bf16 v[2:5], v[178:181], v[210:213], v[2:5]
	s_setprio 0
	s_barrier
	s_add_i32 s40, 0, 0x18000
	v_add_u32_e32 v1, s40, v153
	s_add_i32 s41, 0, 0x1c000
	ds_read_b128 v[132:135], v1
	ds_read_b128 v[136:139], v1 offset:1024
	ds_read_b128 v[158:161], v1 offset:2048
	ds_read_b128 v[162:165], v1 offset:3072
	v_add_u32_e32 v1, s41, v153
	ds_read_b128 v[166:169], v1
	ds_read_b128 v[170:173], v1 offset:1024
	ds_read_b128 v[174:177], v1 offset:2048
	ds_read_b128 v[178:181], v1 offset:3072
	s_add_u32 s34, s38, 0x80000
	s_addc_u32 s35, s39, 0
	s_mov_b32 m0, s52
	v_lshl_add_u64 v[6:7], s[34:35], 0, v[146:147]
	ds_read_b128 v[182:185], v156 offset:32768
	ds_read_b128 v[186:189], v156 offset:33792
	ds_read_b128 v[190:193], v156 offset:34816
	ds_read_b128 v[194:197], v156 offset:35840
	ds_read_b128 v[198:201], v156 offset:36864
	ds_read_b128 v[202:205], v156 offset:37888
	ds_read_b128 v[206:209], v156 offset:38912
	ds_read_b128 v[210:213], v156 offset:39936
	global_load_lds_dwordx4 v[6:7], off
	v_lshl_add_u64 v[6:7], s[34:35], 0, v[142:143]
	s_mov_b32 m0, s53
	s_nop 0
	global_load_lds_dwordx4 v[6:7], off
	s_waitcnt vmcnt(8)
	s_waitcnt lgkmcnt(0)
	s_barrier
	s_setprio 1
	s_waitcnt lgkmcnt(0)
	v_mfma_f32_16x16x32_bf16 v[128:131], v[132:135], v[182:185], v[128:131]
	v_mfma_f32_16x16x32_bf16 v[124:127], v[158:161], v[182:185], v[124:127]
	v_mfma_f32_16x16x32_bf16 v[112:115], v[132:135], v[190:193], v[112:115]
	v_mfma_f32_16x16x32_bf16 v[108:111], v[158:161], v[190:193], v[108:111]
	v_mfma_f32_16x16x32_bf16 v[96:99], v[132:135], v[198:201], v[96:99]
	v_mfma_f32_16x16x32_bf16 v[92:95], v[158:161], v[198:201], v[92:95]
	v_mfma_f32_16x16x32_bf16 v[80:83], v[132:135], v[206:209], v[80:83]
	v_mfma_f32_16x16x32_bf16 v[76:79], v[158:161], v[206:209], v[76:79]
	v_mfma_f32_16x16x32_bf16 v[128:131], v[136:139], v[186:189], v[128:131]
	v_mfma_f32_16x16x32_bf16 v[124:127], v[162:165], v[186:189], v[124:127]
	v_mfma_f32_16x16x32_bf16 v[112:115], v[136:139], v[194:197], v[112:115]
	v_mfma_f32_16x16x32_bf16 v[108:111], v[162:165], v[194:197], v[108:111]
	v_mfma_f32_16x16x32_bf16 v[96:99], v[136:139], v[202:205], v[96:99]
	v_mfma_f32_16x16x32_bf16 v[92:95], v[162:165], v[202:205], v[92:95]
	v_mfma_f32_16x16x32_bf16 v[80:83], v[136:139], v[210:213], v[80:83]
	v_mfma_f32_16x16x32_bf16 v[76:79], v[162:165], v[210:213], v[76:79]
	v_mfma_f32_16x16x32_bf16 v[120:123], v[166:169], v[182:185], v[120:123]
	v_mfma_f32_16x16x32_bf16 v[116:119], v[174:177], v[182:185], v[116:119]
	v_mfma_f32_16x16x32_bf16 v[104:107], v[166:169], v[190:193], v[104:107]
	v_mfma_f32_16x16x32_bf16 v[100:103], v[174:177], v[190:193], v[100:103]
	v_mfma_f32_16x16x32_bf16 v[88:91], v[166:169], v[198:201], v[88:91]
	v_mfma_f32_16x16x32_bf16 v[84:87], v[174:177], v[198:201], v[84:87]
	v_mfma_f32_16x16x32_bf16 v[72:75], v[166:169], v[206:209], v[72:75]
	v_mfma_f32_16x16x32_bf16 v[68:71], v[174:177], v[206:209], v[68:71]
	v_mfma_f32_16x16x32_bf16 v[120:123], v[170:173], v[186:189], v[120:123]
	v_mfma_f32_16x16x32_bf16 v[116:119], v[178:181], v[186:189], v[116:119]
	v_mfma_f32_16x16x32_bf16 v[104:107], v[170:173], v[194:197], v[104:107]
	v_mfma_f32_16x16x32_bf16 v[100:103], v[178:181], v[194:197], v[100:103]
	v_mfma_f32_16x16x32_bf16 v[88:91], v[170:173], v[202:205], v[88:91]
	v_mfma_f32_16x16x32_bf16 v[84:87], v[178:181], v[202:205], v[84:87]
	v_mfma_f32_16x16x32_bf16 v[72:75], v[170:173], v[210:213], v[72:75]
	v_mfma_f32_16x16x32_bf16 v[68:71], v[178:181], v[210:213], v[68:71]
	s_setprio 0
	s_barrier
; #define PG8_STAGE(bufoff, gbase, voff) do { _Pragma("unroll") for (int _i = 0; _i < 2; ++_i) \
;         __builtin_amdgcn_global_load_lds((const unsigned*)((const char*)(gbase) + (voff)[_i]), (LAS unsigned*)(lds + (bufoff) + ldsw + _i * 8192), 16, 0, 0); } while (0)
; #define PG8_LDA(dst, b, h) do { _Pragma("unroll") for (int m = 0; m < 4; ++m) _Pragma("unroll") for (int k = 0; k < 2; ++k) dst[m][k] = *(const LAS bf16x8*)(lds + PG8_SA(b, h) + aoff + m * 2048 + k * 1024); } while (0)
; #define PG8_MMA(ai, bj, At, Bt) do { __builtin_amdgcn_s_setprio(1); _Pragma("unroll") for (int m = 0; m < 4; ++m) _Pragma("unroll") for (int n = 0; n < 2; ++n) _Pragma("unroll") for (int k = 0; k < 2; ++k) \
;         acc[ai][bj][m][n] = __builtin_amdgcn_mfma_f32_16x16x32_bf16(Bt[n][k], At[m][k], acc[ai][bj][m][n], 0, 0, 0); __builtin_amdgcn_s_setprio(0); } while (0)
; #define PG8_WAIT_V(n) asm volatile("s_waitcnt vmcnt(" #n ")" ::: "memory")
; #define PG8_WAIT_L(n) asm volatile("s_waitcnt lgkmcnt(" #n ")" ::: "memory")
; #define PG8_BAR __builtin_amdgcn_s_barrier()
; #define PG8_SCHED __builtin_amdgcn_sched_barrier(0)
; template <class Epi, class Sched, bool ALIGN_EPI = false, bool SP2 = false, bool TWOA = false, bool AGM = false>
; __device__ __forceinline__ void gemm_phase(LAS unsigned char* lds, const Gemm g, const Sched& S, const Epi& E, int wid) {
;     ...
;         for (int t = 0; t < nt; t += 2) {
;     ...
;             PG8_LDA(At, 1, 1); PG8_STAGE(PG8_SB(1, 0), b3, voffB); PG8_STAGE(PG8_SB(1, 1), b3 + hstep, voffB); PG8_STAGE(PG8_SA(1, 0), a3, voffA);
;             PG8_WAIT_V(8); PG8_WAIT_L(0); PG8_BAR; PG8_MMA(1, 0, At, B0); PG8_MMA(1, 1, At, B1); PG8_BAR; PG8_SCHED;
	s_add_i32 s34, s40, s47
	v_lshl_add_u64 v[6:7], v[214:215], 0, s[12:13]
	s_mov_b32 m0, s34
	ds_read_b128 v[182:185], v156 offset:49152
	ds_read_b128 v[186:189], v156 offset:50176
	ds_read_b128 v[190:193], v156 offset:51200
	ds_read_b128 v[194:197], v156 offset:52224
	ds_read_b128 v[198:201], v156 offset:53248
	ds_read_b128 v[202:205], v156 offset:54272
	ds_read_b128 v[206:209], v156 offset:55296
	ds_read_b128 v[210:213], v156 offset:56320
	global_load_lds_dwordx4 v[6:7], off
	s_add_i32 m0, s34, 0x2000
	s_add_u32 s34, s42, 0x100080
	v_lshl_add_u64 v[6:7], v[216:217], 0, s[12:13]
	s_addc_u32 s35, s43, 0
	s_add_i32 s38, s41, s47
	global_load_lds_dwordx4 v[6:7], off
	v_lshl_add_u64 v[6:7], s[34:35], 0, v[144:145]
	s_mov_b32 m0, s38
	s_nop 0
	global_load_lds_dwordx4 v[6:7], off
	v_lshl_add_u64 v[6:7], s[34:35], 0, v[140:141]
	s_add_i32 m0, s38, 0x2000
	s_nop 0
	global_load_lds_dwordx4 v[6:7], off
	v_lshl_add_u64 v[6:7], v[218:219], 0, s[12:13]
	s_mov_b32 m0, s55
	s_nop 0
	global_load_lds_dwordx4 v[6:7], off
	v_lshl_add_u64 v[6:7], v[220:221], 0, s[12:13]
	s_mov_b32 m0, s56
	s_nop 0
	global_load_lds_dwordx4 v[6:7], off
	s_waitcnt vmcnt(8)
	s_waitcnt lgkmcnt(0)
	s_barrier
	s_setprio 1
	s_waitcnt lgkmcnt(0)
	v_mfma_f32_16x16x32_bf16 v[64:67], v[132:135], v[182:185], v[64:67]
	v_mfma_f32_16x16x32_bf16 v[60:63], v[158:161], v[182:185], v[60:63]
	v_mfma_f32_16x16x32_bf16 v[48:51], v[132:135], v[190:193], v[48:51]
	v_mfma_f32_16x16x32_bf16 v[44:47], v[158:161], v[190:193], v[44:47]
	v_mfma_f32_16x16x32_bf16 v[32:35], v[132:135], v[198:201], v[32:35]
	v_mfma_f32_16x16x32_bf16 v[28:31], v[158:161], v[198:201], v[28:31]
	v_mfma_f32_16x16x32_bf16 v[16:19], v[132:135], v[206:209], v[16:19]
	v_mfma_f32_16x16x32_bf16 v[12:15], v[158:161], v[206:209], v[12:15]
	v_mfma_f32_16x16x32_bf16 v[64:67], v[136:139], v[186:189], v[64:67]
	v_mfma_f32_16x16x32_bf16 v[60:63], v[162:165], v[186:189], v[60:63]
	v_mfma_f32_16x16x32_bf16 v[48:51], v[136:139], v[194:197], v[48:51]
	v_mfma_f32_16x16x32_bf16 v[44:47], v[162:165], v[194:197], v[44:47]
	v_mfma_f32_16x16x32_bf16 v[32:35], v[136:139], v[202:205], v[32:35]
	v_mfma_f32_16x16x32_bf16 v[28:31], v[162:165], v[202:205], v[28:31]
	v_mfma_f32_16x16x32_bf16 v[16:19], v[136:139], v[210:213], v[16:19]
	v_mfma_f32_16x16x32_bf16 v[12:15], v[162:165], v[210:213], v[12:15]
	v_mfma_f32_16x16x32_bf16 v[56:59], v[166:169], v[182:185], v[56:59]
	v_mfma_f32_16x16x32_bf16 v[52:55], v[174:177], v[182:185], v[52:55]
	v_mfma_f32_16x16x32_bf16 v[40:43], v[166:169], v[190:193], v[40:43]
	v_mfma_f32_16x16x32_bf16 v[36:39], v[174:177], v[190:193], v[36:39]
	v_mfma_f32_16x16x32_bf16 v[24:27], v[166:169], v[198:201], v[24:27]
	v_mfma_f32_16x16x32_bf16 v[20:23], v[174:177], v[198:201], v[20:23]
	v_mfma_f32_16x16x32_bf16 v[6:9], v[166:169], v[206:209], v[8:11]
	v_mfma_f32_16x16x32_bf16 v[2:5], v[174:177], v[206:209], v[2:5]
	v_mfma_f32_16x16x32_bf16 v[56:59], v[170:173], v[186:189], v[56:59]
	v_mfma_f32_16x16x32_bf16 v[52:55], v[178:181], v[186:189], v[52:55]
	v_mfma_f32_16x16x32_bf16 v[40:43], v[170:173], v[194:197], v[40:43]
	v_mfma_f32_16x16x32_bf16 v[36:39], v[178:181], v[194:197], v[36:39]
	v_mfma_f32_16x16x32_bf16 v[24:27], v[170:173], v[202:205], v[24:27]
	v_mfma_f32_16x16x32_bf16 v[20:23], v[178:181], v[202:205], v[20:23]
	v_mfma_f32_16x16x32_bf16 v[8:11], v[170:173], v[210:213], v[6:9]
	v_mfma_f32_16x16x32_bf16 v[4:7], v[178:181], v[210:213], v[2:5]
	s_setprio 0
	s_barrier
	s_add_u32 s36, s36, 0x100
	s_addc_u32 s37, s37, 0
	s_cmp_gt_u32 s73, 61
	s_cbranch_scc1 .LBB0_829

; #define PG8_STAGE(bufoff, gbase, voff) do { _Pragma("unroll") for (int _i = 0; _i < 2; ++_i) \
;         __builtin_amdgcn_global_load_lds((const unsigned*)((const char*)(gbase) + (voff)[_i]), (LAS unsigned*)(lds + (bufoff) + ldsw + _i * 8192), 16, 0, 0); } while (0)
; #define PG8_LDA(dst, b, h) do { _Pragma("unroll") for (int m = 0; m < 4; ++m) _Pragma("unroll") for (int k = 0; k < 2; ++k) dst[m][k] = *(const LAS bf16x8*)(lds + PG8_SA(b, h) + aoff + m * 2048 + k * 1024); } while (0)
; #define PG8_BAR __builtin_amdgcn_s_barrier()
; template <class Epi, class Sched, bool ALIGN_EPI = false, bool SP2 = false, bool TWOA = false, bool AGM = false>
; __device__ __forceinline__ void gemm_phase(LAS unsigned char* lds, const Gemm g, const Sched& S, const Epi& E, int wid) {
;     ...
;         for (int t = 0; t < nt; t += 2) {
;             const bool last = (t == nt - 2);
;             const char* cA2 = TWOA ? (const char*)g.A2 + (cA - (const char*)g.A) - (size_t)nh * kstepA : cA;
;             const char* a1_ = (TWOA && t + 1 >= nh ? cA2 : cA) + (size_t)(t + 1) * kstepA;
;             const char* a2_ = last ? nA : (TWOA && t + 2 >= nh ? cA2 : cA) + (size_t)(t + 2) * kstepA; const char* a1 = a1_; const char* a2 = a2_; const char* b2 = last ? nB : cB + (size_t)(t + 2) * kstep;
;             if constexpr (TWOA) { asm volatile("" : "+s"(a1)); asm volatile("" : "+s"(a2)); }
;             const char* a3 = a2 + kstepA; const char* b3 = b2 + kstep;
;             if (last && has_next) S.a_ready(nxt);
;             if constexpr (has_mid<Epi>::value) { if (t == nh) E.mid(acc, cur, wr, wc, fr, fq); }
;             if constexpr (SP2) {
;             PG8_LDB(B0, 0, 0); PG8_LDB(B1, 0, 1); PG8_SCHED; PG8_LDA(At, 0, 0); PG8_STAGE(PG8_SA(1, 1), a1 + hstepA, voffA);
;             PG8_WAIT_V(8); PG8_WAIT_L(0); PG8_BAR; PG8_MMA(0, 0, At, B0); PG8_MMA(0, 1, At, B1); PG8_BAR; PG8_SCHED;
;             PG8_LDA(At, 0, 1); PG8_STAGE(PG8_SB(0, 0), b2, voffB); PG8_STAGE(PG8_SB(0, 1), b2 + hstep, voffB); PG8_STAGE(PG8_SA(0, 0), a2, voffA);
;             PG8_WAIT_V(8); PG8_WAIT_L(0); PG8_BAR; PG8_MMA(1, 0, At, B0); PG8_MMA(1, 1, At, B1); PG8_BAR; PG8_SCHED;
;             PG8_LDB(B0, 1, 0); PG8_LDB(B1, 1, 1); PG8_SCHED; PG8_LDA(At, 1, 0); PG8_STAGE(PG8_SA(0, 1), a2 + hstepA, voffA);
;             PG8_WAIT_V(8); PG8_WAIT_L(0); PG8_BAR; PG8_MMA(0, 0, At, B0); PG8_MMA(0, 1, At, B1); PG8_BAR; PG8_SCHED;
.LBB0_901:
	ds_read_b128 v[146:149], v155
	ds_read_b128 v[158:161], v155 offset:1024
	ds_read_b128 v[162:165], v155 offset:2048
	ds_read_b128 v[166:169], v155 offset:3072
	ds_read_b128 v[170:173], v156
	ds_read_b128 v[174:177], v156 offset:1024
	ds_read_b128 v[178:181], v156 offset:2048
	ds_read_b128 v[182:185], v156 offset:3072
	s_add_u32 s38, s36, 0xfff00080
	s_addc_u32 s39, s37, -1
	s_cmp_eq_u32 s67, 60
	s_cselect_b32 s41, s27, s39
	s_cselect_b32 s40, s63, s38
	s_cselect_b32 s39, s25, s66
	s_cselect_b32 s38, s64, s65
	v_lshl_add_u64 v[150:151], s[36:37], 0, v[138:139]
	s_add_i32 m0, s35, 0xc000
	ds_read_b128 v[186:189], v157
	ds_read_b128 v[190:193], v157 offset:1024
	ds_read_b128 v[194:197], v157 offset:2048
	ds_read_b128 v[198:201], v157 offset:3072
	ds_read_b128 v[202:205], v157 offset:4096
	ds_read_b128 v[206:209], v157 offset:5120
	ds_read_b128 v[210:213], v157 offset:6144
	ds_read_b128 v[214:217], v157 offset:7168
	global_load_lds_dwordx4 v[150:151], off
	v_lshl_add_u64 v[150:151], s[36:37], 0, v[140:141]
	s_add_i32 m0, s35, 0xe000
	s_nop 0
	global_load_lds_dwordx4 v[150:151], off
	s_waitcnt vmcnt(8)
	s_waitcnt lgkmcnt(0)
	s_barrier
	s_setprio 1
	s_waitcnt lgkmcnt(0)
	v_mfma_f32_16x16x32_bf16 v[124:127], v[146:149], v[186:189], v[124:127]
	v_mfma_f32_16x16x32_bf16 v[120:123], v[162:165], v[186:189], v[120:123]
	v_mfma_f32_16x16x32_bf16 v[116:119], v[146:149], v[194:197], v[116:119]
	v_mfma_f32_16x16x32_bf16 v[108:111], v[162:165], v[194:197], v[108:111]
	v_mfma_f32_16x16x32_bf16 v[100:103], v[146:149], v[202:205], v[100:103]
	v_mfma_f32_16x16x32_bf16 v[92:95], v[162:165], v[202:205], v[92:95]
	v_mfma_f32_16x16x32_bf16 v[84:87], v[146:149], v[210:213], v[84:87]
	v_mfma_f32_16x16x32_bf16 v[76:79], v[162:165], v[210:213], v[76:79]
	v_mfma_f32_16x16x32_bf16 v[124:127], v[158:161], v[190:193], v[124:127]
	v_mfma_f32_16x16x32_bf16 v[120:123], v[166:169], v[190:193], v[120:123]
	v_mfma_f32_16x16x32_bf16 v[116:119], v[158:161], v[198:201], v[116:119]
	v_mfma_f32_16x16x32_bf16 v[108:111], v[166:169], v[198:201], v[108:111]
	v_mfma_f32_16x16x32_bf16 v[100:103], v[158:161], v[206:209], v[100:103]
	v_mfma_f32_16x16x32_bf16 v[92:95], v[166:169], v[206:209], v[92:95]
	v_mfma_f32_16x16x32_bf16 v[84:87], v[158:161], v[214:217], v[84:87]
	v_mfma_f32_16x16x32_bf16 v[76:79], v[166:169], v[214:217], v[76:79]
	v_mfma_f32_16x16x32_bf16 v[112:115], v[170:173], v[186:189], v[112:115]
	v_mfma_f32_16x16x32_bf16 v[104:107], v[178:181], v[186:189], v[104:107]
	v_mfma_f32_16x16x32_bf16 v[96:99], v[170:173], v[194:197], v[96:99]
	v_mfma_f32_16x16x32_bf16 v[88:91], v[178:181], v[194:197], v[88:91]
	v_mfma_f32_16x16x32_bf16 v[80:83], v[170:173], v[202:205], v[80:83]
	v_mfma_f32_16x16x32_bf16 v[72:75], v[178:181], v[202:205], v[72:75]
	v_mfma_f32_16x16x32_bf16 v[68:71], v[170:173], v[210:213], v[68:71]
	v_mfma_f32_16x16x32_bf16 v[64:67], v[178:181], v[210:213], v[64:67]
	v_mfma_f32_16x16x32_bf16 v[112:115], v[174:177], v[190:193], v[112:115]
	v_mfma_f32_16x16x32_bf16 v[104:107], v[182:185], v[190:193], v[104:107]
	v_mfma_f32_16x16x32_bf16 v[96:99], v[174:177], v[198:201], v[96:99]
	v_mfma_f32_16x16x32_bf16 v[88:91], v[182:185], v[198:201], v[88:91]
	v_mfma_f32_16x16x32_bf16 v[80:83], v[174:177], v[206:209], v[80:83]
	v_mfma_f32_16x16x32_bf16 v[72:75], v[182:185], v[206:209], v[72:75]
	v_mfma_f32_16x16x32_bf16 v[68:71], v[174:177], v[214:217], v[68:71]
	v_mfma_f32_16x16x32_bf16 v[64:67], v[182:185], v[214:217], v[64:67]
	s_setprio 0
	s_barrier
	s_add_i32 s68, s54, s44
	v_lshl_add_u64 v[150:151], s[38:39], 0, v[132:133]
	s_mov_b32 m0, s68
	ds_read_b128 v[186:189], v157 offset:16384
	ds_read_b128 v[190:193], v157 offset:17408
	ds_read_b128 v[194:197], v157 offset:18432
	ds_read_b128 v[198:201], v157 offset:19456
	ds_read_b128 v[202:205], v157 offset:20480
	ds_read_b128 v[206:209], v157 offset:21504
	ds_read_b128 v[210:213], v157 offset:22528
	ds_read_b128 v[214:217], v157 offset:23552
	global_load_lds_dwordx4 v[150:151], off
	s_add_i32 m0, s68, 0x2000
	s_add_u32 s68, s38, 0x100000
	v_lshl_add_u64 v[218:219], s[38:39], 0, v[128:129]
	s_addc_u32 s69, s39, 0
	s_add_i32 s70, s55, s44
	global_load_lds_dwordx4 v[218:219], off
	v_lshl_add_u64 v[220:221], s[68:69], 0, v[132:133]
	s_mov_b32 m0, s70
	v_lshl_add_u64 v[222:223], s[40:41], 0, v[130:131]
	global_load_lds_dwordx4 v[220:221], off
	v_lshl_add_u64 v[220:221], s[68:69], 0, v[128:129]
	s_add_i32 m0, s70, 0x2000
	s_nop 0
	global_load_lds_dwordx4 v[220:221], off
	v_lshl_add_u64 v[220:221], s[40:41], 0, v[134:135]
	s_mov_b32 m0, s35
	s_nop 0
	global_load_lds_dwordx4 v[220:221], off
	s_mov_b32 m0, s47
	s_nop 0
	global_load_lds_dwordx4 v[222:223], off
	s_waitcnt vmcnt(8)
	s_waitcnt lgkmcnt(0)
	s_barrier
; #define PG8_STAGE(bufoff, gbase, voff) do { _Pragma("unroll") for (int _i = 0; _i < 2; ++_i) \
;         __builtin_amdgcn_global_load_lds((const unsigned*)((const char*)(gbase) + (voff)[_i]), (LAS unsigned*)(lds + (bufoff) + ldsw + _i * 8192), 16, 0, 0); } while (0)
; #define PG8_LDA(dst, b, h) do { _Pragma("unroll") for (int m = 0; m < 4; ++m) _Pragma("unroll") for (int k = 0; k < 2; ++k) dst[m][k] = *(const LAS bf16x8*)(lds + PG8_SA(b, h) + aoff + m * 2048 + k * 1024); } while (0)
; #define PG8_LDB(dst, b, h) do { _Pragma("unroll") for (int n = 0; n < 2; ++n) _Pragma("unroll") for (int k = 0; k < 2; ++k) dst[n][k] = *(const LAS bf16x8*)(lds + PG8_SB(b, h) + boff + n * 2048 + k * 1024); } while (0)
; #define PG8_MMA(ai, bj, At, Bt) do { __builtin_amdgcn_s_setprio(1); _Pragma("unroll") for (int m = 0; m < 4; ++m) _Pragma("unroll") for (int n = 0; n < 2; ++n) _Pragma("unroll") for (int k = 0; k < 2; ++k) \
;         acc[ai][bj][m][n] = __builtin_amdgcn_mfma_f32_16x16x32_bf16(Bt[n][k], At[m][k], acc[ai][bj][m][n], 0, 0, 0); __builtin_amdgcn_s_setprio(0); } while (0)
; #define PG8_WAIT_V(n) asm volatile("s_waitcnt vmcnt(" #n ")" ::: "memory")
; #define PG8_WAIT_L(n) asm volatile("s_waitcnt lgkmcnt(" #n ")" ::: "memory")
; #define PG8_BAR __builtin_amdgcn_s_barrier()
; #define PG8_SCHED __builtin_amdgcn_sched_barrier(0)
; template <class Epi, class Sched, bool ALIGN_EPI = false, bool SP2 = false, bool TWOA = false, bool AGM = false>
; __device__ __forceinline__ void gemm_phase(LAS unsigned char* lds, const Gemm g, const Sched& S, const Epi& E, int wid) {
;     ...
;             PG8_WAIT_V(8); PG8_WAIT_L(0); PG8_BAR; PG8_MMA(0, 0, At, B0); PG8_MMA(0, 1, At, B1); PG8_BAR; PG8_SCHED;
;             PG8_LDA(At, 0, 1); PG8_STAGE(PG8_SB(0, 0), b2, voffB); PG8_STAGE(PG8_SB(0, 1), b2 + hstep, voffB); PG8_STAGE(PG8_SA(0, 0), a2, voffA);
;             PG8_WAIT_V(8); PG8_WAIT_L(0); PG8_BAR; PG8_MMA(1, 0, At, B0); PG8_MMA(1, 1, At, B1); PG8_BAR; PG8_SCHED;
;             PG8_LDB(B0, 1, 0); PG8_LDB(B1, 1, 1); PG8_SCHED; PG8_LDA(At, 1, 0); PG8_STAGE(PG8_SA(0, 1), a2 + hstepA, voffA);
;             PG8_WAIT_V(8); PG8_WAIT_L(0); PG8_BAR; PG8_MMA(0, 0, At, B0); PG8_MMA(0, 1, At, B1); PG8_BAR; PG8_SCHED;
	s_setprio 1
	s_waitcnt lgkmcnt(0)
	v_mfma_f32_16x16x32_bf16 v[60:63], v[146:149], v[186:189], v[60:63]
	v_mfma_f32_16x16x32_bf16 v[56:59], v[162:165], v[186:189], v[56:59]
	v_mfma_f32_16x16x32_bf16 v[52:55], v[146:149], v[194:197], v[52:55]
	v_mfma_f32_16x16x32_bf16 v[44:47], v[162:165], v[194:197], v[44:47]
	v_mfma_f32_16x16x32_bf16 v[36:39], v[146:149], v[202:205], v[36:39]
	v_mfma_f32_16x16x32_bf16 v[28:31], v[162:165], v[202:205], v[28:31]
	v_mfma_f32_16x16x32_bf16 v[20:23], v[146:149], v[210:213], v[20:23]
	v_mfma_f32_16x16x32_bf16 v[12:15], v[162:165], v[210:213], v[12:15]
	v_mfma_f32_16x16x32_bf16 v[60:63], v[158:161], v[190:193], v[60:63]
	v_mfma_f32_16x16x32_bf16 v[56:59], v[166:169], v[190:193], v[56:59]
	v_mfma_f32_16x16x32_bf16 v[52:55], v[158:161], v[198:201], v[52:55]
	v_mfma_f32_16x16x32_bf16 v[44:47], v[166:169], v[198:201], v[44:47]
	v_mfma_f32_16x16x32_bf16 v[36:39], v[158:161], v[206:209], v[36:39]
	v_mfma_f32_16x16x32_bf16 v[28:31], v[166:169], v[206:209], v[28:31]
	v_mfma_f32_16x16x32_bf16 v[20:23], v[158:161], v[214:217], v[20:23]
	v_mfma_f32_16x16x32_bf16 v[12:15], v[166:169], v[214:217], v[12:15]
	v_mfma_f32_16x16x32_bf16 v[48:51], v[170:173], v[186:189], v[48:51]
	v_mfma_f32_16x16x32_bf16 v[40:43], v[178:181], v[186:189], v[40:43]
	v_mfma_f32_16x16x32_bf16 v[32:35], v[170:173], v[194:197], v[32:35]
	v_mfma_f32_16x16x32_bf16 v[24:27], v[178:181], v[194:197], v[24:27]
	v_mfma_f32_16x16x32_bf16 v[16:19], v[170:173], v[202:205], v[16:19]
	v_mfma_f32_16x16x32_bf16 v[8:11], v[178:181], v[202:205], v[8:11]
	v_mfma_f32_16x16x32_bf16 v[4:7], v[170:173], v[210:213], v[4:7]
	v_mfma_f32_16x16x32_bf16 v[0:3], v[178:181], v[210:213], v[0:3]
	v_mfma_f32_16x16x32_bf16 v[48:51], v[174:177], v[190:193], v[48:51]
	v_mfma_f32_16x16x32_bf16 v[40:43], v[182:185], v[190:193], v[40:43]
	v_mfma_f32_16x16x32_bf16 v[32:35], v[174:177], v[198:201], v[32:35]
	v_mfma_f32_16x16x32_bf16 v[24:27], v[182:185], v[198:201], v[24:27]
	v_mfma_f32_16x16x32_bf16 v[16:19], v[174:177], v[206:209], v[16:19]
	v_mfma_f32_16x16x32_bf16 v[8:11], v[182:185], v[206:209], v[8:11]
	v_mfma_f32_16x16x32_bf16 v[4:7], v[174:177], v[214:217], v[4:7]
	v_mfma_f32_16x16x32_bf16 v[0:3], v[182:185], v[214:217], v[0:3]
	s_setprio 0
	s_barrier
	s_add_i32 s68, 0, 0x18000
	v_add_u32_e32 v136, s68, v153
	s_add_i32 s69, 0, 0x1c000
	ds_read_b128 v[146:149], v136
	ds_read_b128 v[158:161], v136 offset:1024
	ds_read_b128 v[162:165], v136 offset:2048
	ds_read_b128 v[166:169], v136 offset:3072
	v_add_u32_e32 v136, s69, v153
	ds_read_b128 v[170:173], v136
	ds_read_b128 v[174:177], v136 offset:1024
	ds_read_b128 v[178:181], v136 offset:2048
	ds_read_b128 v[182:185], v136 offset:3072
	s_add_u32 s40, s40, 0x100000
	s_addc_u32 s41, s41, 0
	s_mov_b32 m0, s48
	v_lshl_add_u64 v[224:225], s[40:41], 0, v[134:135]
	ds_read_b128 v[186:189], v157 offset:32768
	ds_read_b128 v[190:193], v157 offset:33792
	ds_read_b128 v[194:197], v157 offset:34816
	ds_read_b128 v[198:201], v157 offset:35840
	ds_read_b128 v[202:205], v157 offset:36864
	ds_read_b128 v[206:209], v157 offset:37888
	ds_read_b128 v[210:213], v157 offset:38912
	ds_read_b128 v[214:217], v157 offset:39936
	global_load_lds_dwordx4 v[224:225], off
	v_lshl_add_u64 v[224:225], s[40:41], 0, v[130:131]
	s_mov_b32 m0, s49
	s_nop 0
	global_load_lds_dwordx4 v[224:225], off
	s_waitcnt vmcnt(8)
	s_waitcnt lgkmcnt(0)
	s_barrier
	s_setprio 1
	s_waitcnt lgkmcnt(0)
	v_mfma_f32_16x16x32_bf16 v[124:127], v[146:149], v[186:189], v[124:127]
	v_mfma_f32_16x16x32_bf16 v[120:123], v[162:165], v[186:189], v[120:123]
	v_mfma_f32_16x16x32_bf16 v[116:119], v[146:149], v[194:197], v[116:119]
	v_mfma_f32_16x16x32_bf16 v[108:111], v[162:165], v[194:197], v[108:111]
	v_mfma_f32_16x16x32_bf16 v[100:103], v[146:149], v[202:205], v[100:103]
	v_mfma_f32_16x16x32_bf16 v[92:95], v[162:165], v[202:205], v[92:95]
	v_mfma_f32_16x16x32_bf16 v[84:87], v[146:149], v[210:213], v[84:87]
	v_mfma_f32_16x16x32_bf16 v[76:79], v[162:165], v[210:213], v[76:79]
	v_mfma_f32_16x16x32_bf16 v[124:127], v[158:161], v[190:193], v[124:127]
	v_mfma_f32_16x16x32_bf16 v[120:123], v[166:169], v[190:193], v[120:123]
	v_mfma_f32_16x16x32_bf16 v[116:119], v[158:161], v[198:201], v[116:119]
	v_mfma_f32_16x16x32_bf16 v[108:111], v[166:169], v[198:201], v[108:111]
	v_mfma_f32_16x16x32_bf16 v[100:103], v[158:161], v[206:209], v[100:103]
	v_mfma_f32_16x16x32_bf16 v[92:95], v[166:169], v[206:209], v[92:95]
	v_mfma_f32_16x16x32_bf16 v[84:87], v[158:161], v[214:217], v[84:87]
	v_mfma_f32_16x16x32_bf16 v[76:79], v[166:169], v[214:217], v[76:79]
	v_mfma_f32_16x16x32_bf16 v[112:115], v[170:173], v[186:189], v[112:115]
	v_mfma_f32_16x16x32_bf16 v[104:107], v[178:181], v[186:189], v[104:107]
	v_mfma_f32_16x16x32_bf16 v[96:99], v[170:173], v[194:197], v[96:99]
	v_mfma_f32_16x16x32_bf16 v[88:91], v[178:181], v[194:197], v[88:91]
	v_mfma_f32_16x16x32_bf16 v[80:83], v[170:173], v[202:205], v[80:83]
	v_mfma_f32_16x16x32_bf16 v[72:75], v[178:181], v[202:205], v[72:75]
	v_mfma_f32_16x16x32_bf16 v[68:71], v[170:173], v[210:213], v[68:71]
	v_mfma_f32_16x16x32_bf16 v[64:67], v[178:181], v[210:213], v[64:67]
	v_mfma_f32_16x16x32_bf16 v[112:115], v[174:177], v[190:193], v[112:115]
	v_mfma_f32_16x16x32_bf16 v[104:107], v[182:185], v[190:193], v[104:107]
	v_mfma_f32_16x16x32_bf16 v[96:99], v[174:177], v[198:201], v[96:99]
	v_mfma_f32_16x16x32_bf16 v[88:91], v[182:185], v[198:201], v[88:91]
	v_mfma_f32_16x16x32_bf16 v[80:83], v[174:177], v[206:209], v[80:83]
	v_mfma_f32_16x16x32_bf16 v[72:75], v[182:185], v[206:209], v[72:75]
	v_mfma_f32_16x16x32_bf16 v[68:71], v[174:177], v[214:217], v[68:71]
	v_mfma_f32_16x16x32_bf16 v[64:67], v[182:185], v[214:217], v[64:67]
	s_setprio 0
	s_barrier
; #define PG8_STAGE(bufoff, gbase, voff) do { _Pragma("unroll") for (int _i = 0; _i < 2; ++_i) \
;         __builtin_amdgcn_global_load_lds((const unsigned*)((const char*)(gbase) + (voff)[_i]), (LAS unsigned*)(lds + (bufoff) + ldsw + _i * 8192), 16, 0, 0); } while (0)
; #define PG8_LDA(dst, b, h) do { _Pragma("unroll") for (int m = 0; m < 4; ++m) _Pragma("unroll") for (int k = 0; k < 2; ++k) dst[m][k] = *(const LAS bf16x8*)(lds + PG8_SA(b, h) + aoff + m * 2048 + k * 1024); } while (0)
; #define PG8_MMA(ai, bj, At, Bt) do { __builtin_amdgcn_s_setprio(1); _Pragma("unroll") for (int m = 0; m < 4; ++m) _Pragma("unroll") for (int n = 0; n < 2; ++n) _Pragma("unroll") for (int k = 0; k < 2; ++k) \
;         acc[ai][bj][m][n] = __builtin_amdgcn_mfma_f32_16x16x32_bf16(Bt[n][k], At[m][k], acc[ai][bj][m][n], 0, 0, 0); __builtin_amdgcn_s_setprio(0); } while (0)
; #define PG8_WAIT_V(n) asm volatile("s_waitcnt vmcnt(" #n ")" ::: "memory")
; #define PG8_WAIT_L(n) asm volatile("s_waitcnt lgkmcnt(" #n ")" ::: "memory")
; #define PG8_BAR __builtin_amdgcn_s_barrier()
; #define PG8_SCHED __builtin_amdgcn_sched_barrier(0)
; template <class Epi, class Sched, bool ALIGN_EPI = false, bool SP2 = false, bool TWOA = false, bool AGM = false>
; __device__ __forceinline__ void gemm_phase(LAS unsigned char* lds, const Gemm g, const Sched& S, const Epi& E, int wid) {
;     ...
;             PG8_LDA(At, 1, 1); PG8_STAGE(PG8_SB(1, 0), b3, voffB); PG8_STAGE(PG8_SB(1, 1), b3 + hstep, voffB); PG8_STAGE(PG8_SA(1, 0), a3, voffA);
;             PG8_WAIT_V(8); PG8_WAIT_L(0); PG8_BAR; PG8_MMA(1, 0, At, B0); PG8_MMA(1, 1, At, B1); PG8_BAR; PG8_SCHED;
;     ...
;         if constexpr (ALIGN_EPI) { if (wr == 0) PG8_BAR; }
	s_add_i32 s40, s68, s44
	v_lshl_add_u64 v[150:151], v[150:151], 0, s[6:7]
	s_mov_b32 m0, s40
	ds_read_b128 v[186:189], v157 offset:49152
	ds_read_b128 v[190:193], v157 offset:50176
	ds_read_b128 v[194:197], v157 offset:51200
	ds_read_b128 v[198:201], v157 offset:52224
	ds_read_b128 v[202:205], v157 offset:53248
	ds_read_b128 v[206:209], v157 offset:54272
	ds_read_b128 v[210:213], v157 offset:55296
	ds_read_b128 v[214:217], v157 offset:56320
	global_load_lds_dwordx4 v[150:151], off
	s_add_i32 m0, s40, 0x2000
	s_add_u32 s38, s38, 0x100080
	v_lshl_add_u64 v[150:151], v[218:219], 0, s[6:7]
	s_addc_u32 s39, s39, 0
	s_add_i32 s40, s69, s44
	global_load_lds_dwordx4 v[150:151], off
	v_lshl_add_u64 v[150:151], s[38:39], 0, v[132:133]
	s_mov_b32 m0, s40
	s_nop 0
	global_load_lds_dwordx4 v[150:151], off
	v_lshl_add_u64 v[150:151], s[38:39], 0, v[128:129]
	s_add_i32 m0, s40, 0x2000
	s_nop 0
	global_load_lds_dwordx4 v[150:151], off
	v_lshl_add_u64 v[150:151], v[220:221], 0, s[6:7]
	s_mov_b32 m0, s52
	s_nop 0
	global_load_lds_dwordx4 v[150:151], off
	v_lshl_add_u64 v[150:151], v[222:223], 0, s[6:7]
	s_mov_b32 m0, s53
	s_nop 0
	global_load_lds_dwordx4 v[150:151], off
	s_waitcnt vmcnt(8)
	s_waitcnt lgkmcnt(0)
	s_barrier
	s_setprio 1
	s_waitcnt lgkmcnt(0)
	v_mfma_f32_16x16x32_bf16 v[60:63], v[146:149], v[186:189], v[60:63]
	v_mfma_f32_16x16x32_bf16 v[56:59], v[162:165], v[186:189], v[56:59]
	v_mfma_f32_16x16x32_bf16 v[52:55], v[146:149], v[194:197], v[52:55]
	v_mfma_f32_16x16x32_bf16 v[44:47], v[162:165], v[194:197], v[44:47]
	v_mfma_f32_16x16x32_bf16 v[36:39], v[146:149], v[202:205], v[36:39]
	v_mfma_f32_16x16x32_bf16 v[28:31], v[162:165], v[202:205], v[28:31]
	v_mfma_f32_16x16x32_bf16 v[20:23], v[146:149], v[210:213], v[20:23]
	v_mfma_f32_16x16x32_bf16 v[12:15], v[162:165], v[210:213], v[12:15]
	v_mfma_f32_16x16x32_bf16 v[60:63], v[158:161], v[190:193], v[60:63]
	v_mfma_f32_16x16x32_bf16 v[56:59], v[166:169], v[190:193], v[56:59]
	v_mfma_f32_16x16x32_bf16 v[52:55], v[158:161], v[198:201], v[52:55]
	v_mfma_f32_16x16x32_bf16 v[44:47], v[166:169], v[198:201], v[44:47]
	v_mfma_f32_16x16x32_bf16 v[36:39], v[158:161], v[206:209], v[36:39]
	v_mfma_f32_16x16x32_bf16 v[28:31], v[166:169], v[206:209], v[28:31]
	v_mfma_f32_16x16x32_bf16 v[20:23], v[158:161], v[214:217], v[20:23]
	v_mfma_f32_16x16x32_bf16 v[12:15], v[166:169], v[214:217], v[12:15]
	v_mfma_f32_16x16x32_bf16 v[48:51], v[170:173], v[186:189], v[48:51]
	v_mfma_f32_16x16x32_bf16 v[40:43], v[178:181], v[186:189], v[40:43]
	v_mfma_f32_16x16x32_bf16 v[32:35], v[170:173], v[194:197], v[32:35]
	v_mfma_f32_16x16x32_bf16 v[24:27], v[178:181], v[194:197], v[24:27]
	v_mfma_f32_16x16x32_bf16 v[16:19], v[170:173], v[202:205], v[16:19]
	v_mfma_f32_16x16x32_bf16 v[8:11], v[178:181], v[202:205], v[8:11]
	v_mfma_f32_16x16x32_bf16 v[4:7], v[170:173], v[210:213], v[4:7]
	v_mfma_f32_16x16x32_bf16 v[0:3], v[178:181], v[210:213], v[0:3]
	v_mfma_f32_16x16x32_bf16 v[48:51], v[174:177], v[190:193], v[48:51]
	v_mfma_f32_16x16x32_bf16 v[40:43], v[182:185], v[190:193], v[40:43]
	v_mfma_f32_16x16x32_bf16 v[32:35], v[174:177], v[198:201], v[32:35]
	v_mfma_f32_16x16x32_bf16 v[24:27], v[182:185], v[198:201], v[24:27]
	v_mfma_f32_16x16x32_bf16 v[16:19], v[174:177], v[206:209], v[16:19]
	v_mfma_f32_16x16x32_bf16 v[8:11], v[182:185], v[206:209], v[8:11]
	v_mfma_f32_16x16x32_bf16 v[4:7], v[174:177], v[214:217], v[4:7]
	v_mfma_f32_16x16x32_bf16 v[0:3], v[182:185], v[214:217], v[0:3]
	s_setprio 0
	s_barrier
	s_add_i32 s67, s67, 2
	s_add_u32 s36, s36, 0x100
	s_addc_u32 s37, s37, 0
	s_add_u32 s65, s65, 0x100
	s_addc_u32 s66, s66, 0
	s_cmp_gt_u32 s67, 61
	s_cbranch_scc0 .LBB0_901
	s_and_b64 vcc, exec, s[8:9]
	s_cbranch_vccz .LBB0_904
	s_barrier
